# GEMM K-loops: barrier ending each compute segment signalled 4 MFMAs early (trailing MFMAs only read registers) to hide the barrier hand-off
# baseline (speedup 1.0000x reference)
; #define PG8_STAGE(bufoff, gbase, voff) do { _Pragma("unroll") for (int _i = 0; _i < 2; ++_i) \
;         __builtin_amdgcn_global_load_lds((const unsigned*)((const char*)(gbase) + (voff)[_i]), (LAS unsigned*)(lds + (bufoff) + ldsw + _i * 8192), 16, 0, 0); } while (0)
; #define PG8_LDA(dst, b, h) do { _Pragma("unroll") for (int m = 0; m < 4; ++m) _Pragma("unroll") for (int k = 0; k < 2; ++k) dst[m][k] = *(const LAS bf16x8*)(lds + PG8_SA(b, h) + aoff + m * 2048 + k * 1024); } while (0)
; #define PG8_LDB(dst, b, h) do { _Pragma("unroll") for (int n = 0; n < 2; ++n) _Pragma("unroll") for (int k = 0; k < 2; ++k) dst[n][k] = *(const LAS bf16x8*)(lds + PG8_SB(b, h) + boff + n * 2048 + k * 1024); } while (0)
; #define PG8_MMA(ai, bj, At, Bt) do { __builtin_amdgcn_s_setprio(1); _Pragma("unroll") for (int m = 0; m < 4; ++m) _Pragma("unroll") for (int n = 0; n < 2; ++n) _Pragma("unroll") for (int k = 0; k < 2; ++k) \
;         acc[ai][bj][m][n] = __builtin_amdgcn_mfma_f32_16x16x32_bf16(Bt[n][k], At[m][k], acc[ai][bj][m][n], 0, 0, 0); __builtin_amdgcn_s_setprio(0); } while (0)
; #define PG8_WAIT_V(n) asm volatile("s_waitcnt vmcnt(" #n ")" ::: "memory")
; #define PG8_WAIT_L(n) asm volatile("s_waitcnt lgkmcnt(" #n ")" ::: "memory")
; #define PG8_BAR __builtin_amdgcn_s_barrier()
; #define PG8_SCHED __builtin_amdgcn_sched_barrier(0)
; template <class Epi, bool ALIGN_EPI>
; __device__ __forceinline__ void gemm_phase(LAS unsigned char* lds, const Gemm g, const StaticOrder& S, const Epi& E) {
;     ...
;             const char* a1 = cA + (size_t)(t + 1) * kstep;
;             const char* a2 = last ? nA : cA + (size_t)(t + 2) * kstep; const char* b2 = last ? nB : cB + (size_t)(t + 2) * kstep;
;             const char* a3 = a2 + kstep; const char* b3 = b2 + kstep;
;             PG8_LDB(B0, 0, 0); PG8_LDB(B1, 0, 1); PG8_SCHED; PG8_LDA(At, 0, 0); PG8_STAGE(PG8_SA(1, 1), a1 + hA, voffA);
;             PG8_WAIT_V(8); PG8_WAIT_L(0); PG8_BAR; PG8_MMA(0, 0, At, B0); PG8_MMA(0, 1, At, B1); PG8_BAR; PG8_SCHED;
;             PG8_LDA(At, 0, 1); PG8_STAGE(PG8_SB(0, 0), b2, voffB); PG8_STAGE(PG8_SB(0, 1), b2 + hB, voffB); PG8_STAGE(PG8_SA(0, 0), a2, voffA);
;             PG8_WAIT_V(8); PG8_WAIT_L(0); PG8_BAR; PG8_MMA(1, 0, At, B0); PG8_MMA(1, 1, At, B1); PG8_BAR; PG8_SCHED;
.LBB0_252:
	ds_read_b128 v[168:171], v153
	ds_read_b128 v[172:175], v153 offset:1024
	ds_read_b128 v[176:179], v153 offset:2048
	ds_read_b128 v[180:183], v153 offset:3072
	ds_read_b128 v[184:187], v154
	ds_read_b128 v[188:191], v154 offset:1024
	ds_read_b128 v[194:197], v154 offset:2048
	ds_read_b128 v[198:201], v154 offset:3072
	s_add_u32 s8, s6, 0xfff80080
	s_addc_u32 s9, s7, -1
	s_cmp_eq_u32 s71, 28
	s_cselect_b32 s55, s47, s9
	s_cselect_b32 s54, s67, s8
	s_cselect_b32 s9, s45, s70
	s_cselect_b32 s8, s68, s69
	v_lshl_add_u64 v[234:235], s[6:7], 0, v[136:137]
	s_add_i32 m0, s39, 0xc000
	ds_read_b128 v[202:205], v155
	ds_read_b128 v[206:209], v155 offset:1024
	ds_read_b128 v[210:213], v155 offset:2048
	ds_read_b128 v[214:217], v155 offset:3072
	ds_read_b128 v[218:221], v155 offset:4096
	ds_read_b128 v[222:225], v155 offset:5120
	ds_read_b128 v[226:229], v155 offset:6144
	ds_read_b128 v[230:233], v155 offset:7168
	global_load_lds_dwordx4 v[234:235], off
	v_lshl_add_u64 v[234:235], s[6:7], 0, v[138:139]
	s_add_i32 m0, s39, 0xe000
	s_nop 0
	global_load_lds_dwordx4 v[234:235], off
	s_waitcnt vmcnt(8)
	s_waitcnt lgkmcnt(0)
	s_barrier
	s_setprio 1
	s_waitcnt lgkmcnt(0)
	v_mfma_f32_16x16x32_bf16 v[124:127], v[168:171], v[202:205], v[124:127]
	v_mfma_f32_16x16x32_bf16 v[124:127], v[172:175], v[206:209], v[124:127]
	v_mfma_f32_16x16x32_bf16 v[120:123], v[176:179], v[202:205], v[120:123]
	v_mfma_f32_16x16x32_bf16 v[120:123], v[180:183], v[206:209], v[120:123]
	v_mfma_f32_16x16x32_bf16 v[108:111], v[168:171], v[210:213], v[108:111]
	v_mfma_f32_16x16x32_bf16 v[108:111], v[172:175], v[214:217], v[108:111]
	v_mfma_f32_16x16x32_bf16 v[104:107], v[176:179], v[210:213], v[104:107]
	v_mfma_f32_16x16x32_bf16 v[104:107], v[180:183], v[214:217], v[104:107]
	v_mfma_f32_16x16x32_bf16 v[92:95], v[168:171], v[218:221], v[92:95]
	v_mfma_f32_16x16x32_bf16 v[92:95], v[172:175], v[222:225], v[92:95]
	v_mfma_f32_16x16x32_bf16 v[88:91], v[176:179], v[218:221], v[88:91]
	v_mfma_f32_16x16x32_bf16 v[88:91], v[180:183], v[222:225], v[88:91]
	v_mfma_f32_16x16x32_bf16 v[76:79], v[168:171], v[226:229], v[76:79]
	v_mfma_f32_16x16x32_bf16 v[76:79], v[172:175], v[230:233], v[76:79]
	v_mfma_f32_16x16x32_bf16 v[72:75], v[176:179], v[226:229], v[72:75]
	v_mfma_f32_16x16x32_bf16 v[72:75], v[180:183], v[230:233], v[72:75]
	s_setprio 0
	s_setprio 1
	v_mfma_f32_16x16x32_bf16 v[116:119], v[184:187], v[202:205], v[116:119]
	v_mfma_f32_16x16x32_bf16 v[116:119], v[188:191], v[206:209], v[116:119]
	v_mfma_f32_16x16x32_bf16 v[112:115], v[194:197], v[202:205], v[112:115]
	v_mfma_f32_16x16x32_bf16 v[112:115], v[198:201], v[206:209], v[112:115]
	v_mfma_f32_16x16x32_bf16 v[100:103], v[184:187], v[210:213], v[100:103]
	v_mfma_f32_16x16x32_bf16 v[100:103], v[188:191], v[214:217], v[100:103]
	v_mfma_f32_16x16x32_bf16 v[96:99], v[194:197], v[210:213], v[96:99]
	v_mfma_f32_16x16x32_bf16 v[96:99], v[198:201], v[214:217], v[96:99]
	v_mfma_f32_16x16x32_bf16 v[84:87], v[184:187], v[218:221], v[84:87]
	v_mfma_f32_16x16x32_bf16 v[84:87], v[188:191], v[222:225], v[84:87]
	v_mfma_f32_16x16x32_bf16 v[80:83], v[194:197], v[218:221], v[80:83]
	v_mfma_f32_16x16x32_bf16 v[80:83], v[198:201], v[222:225], v[80:83]
	s_barrier
	v_mfma_f32_16x16x32_bf16 v[68:71], v[184:187], v[226:229], v[68:71]
	v_mfma_f32_16x16x32_bf16 v[68:71], v[188:191], v[230:233], v[68:71]
	v_mfma_f32_16x16x32_bf16 v[64:67], v[194:197], v[226:229], v[64:67]
	v_mfma_f32_16x16x32_bf16 v[64:67], v[198:201], v[230:233], v[64:67]
	s_setprio 0
	s_add_i32 s72, s63, s33
	v_lshl_add_u64 v[234:235], s[8:9], 0, v[132:133]
	s_mov_b32 m0, s72
	ds_read_b128 v[202:205], v155 offset:16384
	ds_read_b128 v[206:209], v155 offset:17408
	ds_read_b128 v[210:213], v155 offset:18432
	ds_read_b128 v[214:217], v155 offset:19456
	ds_read_b128 v[218:221], v155 offset:20480
	ds_read_b128 v[222:225], v155 offset:21504
	ds_read_b128 v[226:229], v155 offset:22528
	ds_read_b128 v[230:233], v155 offset:23552
	global_load_lds_dwordx4 v[234:235], off
	s_add_i32 m0, s72, 0x2000
	s_add_u32 s72, s8, 0x80000
	v_lshl_add_u64 v[236:237], s[8:9], 0, v[128:129]
	s_addc_u32 s73, s9, 0
	s_add_i32 s74, s64, s33
	global_load_lds_dwordx4 v[236:237], off
	v_lshl_add_u64 v[238:239], s[72:73], 0, v[132:133]
	s_mov_b32 m0, s74
	v_lshl_add_u64 v[240:241], s[54:55], 0, v[130:131]
	global_load_lds_dwordx4 v[238:239], off
	v_lshl_add_u64 v[238:239], s[72:73], 0, v[128:129]
	s_add_i32 m0, s74, 0x2000
	s_nop 0
	global_load_lds_dwordx4 v[238:239], off
	v_lshl_add_u64 v[238:239], s[54:55], 0, v[134:135]
	s_mov_b32 m0, s39
	s_nop 0
	global_load_lds_dwordx4 v[238:239], off
	s_mov_b32 m0, s53
	s_nop 0
	global_load_lds_dwordx4 v[240:241], off
	s_waitcnt vmcnt(8)
	s_waitcnt lgkmcnt(0)
	s_barrier
; #define PG8_STAGE(bufoff, gbase, voff) do { _Pragma("unroll") for (int _i = 0; _i < 2; ++_i) \
;         __builtin_amdgcn_global_load_lds((const unsigned*)((const char*)(gbase) + (voff)[_i]), (LAS unsigned*)(lds + (bufoff) + ldsw + _i * 8192), 16, 0, 0); } while (0)
; #define PG8_LDA(dst, b, h) do { _Pragma("unroll") for (int m = 0; m < 4; ++m) _Pragma("unroll") for (int k = 0; k < 2; ++k) dst[m][k] = *(const LAS bf16x8*)(lds + PG8_SA(b, h) + aoff + m * 2048 + k * 1024); } while (0)
; #define PG8_LDB(dst, b, h) do { _Pragma("unroll") for (int n = 0; n < 2; ++n) _Pragma("unroll") for (int k = 0; k < 2; ++k) dst[n][k] = *(const LAS bf16x8*)(lds + PG8_SB(b, h) + boff + n * 2048 + k * 1024); } while (0)
; #define PG8_MMA(ai, bj, At, Bt) do { __builtin_amdgcn_s_setprio(1); _Pragma("unroll") for (int m = 0; m < 4; ++m) _Pragma("unroll") for (int n = 0; n < 2; ++n) _Pragma("unroll") for (int k = 0; k < 2; ++k) \
;         acc[ai][bj][m][n] = __builtin_amdgcn_mfma_f32_16x16x32_bf16(Bt[n][k], At[m][k], acc[ai][bj][m][n], 0, 0, 0); __builtin_amdgcn_s_setprio(0); } while (0)
; #define PG8_WAIT_V(n) asm volatile("s_waitcnt vmcnt(" #n ")" ::: "memory")
; #define PG8_WAIT_L(n) asm volatile("s_waitcnt lgkmcnt(" #n ")" ::: "memory")
; #define PG8_BAR __builtin_amdgcn_s_barrier()
; #define PG8_SCHED __builtin_amdgcn_sched_barrier(0)
; template <class Epi, bool ALIGN_EPI>
; __device__ __forceinline__ void gemm_phase(LAS unsigned char* lds, const Gemm g, const StaticOrder& S, const Epi& E) {
;     ...
;             PG8_WAIT_V(8); PG8_WAIT_L(0); PG8_BAR; PG8_MMA(1, 0, At, B0); PG8_MMA(1, 1, At, B1); PG8_BAR; PG8_SCHED;
;             PG8_LDB(B0, 1, 0); PG8_LDB(B1, 1, 1); PG8_SCHED; PG8_LDA(At, 1, 0); PG8_STAGE(PG8_SA(0, 1), a2 + hA, voffA);
;             PG8_WAIT_V(8); PG8_WAIT_L(0); PG8_BAR; PG8_MMA(0, 0, At, B0); PG8_MMA(0, 1, At, B1); PG8_BAR; PG8_SCHED;
	s_setprio 1
	s_waitcnt lgkmcnt(0)
	v_mfma_f32_16x16x32_bf16 v[60:63], v[168:171], v[202:205], v[60:63]
	v_mfma_f32_16x16x32_bf16 v[60:63], v[172:175], v[206:209], v[60:63]
	v_mfma_f32_16x16x32_bf16 v[56:59], v[176:179], v[202:205], v[56:59]
	v_mfma_f32_16x16x32_bf16 v[56:59], v[180:183], v[206:209], v[56:59]
	v_mfma_f32_16x16x32_bf16 v[48:51], v[168:171], v[210:213], v[48:51]
	v_mfma_f32_16x16x32_bf16 v[48:51], v[172:175], v[214:217], v[48:51]
	v_mfma_f32_16x16x32_bf16 v[40:43], v[176:179], v[210:213], v[40:43]
	v_mfma_f32_16x16x32_bf16 v[40:43], v[180:183], v[214:217], v[40:43]
	v_mfma_f32_16x16x32_bf16 v[32:35], v[168:171], v[218:221], v[32:35]
	v_mfma_f32_16x16x32_bf16 v[32:35], v[172:175], v[222:225], v[32:35]
	v_mfma_f32_16x16x32_bf16 v[24:27], v[176:179], v[218:221], v[24:27]
	v_mfma_f32_16x16x32_bf16 v[24:27], v[180:183], v[222:225], v[24:27]
	v_mfma_f32_16x16x32_bf16 v[16:19], v[168:171], v[226:229], v[16:19]
	v_mfma_f32_16x16x32_bf16 v[16:19], v[172:175], v[230:233], v[16:19]
	v_mfma_f32_16x16x32_bf16 v[8:11], v[176:179], v[226:229], v[8:11]
	v_mfma_f32_16x16x32_bf16 v[8:11], v[180:183], v[230:233], v[8:11]
	s_setprio 0
	s_setprio 1
	v_mfma_f32_16x16x32_bf16 v[52:55], v[184:187], v[202:205], v[52:55]
	v_mfma_f32_16x16x32_bf16 v[52:55], v[188:191], v[206:209], v[52:55]
	v_mfma_f32_16x16x32_bf16 v[44:47], v[194:197], v[202:205], v[44:47]
	v_mfma_f32_16x16x32_bf16 v[44:47], v[198:201], v[206:209], v[44:47]
	v_mfma_f32_16x16x32_bf16 v[36:39], v[184:187], v[210:213], v[36:39]
	v_mfma_f32_16x16x32_bf16 v[36:39], v[188:191], v[214:217], v[36:39]
	v_mfma_f32_16x16x32_bf16 v[28:31], v[194:197], v[210:213], v[28:31]
	v_mfma_f32_16x16x32_bf16 v[28:31], v[198:201], v[214:217], v[28:31]
	v_mfma_f32_16x16x32_bf16 v[20:23], v[184:187], v[218:221], v[20:23]
	v_mfma_f32_16x16x32_bf16 v[20:23], v[188:191], v[222:225], v[20:23]
	v_mfma_f32_16x16x32_bf16 v[12:15], v[194:197], v[218:221], v[12:15]
	v_mfma_f32_16x16x32_bf16 v[12:15], v[198:201], v[222:225], v[12:15]
	s_barrier
	v_mfma_f32_16x16x32_bf16 v[4:7], v[184:187], v[226:229], v[4:7]
	v_mfma_f32_16x16x32_bf16 v[4:7], v[188:191], v[230:233], v[4:7]
	v_mfma_f32_16x16x32_bf16 v[0:3], v[194:197], v[226:229], v[0:3]
	v_mfma_f32_16x16x32_bf16 v[0:3], v[198:201], v[230:233], v[0:3]
	s_setprio 0
	s_add_i32 s72, 0, 0x18000
	v_add_u32_e32 v167, s72, v149
	s_add_i32 s73, 0, 0x1c000
	ds_read_b128 v[168:171], v167
	ds_read_b128 v[172:175], v167 offset:1024
	ds_read_b128 v[176:179], v167 offset:2048
	ds_read_b128 v[180:183], v167 offset:3072
	v_add_u32_e32 v167, s73, v149
	ds_read_b128 v[184:187], v167
	ds_read_b128 v[188:191], v167 offset:1024
	ds_read_b128 v[194:197], v167 offset:2048
	ds_read_b128 v[198:201], v167 offset:3072
	s_add_u32 s54, s54, 0x80000
	s_addc_u32 s55, s55, 0
	s_mov_b32 m0, s56
	v_lshl_add_u64 v[242:243], s[54:55], 0, v[134:135]
	ds_read_b128 v[202:205], v155 offset:32768
	ds_read_b128 v[206:209], v155 offset:33792
	ds_read_b128 v[210:213], v155 offset:34816
	ds_read_b128 v[214:217], v155 offset:35840
	ds_read_b128 v[218:221], v155 offset:36864
	ds_read_b128 v[222:225], v155 offset:37888
	ds_read_b128 v[226:229], v155 offset:38912
	ds_read_b128 v[230:233], v155 offset:39936
	global_load_lds_dwordx4 v[242:243], off
	v_lshl_add_u64 v[242:243], s[54:55], 0, v[130:131]
	s_mov_b32 m0, s57
	s_nop 0
	global_load_lds_dwordx4 v[242:243], off
	s_waitcnt vmcnt(8)
	s_waitcnt lgkmcnt(0)
	s_barrier
	s_setprio 1
	s_waitcnt lgkmcnt(0)
	v_mfma_f32_16x16x32_bf16 v[124:127], v[168:171], v[202:205], v[124:127]
	v_mfma_f32_16x16x32_bf16 v[124:127], v[172:175], v[206:209], v[124:127]
	v_mfma_f32_16x16x32_bf16 v[120:123], v[176:179], v[202:205], v[120:123]
	v_mfma_f32_16x16x32_bf16 v[120:123], v[180:183], v[206:209], v[120:123]
	v_mfma_f32_16x16x32_bf16 v[108:111], v[168:171], v[210:213], v[108:111]
	v_mfma_f32_16x16x32_bf16 v[108:111], v[172:175], v[214:217], v[108:111]
	v_mfma_f32_16x16x32_bf16 v[104:107], v[176:179], v[210:213], v[104:107]
	v_mfma_f32_16x16x32_bf16 v[104:107], v[180:183], v[214:217], v[104:107]
	v_mfma_f32_16x16x32_bf16 v[92:95], v[168:171], v[218:221], v[92:95]
	v_mfma_f32_16x16x32_bf16 v[92:95], v[172:175], v[222:225], v[92:95]
	v_mfma_f32_16x16x32_bf16 v[88:91], v[176:179], v[218:221], v[88:91]
	v_mfma_f32_16x16x32_bf16 v[88:91], v[180:183], v[222:225], v[88:91]
	v_mfma_f32_16x16x32_bf16 v[76:79], v[168:171], v[226:229], v[76:79]
	v_mfma_f32_16x16x32_bf16 v[76:79], v[172:175], v[230:233], v[76:79]
	v_mfma_f32_16x16x32_bf16 v[72:75], v[176:179], v[226:229], v[72:75]
	v_mfma_f32_16x16x32_bf16 v[72:75], v[180:183], v[230:233], v[72:75]
	s_setprio 0
	s_setprio 1
	v_mfma_f32_16x16x32_bf16 v[116:119], v[184:187], v[202:205], v[116:119]
	v_mfma_f32_16x16x32_bf16 v[116:119], v[188:191], v[206:209], v[116:119]
	v_mfma_f32_16x16x32_bf16 v[112:115], v[194:197], v[202:205], v[112:115]
	v_mfma_f32_16x16x32_bf16 v[112:115], v[198:201], v[206:209], v[112:115]
	v_mfma_f32_16x16x32_bf16 v[100:103], v[184:187], v[210:213], v[100:103]
	v_mfma_f32_16x16x32_bf16 v[100:103], v[188:191], v[214:217], v[100:103]
	v_mfma_f32_16x16x32_bf16 v[96:99], v[194:197], v[210:213], v[96:99]
	v_mfma_f32_16x16x32_bf16 v[96:99], v[198:201], v[214:217], v[96:99]
	v_mfma_f32_16x16x32_bf16 v[84:87], v[184:187], v[218:221], v[84:87]
	v_mfma_f32_16x16x32_bf16 v[84:87], v[188:191], v[222:225], v[84:87]
	v_mfma_f32_16x16x32_bf16 v[80:83], v[194:197], v[218:221], v[80:83]
	v_mfma_f32_16x16x32_bf16 v[80:83], v[198:201], v[222:225], v[80:83]
	s_barrier
; #define PG8_STAGE(bufoff, gbase, voff) do { _Pragma("unroll") for (int _i = 0; _i < 2; ++_i) \
;         __builtin_amdgcn_global_load_lds((const unsigned*)((const char*)(gbase) + (voff)[_i]), (LAS unsigned*)(lds + (bufoff) + ldsw + _i * 8192), 16, 0, 0); } while (0)
; #define PG8_LDA(dst, b, h) do { _Pragma("unroll") for (int m = 0; m < 4; ++m) _Pragma("unroll") for (int k = 0; k < 2; ++k) dst[m][k] = *(const LAS bf16x8*)(lds + PG8_SA(b, h) + aoff + m * 2048 + k * 1024); } while (0)
; #define PG8_MMA(ai, bj, At, Bt) do { __builtin_amdgcn_s_setprio(1); _Pragma("unroll") for (int m = 0; m < 4; ++m) _Pragma("unroll") for (int n = 0; n < 2; ++n) _Pragma("unroll") for (int k = 0; k < 2; ++k) \
;         acc[ai][bj][m][n] = __builtin_amdgcn_mfma_f32_16x16x32_bf16(Bt[n][k], At[m][k], acc[ai][bj][m][n], 0, 0, 0); __builtin_amdgcn_s_setprio(0); } while (0)
; #define PG8_WAIT_V(n) asm volatile("s_waitcnt vmcnt(" #n ")" ::: "memory")
; #define PG8_WAIT_L(n) asm volatile("s_waitcnt lgkmcnt(" #n ")" ::: "memory")
; #define PG8_BAR __builtin_amdgcn_s_barrier()
; #define PG8_SCHED __builtin_amdgcn_sched_barrier(0)
; template <class Epi, bool ALIGN_EPI>
; __device__ __forceinline__ void gemm_phase(LAS unsigned char* lds, const Gemm g, const StaticOrder& S, const Epi& E) {
;     ...
;             PG8_WAIT_V(8); PG8_WAIT_L(0); PG8_BAR; PG8_MMA(0, 0, At, B0); PG8_MMA(0, 1, At, B1); PG8_BAR; PG8_SCHED;
;             PG8_LDA(At, 1, 1); PG8_STAGE(PG8_SB(1, 0), b3, voffB); PG8_STAGE(PG8_SB(1, 1), b3 + hB, voffB); PG8_STAGE(PG8_SA(1, 0), a3, voffA);
;             PG8_WAIT_V(8); PG8_WAIT_L(0); PG8_BAR; PG8_MMA(1, 0, At, B0); PG8_MMA(1, 1, At, B1); PG8_BAR; PG8_SCHED;
;         }
	v_mfma_f32_16x16x32_bf16 v[68:71], v[184:187], v[226:229], v[68:71]
	v_mfma_f32_16x16x32_bf16 v[68:71], v[188:191], v[230:233], v[68:71]
	v_mfma_f32_16x16x32_bf16 v[64:67], v[194:197], v[226:229], v[64:67]
	v_mfma_f32_16x16x32_bf16 v[64:67], v[198:201], v[230:233], v[64:67]
	s_setprio 0
	s_add_i32 s54, s72, s33
	v_lshl_add_u64 v[234:235], v[234:235], 0, s[20:21]
	s_mov_b32 m0, s54
	ds_read_b128 v[202:205], v155 offset:49152
	ds_read_b128 v[206:209], v155 offset:50176
	ds_read_b128 v[210:213], v155 offset:51200
	ds_read_b128 v[214:217], v155 offset:52224
	ds_read_b128 v[218:221], v155 offset:53248
	ds_read_b128 v[222:225], v155 offset:54272
	ds_read_b128 v[226:229], v155 offset:55296
	ds_read_b128 v[230:233], v155 offset:56320
	global_load_lds_dwordx4 v[234:235], off
	s_add_i32 m0, s54, 0x2000
	s_add_u32 s8, s8, 0x80080
	v_lshl_add_u64 v[234:235], v[236:237], 0, s[20:21]
	s_addc_u32 s9, s9, 0
	s_add_i32 s54, s73, s33
	global_load_lds_dwordx4 v[234:235], off
	v_lshl_add_u64 v[234:235], s[8:9], 0, v[132:133]
	s_mov_b32 m0, s54
	s_nop 0
	global_load_lds_dwordx4 v[234:235], off
	v_lshl_add_u64 v[234:235], s[8:9], 0, v[128:129]
	s_add_i32 m0, s54, 0x2000
	s_nop 0
	global_load_lds_dwordx4 v[234:235], off
	v_lshl_add_u64 v[234:235], v[238:239], 0, s[20:21]
	s_mov_b32 m0, s60
	s_nop 0
	global_load_lds_dwordx4 v[234:235], off
	v_lshl_add_u64 v[234:235], v[240:241], 0, s[20:21]
	s_mov_b32 m0, s61
	s_nop 0
	global_load_lds_dwordx4 v[234:235], off
	s_waitcnt vmcnt(8)
	s_waitcnt lgkmcnt(0)
	s_barrier
	s_setprio 1
	s_waitcnt lgkmcnt(0)
	v_mfma_f32_16x16x32_bf16 v[60:63], v[168:171], v[202:205], v[60:63]
	v_mfma_f32_16x16x32_bf16 v[60:63], v[172:175], v[206:209], v[60:63]
	v_mfma_f32_16x16x32_bf16 v[56:59], v[176:179], v[202:205], v[56:59]
	v_mfma_f32_16x16x32_bf16 v[56:59], v[180:183], v[206:209], v[56:59]
	v_mfma_f32_16x16x32_bf16 v[48:51], v[168:171], v[210:213], v[48:51]
	v_mfma_f32_16x16x32_bf16 v[48:51], v[172:175], v[214:217], v[48:51]
	v_mfma_f32_16x16x32_bf16 v[40:43], v[176:179], v[210:213], v[40:43]
	v_mfma_f32_16x16x32_bf16 v[40:43], v[180:183], v[214:217], v[40:43]
	v_mfma_f32_16x16x32_bf16 v[32:35], v[168:171], v[218:221], v[32:35]
	v_mfma_f32_16x16x32_bf16 v[32:35], v[172:175], v[222:225], v[32:35]
	v_mfma_f32_16x16x32_bf16 v[24:27], v[176:179], v[218:221], v[24:27]
	v_mfma_f32_16x16x32_bf16 v[24:27], v[180:183], v[222:225], v[24:27]
	v_mfma_f32_16x16x32_bf16 v[16:19], v[168:171], v[226:229], v[16:19]
	v_mfma_f32_16x16x32_bf16 v[16:19], v[172:175], v[230:233], v[16:19]
	v_mfma_f32_16x16x32_bf16 v[8:11], v[176:179], v[226:229], v[8:11]
	v_mfma_f32_16x16x32_bf16 v[8:11], v[180:183], v[230:233], v[8:11]
	s_setprio 0
	s_setprio 1
	v_mfma_f32_16x16x32_bf16 v[52:55], v[184:187], v[202:205], v[52:55]
	v_mfma_f32_16x16x32_bf16 v[52:55], v[188:191], v[206:209], v[52:55]
	v_mfma_f32_16x16x32_bf16 v[44:47], v[194:197], v[202:205], v[44:47]
	v_mfma_f32_16x16x32_bf16 v[44:47], v[198:201], v[206:209], v[44:47]
	v_mfma_f32_16x16x32_bf16 v[36:39], v[184:187], v[210:213], v[36:39]
	v_mfma_f32_16x16x32_bf16 v[36:39], v[188:191], v[214:217], v[36:39]
	v_mfma_f32_16x16x32_bf16 v[28:31], v[194:197], v[210:213], v[28:31]
	v_mfma_f32_16x16x32_bf16 v[28:31], v[198:201], v[214:217], v[28:31]
	v_mfma_f32_16x16x32_bf16 v[20:23], v[184:187], v[218:221], v[20:23]
	v_mfma_f32_16x16x32_bf16 v[20:23], v[188:191], v[222:225], v[20:23]
	v_mfma_f32_16x16x32_bf16 v[12:15], v[194:197], v[218:221], v[12:15]
	v_mfma_f32_16x16x32_bf16 v[12:15], v[198:201], v[222:225], v[12:15]
	s_barrier
	v_mfma_f32_16x16x32_bf16 v[4:7], v[184:187], v[226:229], v[4:7]
	v_mfma_f32_16x16x32_bf16 v[4:7], v[188:191], v[230:233], v[4:7]
	v_mfma_f32_16x16x32_bf16 v[0:3], v[194:197], v[226:229], v[0:3]
	v_mfma_f32_16x16x32_bf16 v[0:3], v[198:201], v[230:233], v[0:3]
	s_setprio 0
	s_add_i32 s71, s71, 2
	s_add_u32 s6, s6, 0x100
	s_addc_u32 s7, s7, 0
	s_add_u32 s69, s69, 0x100
	s_addc_u32 s70, s70, 0
	s_cmp_gt_u32 s71, 29
	s_cbranch_scc0 .LBB0_252
	s_and_b64 vcc, exec, s[22:23]
	s_cbranch_vccz .LBB0_255
	s_barrier

; #define PG8_STAGE(bufoff, gbase, voff) do { _Pragma("unroll") for (int _i = 0; _i < 2; ++_i) \
;         __builtin_amdgcn_global_load_lds((const unsigned*)((const char*)(gbase) + (voff)[_i]), (LAS unsigned*)(lds + (bufoff) + ldsw + _i * 8192), 16, 0, 0); } while (0)
; #define PG8_LDA(dst, b, h) do { _Pragma("unroll") for (int m = 0; m < 4; ++m) _Pragma("unroll") for (int k = 0; k < 2; ++k) dst[m][k] = *(const LAS bf16x8*)(lds + PG8_SA(b, h) + aoff + m * 2048 + k * 1024); } while (0)
; #define PG8_LDB(dst, b, h) do { _Pragma("unroll") for (int n = 0; n < 2; ++n) _Pragma("unroll") for (int k = 0; k < 2; ++k) dst[n][k] = *(const LAS bf16x8*)(lds + PG8_SB(b, h) + boff + n * 2048 + k * 1024); } while (0)
; #define PG8_MMA(ai, bj, At, Bt) do { __builtin_amdgcn_s_setprio(1); _Pragma("unroll") for (int m = 0; m < 4; ++m) _Pragma("unroll") for (int n = 0; n < 2; ++n) _Pragma("unroll") for (int k = 0; k < 2; ++k) \
;         acc[ai][bj][m][n] = __builtin_amdgcn_mfma_f32_16x16x32_bf16(Bt[n][k], At[m][k], acc[ai][bj][m][n], 0, 0, 0); __builtin_amdgcn_s_setprio(0); } while (0)
; #define PG8_WAIT_V(n) asm volatile("s_waitcnt vmcnt(" #n ")" ::: "memory")
; #define PG8_WAIT_L(n) asm volatile("s_waitcnt lgkmcnt(" #n ")" ::: "memory")
; #define PG8_BAR __builtin_amdgcn_s_barrier()
; #define PG8_SCHED __builtin_amdgcn_sched_barrier(0)
; template <class Epi, bool ALIGN_EPI>
; __device__ __forceinline__ void gemm_phase(LAS unsigned char* lds, const Gemm g, const StaticOrder& S, const Epi& E) {
;     ...
;             const char* a1 = cA + (size_t)(t + 1) * kstep;
;             const char* a2 = last ? nA : cA + (size_t)(t + 2) * kstep; const char* b2 = last ? nB : cB + (size_t)(t + 2) * kstep;
;             const char* a3 = a2 + kstep; const char* b3 = b2 + kstep;
;             PG8_LDB(B0, 0, 0); PG8_LDB(B1, 0, 1); PG8_SCHED; PG8_LDA(At, 0, 0); PG8_STAGE(PG8_SA(1, 1), a1 + hA, voffA);
;             PG8_WAIT_V(8); PG8_WAIT_L(0); PG8_BAR; PG8_MMA(0, 0, At, B0); PG8_MMA(0, 1, At, B1); PG8_BAR; PG8_SCHED;
;             PG8_LDA(At, 0, 1); PG8_STAGE(PG8_SB(0, 0), b2, voffB); PG8_STAGE(PG8_SB(0, 1), b2 + hB, voffB); PG8_STAGE(PG8_SA(0, 0), a2, voffA);
;             PG8_WAIT_V(8); PG8_WAIT_L(0); PG8_BAR; PG8_MMA(1, 0, At, B0); PG8_MMA(1, 1, At, B1); PG8_BAR; PG8_SCHED;
.LBB0_385:
	ds_read_b128 v[152:155], v149
	ds_read_b128 v[156:159], v149 offset:1024
	ds_read_b128 v[160:163], v149 offset:2048
	ds_read_b128 v[164:167], v149 offset:3072
	ds_read_b128 v[168:171], v150
	ds_read_b128 v[172:175], v150 offset:1024
	ds_read_b128 v[176:179], v150 offset:2048
	ds_read_b128 v[180:183], v150 offset:3072
	s_add_u32 s40, s36, 0xfff80080
	s_addc_u32 s41, s37, -1
	s_cmp_eq_u32 s61, 4
	s_cselect_b32 s43, s27, s41
	s_cselect_b32 s42, s57, s40
	s_cselect_b32 s41, s25, s60
	s_cselect_b32 s40, s58, s59
	v_lshl_add_u64 v[144:145], s[36:37], 0, v[136:137]
	s_add_i32 m0, s35, 0xc000
	ds_read_b128 v[184:187], v151
	ds_read_b128 v[188:191], v151 offset:1024
	ds_read_b128 v[194:197], v151 offset:2048
	ds_read_b128 v[198:201], v151 offset:3072
	ds_read_b128 v[202:205], v151 offset:4096
	ds_read_b128 v[206:209], v151 offset:5120
	ds_read_b128 v[210:213], v151 offset:6144
	ds_read_b128 v[214:217], v151 offset:7168
	global_load_lds_dwordx4 v[144:145], off
	v_lshl_add_u64 v[144:145], s[36:37], 0, v[138:139]
	s_add_i32 m0, s35, 0xe000
	s_nop 0
	global_load_lds_dwordx4 v[144:145], off
	s_waitcnt vmcnt(8)
	s_waitcnt lgkmcnt(0)
	s_barrier
	s_setprio 1
	s_waitcnt lgkmcnt(0)
	v_mfma_f32_16x16x32_bf16 v[124:127], v[152:155], v[184:187], v[124:127]
	v_mfma_f32_16x16x32_bf16 v[124:127], v[156:159], v[188:191], v[124:127]
	v_mfma_f32_16x16x32_bf16 v[120:123], v[160:163], v[184:187], v[120:123]
	v_mfma_f32_16x16x32_bf16 v[120:123], v[164:167], v[188:191], v[120:123]
	v_mfma_f32_16x16x32_bf16 v[116:119], v[152:155], v[194:197], v[116:119]
	v_mfma_f32_16x16x32_bf16 v[116:119], v[156:159], v[198:201], v[116:119]
	v_mfma_f32_16x16x32_bf16 v[108:111], v[160:163], v[194:197], v[108:111]
	v_mfma_f32_16x16x32_bf16 v[108:111], v[164:167], v[198:201], v[108:111]
	v_mfma_f32_16x16x32_bf16 v[100:103], v[152:155], v[202:205], v[100:103]
	v_mfma_f32_16x16x32_bf16 v[100:103], v[156:159], v[206:209], v[100:103]
	v_mfma_f32_16x16x32_bf16 v[92:95], v[160:163], v[202:205], v[92:95]
	v_mfma_f32_16x16x32_bf16 v[92:95], v[164:167], v[206:209], v[92:95]
	v_mfma_f32_16x16x32_bf16 v[84:87], v[152:155], v[210:213], v[84:87]
	v_mfma_f32_16x16x32_bf16 v[84:87], v[156:159], v[214:217], v[84:87]
	v_mfma_f32_16x16x32_bf16 v[76:79], v[160:163], v[210:213], v[76:79]
	v_mfma_f32_16x16x32_bf16 v[76:79], v[164:167], v[214:217], v[76:79]
	s_setprio 0
	s_setprio 1
	v_mfma_f32_16x16x32_bf16 v[112:115], v[168:171], v[184:187], v[112:115]
	v_mfma_f32_16x16x32_bf16 v[112:115], v[172:175], v[188:191], v[112:115]
	v_mfma_f32_16x16x32_bf16 v[104:107], v[176:179], v[184:187], v[104:107]
	v_mfma_f32_16x16x32_bf16 v[104:107], v[180:183], v[188:191], v[104:107]
	v_mfma_f32_16x16x32_bf16 v[96:99], v[168:171], v[194:197], v[96:99]
	v_mfma_f32_16x16x32_bf16 v[96:99], v[172:175], v[198:201], v[96:99]
	v_mfma_f32_16x16x32_bf16 v[88:91], v[176:179], v[194:197], v[88:91]
	v_mfma_f32_16x16x32_bf16 v[88:91], v[180:183], v[198:201], v[88:91]
	v_mfma_f32_16x16x32_bf16 v[80:83], v[168:171], v[202:205], v[80:83]
	v_mfma_f32_16x16x32_bf16 v[80:83], v[172:175], v[206:209], v[80:83]
	v_mfma_f32_16x16x32_bf16 v[72:75], v[176:179], v[202:205], v[72:75]
	v_mfma_f32_16x16x32_bf16 v[72:75], v[180:183], v[206:209], v[72:75]
	s_barrier
	v_mfma_f32_16x16x32_bf16 v[68:71], v[168:171], v[210:213], v[68:71]
	v_mfma_f32_16x16x32_bf16 v[68:71], v[172:175], v[214:217], v[68:71]
	v_mfma_f32_16x16x32_bf16 v[64:67], v[176:179], v[210:213], v[64:67]
	v_mfma_f32_16x16x32_bf16 v[64:67], v[180:183], v[214:217], v[64:67]
	s_setprio 0
	s_add_i32 s62, s53, s45
	v_lshl_add_u64 v[144:145], s[40:41], 0, v[132:133]
	s_mov_b32 m0, s62
	ds_read_b128 v[184:187], v151 offset:16384
	ds_read_b128 v[188:191], v151 offset:17408
	ds_read_b128 v[194:197], v151 offset:18432
	ds_read_b128 v[198:201], v151 offset:19456
	ds_read_b128 v[202:205], v151 offset:20480
	ds_read_b128 v[206:209], v151 offset:21504
	ds_read_b128 v[210:213], v151 offset:22528
	ds_read_b128 v[214:217], v151 offset:23552
	global_load_lds_dwordx4 v[144:145], off
	s_add_i32 m0, s62, 0x2000
	s_add_u32 s62, s40, 0x20000
	v_lshl_add_u64 v[218:219], s[40:41], 0, v[128:129]
	s_addc_u32 s63, s41, 0
	s_add_i32 s64, s54, s45
	global_load_lds_dwordx4 v[218:219], off
	v_lshl_add_u64 v[220:221], s[62:63], 0, v[132:133]
	s_mov_b32 m0, s64
	v_lshl_add_u64 v[222:223], s[42:43], 0, v[130:131]
	global_load_lds_dwordx4 v[220:221], off
	v_lshl_add_u64 v[220:221], s[62:63], 0, v[128:129]
	s_add_i32 m0, s64, 0x2000
	s_nop 0
	global_load_lds_dwordx4 v[220:221], off
	v_lshl_add_u64 v[220:221], s[42:43], 0, v[134:135]
	s_mov_b32 m0, s35
	s_nop 0
	global_load_lds_dwordx4 v[220:221], off
	s_mov_b32 m0, s47
	s_nop 0
	global_load_lds_dwordx4 v[222:223], off
	s_waitcnt vmcnt(8)
	s_waitcnt lgkmcnt(0)
	s_barrier
; #define PG8_STAGE(bufoff, gbase, voff) do { _Pragma("unroll") for (int _i = 0; _i < 2; ++_i) \
;         __builtin_amdgcn_global_load_lds((const unsigned*)((const char*)(gbase) + (voff)[_i]), (LAS unsigned*)(lds + (bufoff) + ldsw + _i * 8192), 16, 0, 0); } while (0)
; #define PG8_LDA(dst, b, h) do { _Pragma("unroll") for (int m = 0; m < 4; ++m) _Pragma("unroll") for (int k = 0; k < 2; ++k) dst[m][k] = *(const LAS bf16x8*)(lds + PG8_SA(b, h) + aoff + m * 2048 + k * 1024); } while (0)
; #define PG8_LDB(dst, b, h) do { _Pragma("unroll") for (int n = 0; n < 2; ++n) _Pragma("unroll") for (int k = 0; k < 2; ++k) dst[n][k] = *(const LAS bf16x8*)(lds + PG8_SB(b, h) + boff + n * 2048 + k * 1024); } while (0)
; #define PG8_MMA(ai, bj, At, Bt) do { __builtin_amdgcn_s_setprio(1); _Pragma("unroll") for (int m = 0; m < 4; ++m) _Pragma("unroll") for (int n = 0; n < 2; ++n) _Pragma("unroll") for (int k = 0; k < 2; ++k) \
;         acc[ai][bj][m][n] = __builtin_amdgcn_mfma_f32_16x16x32_bf16(Bt[n][k], At[m][k], acc[ai][bj][m][n], 0, 0, 0); __builtin_amdgcn_s_setprio(0); } while (0)
; #define PG8_WAIT_V(n) asm volatile("s_waitcnt vmcnt(" #n ")" ::: "memory")
; #define PG8_WAIT_L(n) asm volatile("s_waitcnt lgkmcnt(" #n ")" ::: "memory")
; #define PG8_BAR __builtin_amdgcn_s_barrier()
; #define PG8_SCHED __builtin_amdgcn_sched_barrier(0)
; template <class Epi, bool ALIGN_EPI>
; __device__ __forceinline__ void gemm_phase(LAS unsigned char* lds, const Gemm g, const StaticOrder& S, const Epi& E) {
;     ...
;             PG8_WAIT_V(8); PG8_WAIT_L(0); PG8_BAR; PG8_MMA(1, 0, At, B0); PG8_MMA(1, 1, At, B1); PG8_BAR; PG8_SCHED;
;             PG8_LDB(B0, 1, 0); PG8_LDB(B1, 1, 1); PG8_SCHED; PG8_LDA(At, 1, 0); PG8_STAGE(PG8_SA(0, 1), a2 + hA, voffA);
;             PG8_WAIT_V(8); PG8_WAIT_L(0); PG8_BAR; PG8_MMA(0, 0, At, B0); PG8_MMA(0, 1, At, B1); PG8_BAR; PG8_SCHED;
	s_setprio 1
	s_waitcnt lgkmcnt(0)
	v_mfma_f32_16x16x32_bf16 v[60:63], v[152:155], v[184:187], v[60:63]
	v_mfma_f32_16x16x32_bf16 v[60:63], v[156:159], v[188:191], v[60:63]
	v_mfma_f32_16x16x32_bf16 v[56:59], v[160:163], v[184:187], v[56:59]
	v_mfma_f32_16x16x32_bf16 v[56:59], v[164:167], v[188:191], v[56:59]
	v_mfma_f32_16x16x32_bf16 v[52:55], v[152:155], v[194:197], v[52:55]
	v_mfma_f32_16x16x32_bf16 v[52:55], v[156:159], v[198:201], v[52:55]
	v_mfma_f32_16x16x32_bf16 v[44:47], v[160:163], v[194:197], v[44:47]
	v_mfma_f32_16x16x32_bf16 v[44:47], v[164:167], v[198:201], v[44:47]
	v_mfma_f32_16x16x32_bf16 v[36:39], v[152:155], v[202:205], v[36:39]
	v_mfma_f32_16x16x32_bf16 v[36:39], v[156:159], v[206:209], v[36:39]
	v_mfma_f32_16x16x32_bf16 v[28:31], v[160:163], v[202:205], v[28:31]
	v_mfma_f32_16x16x32_bf16 v[28:31], v[164:167], v[206:209], v[28:31]
	v_mfma_f32_16x16x32_bf16 v[20:23], v[152:155], v[210:213], v[20:23]
	v_mfma_f32_16x16x32_bf16 v[20:23], v[156:159], v[214:217], v[20:23]
	v_mfma_f32_16x16x32_bf16 v[12:15], v[160:163], v[210:213], v[12:15]
	v_mfma_f32_16x16x32_bf16 v[12:15], v[164:167], v[214:217], v[12:15]
	s_setprio 0
	s_setprio 1
	v_mfma_f32_16x16x32_bf16 v[48:51], v[168:171], v[184:187], v[48:51]
	v_mfma_f32_16x16x32_bf16 v[48:51], v[172:175], v[188:191], v[48:51]
	v_mfma_f32_16x16x32_bf16 v[40:43], v[176:179], v[184:187], v[40:43]
	v_mfma_f32_16x16x32_bf16 v[40:43], v[180:183], v[188:191], v[40:43]
	v_mfma_f32_16x16x32_bf16 v[32:35], v[168:171], v[194:197], v[32:35]
	v_mfma_f32_16x16x32_bf16 v[32:35], v[172:175], v[198:201], v[32:35]
	v_mfma_f32_16x16x32_bf16 v[24:27], v[176:179], v[194:197], v[24:27]
	v_mfma_f32_16x16x32_bf16 v[24:27], v[180:183], v[198:201], v[24:27]
	v_mfma_f32_16x16x32_bf16 v[16:19], v[168:171], v[202:205], v[16:19]
	v_mfma_f32_16x16x32_bf16 v[16:19], v[172:175], v[206:209], v[16:19]
	v_mfma_f32_16x16x32_bf16 v[8:11], v[176:179], v[202:205], v[8:11]
	v_mfma_f32_16x16x32_bf16 v[8:11], v[180:183], v[206:209], v[8:11]
	s_barrier
	v_mfma_f32_16x16x32_bf16 v[4:7], v[168:171], v[210:213], v[4:7]
	v_mfma_f32_16x16x32_bf16 v[4:7], v[172:175], v[214:217], v[4:7]
	v_mfma_f32_16x16x32_bf16 v[0:3], v[176:179], v[210:213], v[0:3]
	v_mfma_f32_16x16x32_bf16 v[0:3], v[180:183], v[214:217], v[0:3]
	s_setprio 0
	s_add_i32 s62, 0, 0x18000
	s_add_i32 s63, 0, 0x1c000
	v_add_u32_e32 v164, s62, v147
	v_add_u32_e32 v180, s63, v147
	ds_read_b128 v[152:155], v164
	ds_read_b128 v[156:159], v164 offset:1024
	ds_read_b128 v[160:163], v164 offset:2048
	ds_read_b128 v[164:167], v164 offset:3072
	ds_read_b128 v[168:171], v180
	ds_read_b128 v[172:175], v180 offset:1024
	ds_read_b128 v[176:179], v180 offset:2048
	ds_read_b128 v[180:183], v180 offset:3072
	s_add_u32 s42, s42, 0x80000
	s_addc_u32 s43, s43, 0
	s_mov_b32 m0, s48
	v_lshl_add_u64 v[224:225], s[42:43], 0, v[134:135]
	ds_read_b128 v[184:187], v151 offset:32768
	ds_read_b128 v[188:191], v151 offset:33792
	ds_read_b128 v[194:197], v151 offset:34816
	ds_read_b128 v[198:201], v151 offset:35840
	ds_read_b128 v[202:205], v151 offset:36864
	ds_read_b128 v[206:209], v151 offset:37888
	ds_read_b128 v[210:213], v151 offset:38912
	ds_read_b128 v[214:217], v151 offset:39936
	global_load_lds_dwordx4 v[224:225], off
	v_lshl_add_u64 v[224:225], s[42:43], 0, v[130:131]
	s_mov_b32 m0, s49
	s_nop 0
	global_load_lds_dwordx4 v[224:225], off
	s_waitcnt vmcnt(8)
	s_waitcnt lgkmcnt(0)
	s_barrier
	s_setprio 1
	s_waitcnt lgkmcnt(0)
	v_mfma_f32_16x16x32_bf16 v[124:127], v[152:155], v[184:187], v[124:127]
	v_mfma_f32_16x16x32_bf16 v[124:127], v[156:159], v[188:191], v[124:127]
	v_mfma_f32_16x16x32_bf16 v[120:123], v[160:163], v[184:187], v[120:123]
	v_mfma_f32_16x16x32_bf16 v[120:123], v[164:167], v[188:191], v[120:123]
	v_mfma_f32_16x16x32_bf16 v[116:119], v[152:155], v[194:197], v[116:119]
	v_mfma_f32_16x16x32_bf16 v[116:119], v[156:159], v[198:201], v[116:119]
	v_mfma_f32_16x16x32_bf16 v[108:111], v[160:163], v[194:197], v[108:111]
	v_mfma_f32_16x16x32_bf16 v[108:111], v[164:167], v[198:201], v[108:111]
	v_mfma_f32_16x16x32_bf16 v[100:103], v[152:155], v[202:205], v[100:103]
	v_mfma_f32_16x16x32_bf16 v[100:103], v[156:159], v[206:209], v[100:103]
	v_mfma_f32_16x16x32_bf16 v[92:95], v[160:163], v[202:205], v[92:95]
	v_mfma_f32_16x16x32_bf16 v[92:95], v[164:167], v[206:209], v[92:95]
	v_mfma_f32_16x16x32_bf16 v[84:87], v[152:155], v[210:213], v[84:87]
	v_mfma_f32_16x16x32_bf16 v[84:87], v[156:159], v[214:217], v[84:87]
	v_mfma_f32_16x16x32_bf16 v[76:79], v[160:163], v[210:213], v[76:79]
	v_mfma_f32_16x16x32_bf16 v[76:79], v[164:167], v[214:217], v[76:79]
	s_setprio 0
	s_setprio 1
	v_mfma_f32_16x16x32_bf16 v[112:115], v[168:171], v[184:187], v[112:115]
	v_mfma_f32_16x16x32_bf16 v[112:115], v[172:175], v[188:191], v[112:115]
	v_mfma_f32_16x16x32_bf16 v[104:107], v[176:179], v[184:187], v[104:107]
	v_mfma_f32_16x16x32_bf16 v[104:107], v[180:183], v[188:191], v[104:107]
	v_mfma_f32_16x16x32_bf16 v[96:99], v[168:171], v[194:197], v[96:99]
	v_mfma_f32_16x16x32_bf16 v[96:99], v[172:175], v[198:201], v[96:99]
	v_mfma_f32_16x16x32_bf16 v[88:91], v[176:179], v[194:197], v[88:91]
	v_mfma_f32_16x16x32_bf16 v[88:91], v[180:183], v[198:201], v[88:91]
	v_mfma_f32_16x16x32_bf16 v[80:83], v[168:171], v[202:205], v[80:83]
	v_mfma_f32_16x16x32_bf16 v[80:83], v[172:175], v[206:209], v[80:83]
	v_mfma_f32_16x16x32_bf16 v[72:75], v[176:179], v[202:205], v[72:75]
	v_mfma_f32_16x16x32_bf16 v[72:75], v[180:183], v[206:209], v[72:75]
	s_barrier
; #define PG8_STAGE(bufoff, gbase, voff) do { _Pragma("unroll") for (int _i = 0; _i < 2; ++_i) \
;         __builtin_amdgcn_global_load_lds((const unsigned*)((const char*)(gbase) + (voff)[_i]), (LAS unsigned*)(lds + (bufoff) + ldsw + _i * 8192), 16, 0, 0); } while (0)
; #define PG8_LDA(dst, b, h) do { _Pragma("unroll") for (int m = 0; m < 4; ++m) _Pragma("unroll") for (int k = 0; k < 2; ++k) dst[m][k] = *(const LAS bf16x8*)(lds + PG8_SA(b, h) + aoff + m * 2048 + k * 1024); } while (0)
; #define PG8_MMA(ai, bj, At, Bt) do { __builtin_amdgcn_s_setprio(1); _Pragma("unroll") for (int m = 0; m < 4; ++m) _Pragma("unroll") for (int n = 0; n < 2; ++n) _Pragma("unroll") for (int k = 0; k < 2; ++k) \
;         acc[ai][bj][m][n] = __builtin_amdgcn_mfma_f32_16x16x32_bf16(Bt[n][k], At[m][k], acc[ai][bj][m][n], 0, 0, 0); __builtin_amdgcn_s_setprio(0); } while (0)
; #define PG8_WAIT_V(n) asm volatile("s_waitcnt vmcnt(" #n ")" ::: "memory")
; #define PG8_WAIT_L(n) asm volatile("s_waitcnt lgkmcnt(" #n ")" ::: "memory")
; #define PG8_BAR __builtin_amdgcn_s_barrier()
; #define PG8_SCHED __builtin_amdgcn_sched_barrier(0)
; template <class Epi, bool ALIGN_EPI>
; __device__ __forceinline__ void gemm_phase(LAS unsigned char* lds, const Gemm g, const StaticOrder& S, const Epi& E) {
;     ...
;             PG8_WAIT_V(8); PG8_WAIT_L(0); PG8_BAR; PG8_MMA(0, 0, At, B0); PG8_MMA(0, 1, At, B1); PG8_BAR; PG8_SCHED;
;             PG8_LDA(At, 1, 1); PG8_STAGE(PG8_SB(1, 0), b3, voffB); PG8_STAGE(PG8_SB(1, 1), b3 + hB, voffB); PG8_STAGE(PG8_SA(1, 0), a3, voffA);
;             PG8_WAIT_V(8); PG8_WAIT_L(0); PG8_BAR; PG8_MMA(1, 0, At, B0); PG8_MMA(1, 1, At, B1); PG8_BAR; PG8_SCHED;
;         }
	v_mfma_f32_16x16x32_bf16 v[68:71], v[168:171], v[210:213], v[68:71]
	v_mfma_f32_16x16x32_bf16 v[68:71], v[172:175], v[214:217], v[68:71]
	v_mfma_f32_16x16x32_bf16 v[64:67], v[176:179], v[210:213], v[64:67]
	v_mfma_f32_16x16x32_bf16 v[64:67], v[180:183], v[214:217], v[64:67]
	s_setprio 0
	s_add_i32 s42, s62, s45
	v_lshl_add_u64 v[144:145], v[144:145], 0, s[18:19]
	s_mov_b32 m0, s42
	ds_read_b128 v[184:187], v151 offset:49152
	ds_read_b128 v[188:191], v151 offset:50176
	ds_read_b128 v[194:197], v151 offset:51200
	ds_read_b128 v[198:201], v151 offset:52224
	ds_read_b128 v[202:205], v151 offset:53248
	ds_read_b128 v[206:209], v151 offset:54272
	ds_read_b128 v[210:213], v151 offset:55296
	ds_read_b128 v[214:217], v151 offset:56320
	global_load_lds_dwordx4 v[144:145], off
	s_add_i32 m0, s42, 0x2000
	s_add_u32 s40, s40, 0x20080
	v_lshl_add_u64 v[144:145], v[218:219], 0, s[18:19]
	s_addc_u32 s41, s41, 0
	s_add_i32 s42, s63, s45
	global_load_lds_dwordx4 v[144:145], off
	v_lshl_add_u64 v[144:145], s[40:41], 0, v[132:133]
	s_mov_b32 m0, s42
	s_nop 0
	global_load_lds_dwordx4 v[144:145], off
	v_lshl_add_u64 v[144:145], s[40:41], 0, v[128:129]
	s_add_i32 m0, s42, 0x2000
	s_nop 0
	global_load_lds_dwordx4 v[144:145], off
	v_lshl_add_u64 v[144:145], v[220:221], 0, s[18:19]
	s_mov_b32 m0, s50
	s_nop 0
	global_load_lds_dwordx4 v[144:145], off
	v_lshl_add_u64 v[144:145], v[222:223], 0, s[18:19]
	s_mov_b32 m0, s51
	s_nop 0
	global_load_lds_dwordx4 v[144:145], off
	s_waitcnt vmcnt(8)
	s_waitcnt lgkmcnt(0)
	s_barrier
	s_setprio 1
	s_waitcnt lgkmcnt(0)
	v_mfma_f32_16x16x32_bf16 v[60:63], v[152:155], v[184:187], v[60:63]
	v_mfma_f32_16x16x32_bf16 v[60:63], v[156:159], v[188:191], v[60:63]
	v_mfma_f32_16x16x32_bf16 v[56:59], v[160:163], v[184:187], v[56:59]
	v_mfma_f32_16x16x32_bf16 v[56:59], v[164:167], v[188:191], v[56:59]
	v_mfma_f32_16x16x32_bf16 v[52:55], v[152:155], v[194:197], v[52:55]
	v_mfma_f32_16x16x32_bf16 v[52:55], v[156:159], v[198:201], v[52:55]
	v_mfma_f32_16x16x32_bf16 v[44:47], v[160:163], v[194:197], v[44:47]
	v_mfma_f32_16x16x32_bf16 v[44:47], v[164:167], v[198:201], v[44:47]
	v_mfma_f32_16x16x32_bf16 v[36:39], v[152:155], v[202:205], v[36:39]
	v_mfma_f32_16x16x32_bf16 v[36:39], v[156:159], v[206:209], v[36:39]
	v_mfma_f32_16x16x32_bf16 v[28:31], v[160:163], v[202:205], v[28:31]
	v_mfma_f32_16x16x32_bf16 v[28:31], v[164:167], v[206:209], v[28:31]
	v_mfma_f32_16x16x32_bf16 v[20:23], v[152:155], v[210:213], v[20:23]
	v_mfma_f32_16x16x32_bf16 v[20:23], v[156:159], v[214:217], v[20:23]
	v_mfma_f32_16x16x32_bf16 v[12:15], v[160:163], v[210:213], v[12:15]
	v_mfma_f32_16x16x32_bf16 v[12:15], v[164:167], v[214:217], v[12:15]
	s_setprio 0
	s_setprio 1
	v_mfma_f32_16x16x32_bf16 v[48:51], v[168:171], v[184:187], v[48:51]
	v_mfma_f32_16x16x32_bf16 v[48:51], v[172:175], v[188:191], v[48:51]
	v_mfma_f32_16x16x32_bf16 v[40:43], v[176:179], v[184:187], v[40:43]
	v_mfma_f32_16x16x32_bf16 v[40:43], v[180:183], v[188:191], v[40:43]
	v_mfma_f32_16x16x32_bf16 v[32:35], v[168:171], v[194:197], v[32:35]
	v_mfma_f32_16x16x32_bf16 v[32:35], v[172:175], v[198:201], v[32:35]
	v_mfma_f32_16x16x32_bf16 v[24:27], v[176:179], v[194:197], v[24:27]
	v_mfma_f32_16x16x32_bf16 v[24:27], v[180:183], v[198:201], v[24:27]
	v_mfma_f32_16x16x32_bf16 v[16:19], v[168:171], v[202:205], v[16:19]
	v_mfma_f32_16x16x32_bf16 v[16:19], v[172:175], v[206:209], v[16:19]
	v_mfma_f32_16x16x32_bf16 v[8:11], v[176:179], v[202:205], v[8:11]
	v_mfma_f32_16x16x32_bf16 v[8:11], v[180:183], v[206:209], v[8:11]
	s_barrier
	v_mfma_f32_16x16x32_bf16 v[4:7], v[168:171], v[210:213], v[4:7]
	v_mfma_f32_16x16x32_bf16 v[4:7], v[172:175], v[214:217], v[4:7]
	v_mfma_f32_16x16x32_bf16 v[0:3], v[176:179], v[210:213], v[0:3]
	v_mfma_f32_16x16x32_bf16 v[0:3], v[180:183], v[214:217], v[0:3]
	s_setprio 0
	s_add_i32 s61, s61, 2
	s_add_u32 s36, s36, 0x100
	s_addc_u32 s37, s37, 0
	s_add_u32 s59, s59, 0x100
	s_addc_u32 s60, s60, 0
	s_cmp_gt_u32 s61, 5
	s_cbranch_scc0 .LBB0_385
	s_and_b64 vcc, exec, s[20:21]
	s_cbranch_vccz .LBB0_388
	s_barrier

; #define PG8_STAGE(bufoff, gbase, voff) do { _Pragma("unroll") for (int _i = 0; _i < 2; ++_i) \
;         __builtin_amdgcn_global_load_lds((const unsigned*)((const char*)(gbase) + (voff)[_i]), (LAS unsigned*)(lds + (bufoff) + ldsw + _i * 8192), 16, 0, 0); } while (0)
; #define PG8_LDA(dst, b, h) do { _Pragma("unroll") for (int m = 0; m < 4; ++m) _Pragma("unroll") for (int k = 0; k < 2; ++k) dst[m][k] = *(const LAS bf16x8*)(lds + PG8_SA(b, h) + aoff + m * 2048 + k * 1024); } while (0)
; #define PG8_LDB(dst, b, h) do { _Pragma("unroll") for (int n = 0; n < 2; ++n) _Pragma("unroll") for (int k = 0; k < 2; ++k) dst[n][k] = *(const LAS bf16x8*)(lds + PG8_SB(b, h) + boff + n * 2048 + k * 1024); } while (0)
; #define PG8_MMA(ai, bj, At, Bt) do { __builtin_amdgcn_s_setprio(1); _Pragma("unroll") for (int m = 0; m < 4; ++m) _Pragma("unroll") for (int n = 0; n < 2; ++n) _Pragma("unroll") for (int k = 0; k < 2; ++k) \
;         acc[ai][bj][m][n] = __builtin_amdgcn_mfma_f32_16x16x32_bf16(Bt[n][k], At[m][k], acc[ai][bj][m][n], 0, 0, 0); __builtin_amdgcn_s_setprio(0); } while (0)
; #define PG8_WAIT_V(n) asm volatile("s_waitcnt vmcnt(" #n ")" ::: "memory")
; #define PG8_WAIT_L(n) asm volatile("s_waitcnt lgkmcnt(" #n ")" ::: "memory")
; #define PG8_BAR __builtin_amdgcn_s_barrier()
; #define PG8_SCHED __builtin_amdgcn_sched_barrier(0)
; template <class Epi, bool ALIGN_EPI>
; __device__ __forceinline__ void gemm_phase(LAS unsigned char* lds, const Gemm g, const StaticOrder& S, const Epi& E) {
;     ...
;             const char* a1 = cA + (size_t)(t + 1) * kstep;
;             const char* a2 = last ? nA : cA + (size_t)(t + 2) * kstep; const char* b2 = last ? nB : cB + (size_t)(t + 2) * kstep;
;             const char* a3 = a2 + kstep; const char* b3 = b2 + kstep;
;             PG8_LDB(B0, 0, 0); PG8_LDB(B1, 0, 1); PG8_SCHED; PG8_LDA(At, 0, 0); PG8_STAGE(PG8_SA(1, 1), a1 + hA, voffA);
;             PG8_WAIT_V(8); PG8_WAIT_L(0); PG8_BAR; PG8_MMA(0, 0, At, B0); PG8_MMA(0, 1, At, B1); PG8_BAR; PG8_SCHED;
;             PG8_LDA(At, 0, 1); PG8_STAGE(PG8_SB(0, 0), b2, voffB); PG8_STAGE(PG8_SB(0, 1), b2 + hB, voffB); PG8_STAGE(PG8_SA(0, 0), a2, voffA);
;             PG8_WAIT_V(8); PG8_WAIT_L(0); PG8_BAR; PG8_MMA(1, 0, At, B0); PG8_MMA(1, 1, At, B1); PG8_BAR; PG8_SCHED;
.LBB0_403:
	ds_read_b128 v[152:155], v149
	ds_read_b128 v[156:159], v149 offset:1024
	ds_read_b128 v[160:163], v149 offset:2048
	ds_read_b128 v[164:167], v149 offset:3072
	ds_read_b128 v[168:171], v150
	ds_read_b128 v[172:175], v150 offset:1024
	ds_read_b128 v[176:179], v150 offset:2048
	ds_read_b128 v[180:183], v150 offset:3072
	s_add_u32 s30, s6, 0xfff80080
	s_addc_u32 s31, s7, -1
	s_cmp_eq_u32 s53, 8
	s_cselect_b32 s35, s23, s31
	s_cselect_b32 s34, s50, s30
	s_cselect_b32 s31, s25, s52
	s_cselect_b32 s30, s24, s51
	v_lshl_add_u64 v[144:145], s[6:7], 0, v[136:137]
	s_add_i32 m0, s0, 0xc000
	ds_read_b128 v[184:187], v151
	ds_read_b128 v[188:191], v151 offset:1024
	ds_read_b128 v[194:197], v151 offset:2048
	ds_read_b128 v[198:201], v151 offset:3072
	ds_read_b128 v[202:205], v151 offset:4096
	ds_read_b128 v[206:209], v151 offset:5120
	ds_read_b128 v[210:213], v151 offset:6144
	ds_read_b128 v[214:217], v151 offset:7168
	global_load_lds_dwordx4 v[144:145], off
	v_lshl_add_u64 v[144:145], s[6:7], 0, v[138:139]
	s_add_i32 m0, s0, 0xe000
	s_nop 0
	global_load_lds_dwordx4 v[144:145], off
	s_waitcnt vmcnt(8)
	s_waitcnt lgkmcnt(0)
	s_barrier
	s_setprio 1
	s_waitcnt lgkmcnt(0)
	v_mfma_f32_16x16x32_bf16 v[124:127], v[152:155], v[184:187], v[124:127]
	v_mfma_f32_16x16x32_bf16 v[124:127], v[156:159], v[188:191], v[124:127]
	v_mfma_f32_16x16x32_bf16 v[120:123], v[160:163], v[184:187], v[120:123]
	v_mfma_f32_16x16x32_bf16 v[120:123], v[164:167], v[188:191], v[120:123]
	v_mfma_f32_16x16x32_bf16 v[116:119], v[152:155], v[194:197], v[116:119]
	v_mfma_f32_16x16x32_bf16 v[116:119], v[156:159], v[198:201], v[116:119]
	v_mfma_f32_16x16x32_bf16 v[108:111], v[160:163], v[194:197], v[108:111]
	v_mfma_f32_16x16x32_bf16 v[108:111], v[164:167], v[198:201], v[108:111]
	v_mfma_f32_16x16x32_bf16 v[100:103], v[152:155], v[202:205], v[100:103]
	v_mfma_f32_16x16x32_bf16 v[100:103], v[156:159], v[206:209], v[100:103]
	v_mfma_f32_16x16x32_bf16 v[92:95], v[160:163], v[202:205], v[92:95]
	v_mfma_f32_16x16x32_bf16 v[92:95], v[164:167], v[206:209], v[92:95]
	v_mfma_f32_16x16x32_bf16 v[84:87], v[152:155], v[210:213], v[84:87]
	v_mfma_f32_16x16x32_bf16 v[84:87], v[156:159], v[214:217], v[84:87]
	v_mfma_f32_16x16x32_bf16 v[76:79], v[160:163], v[210:213], v[76:79]
	v_mfma_f32_16x16x32_bf16 v[76:79], v[164:167], v[214:217], v[76:79]
	s_setprio 0
	s_setprio 1
	v_mfma_f32_16x16x32_bf16 v[112:115], v[168:171], v[184:187], v[112:115]
	v_mfma_f32_16x16x32_bf16 v[112:115], v[172:175], v[188:191], v[112:115]
	v_mfma_f32_16x16x32_bf16 v[104:107], v[176:179], v[184:187], v[104:107]
	v_mfma_f32_16x16x32_bf16 v[104:107], v[180:183], v[188:191], v[104:107]
	v_mfma_f32_16x16x32_bf16 v[96:99], v[168:171], v[194:197], v[96:99]
	v_mfma_f32_16x16x32_bf16 v[96:99], v[172:175], v[198:201], v[96:99]
	v_mfma_f32_16x16x32_bf16 v[88:91], v[176:179], v[194:197], v[88:91]
	v_mfma_f32_16x16x32_bf16 v[88:91], v[180:183], v[198:201], v[88:91]
	v_mfma_f32_16x16x32_bf16 v[80:83], v[168:171], v[202:205], v[80:83]
	v_mfma_f32_16x16x32_bf16 v[80:83], v[172:175], v[206:209], v[80:83]
	v_mfma_f32_16x16x32_bf16 v[72:75], v[176:179], v[202:205], v[72:75]
	v_mfma_f32_16x16x32_bf16 v[72:75], v[180:183], v[206:209], v[72:75]
	s_barrier
	v_mfma_f32_16x16x32_bf16 v[68:71], v[168:171], v[210:213], v[68:71]
	v_mfma_f32_16x16x32_bf16 v[68:71], v[172:175], v[214:217], v[68:71]
	v_mfma_f32_16x16x32_bf16 v[64:67], v[176:179], v[210:213], v[64:67]
	v_mfma_f32_16x16x32_bf16 v[64:67], v[180:183], v[214:217], v[64:67]
	s_setprio 0
	s_add_i32 s54, s45, s2
	v_lshl_add_u64 v[144:145], s[30:31], 0, v[132:133]
	s_mov_b32 m0, s54
	ds_read_b128 v[184:187], v151 offset:16384
	ds_read_b128 v[188:191], v151 offset:17408
	ds_read_b128 v[194:197], v151 offset:18432
	ds_read_b128 v[198:201], v151 offset:19456
	ds_read_b128 v[202:205], v151 offset:20480
	ds_read_b128 v[206:209], v151 offset:21504
	ds_read_b128 v[210:213], v151 offset:22528
	ds_read_b128 v[214:217], v151 offset:23552
	global_load_lds_dwordx4 v[144:145], off
	s_add_i32 m0, s54, 0x2000
	s_add_u32 s54, s30, 0x30000
	v_lshl_add_u64 v[218:219], s[30:31], 0, v[128:129]
	s_addc_u32 s55, s31, 0
	s_add_i32 s56, s46, s2
	global_load_lds_dwordx4 v[218:219], off
	v_lshl_add_u64 v[220:221], s[54:55], 0, v[132:133]
	s_mov_b32 m0, s56
	v_lshl_add_u64 v[222:223], s[34:35], 0, v[130:131]
	global_load_lds_dwordx4 v[220:221], off
	v_lshl_add_u64 v[220:221], s[54:55], 0, v[128:129]
	s_add_i32 m0, s56, 0x2000
	s_nop 0
	global_load_lds_dwordx4 v[220:221], off
	v_lshl_add_u64 v[220:221], s[34:35], 0, v[134:135]
	s_mov_b32 m0, s0
	s_nop 0
	global_load_lds_dwordx4 v[220:221], off
	s_mov_b32 m0, s1
	s_nop 0
	global_load_lds_dwordx4 v[222:223], off
	s_waitcnt vmcnt(8)
	s_waitcnt lgkmcnt(0)
	s_barrier
; #define PG8_STAGE(bufoff, gbase, voff) do { _Pragma("unroll") for (int _i = 0; _i < 2; ++_i) \
;         __builtin_amdgcn_global_load_lds((const unsigned*)((const char*)(gbase) + (voff)[_i]), (LAS unsigned*)(lds + (bufoff) + ldsw + _i * 8192), 16, 0, 0); } while (0)
; #define PG8_LDA(dst, b, h) do { _Pragma("unroll") for (int m = 0; m < 4; ++m) _Pragma("unroll") for (int k = 0; k < 2; ++k) dst[m][k] = *(const LAS bf16x8*)(lds + PG8_SA(b, h) + aoff + m * 2048 + k * 1024); } while (0)
; #define PG8_LDB(dst, b, h) do { _Pragma("unroll") for (int n = 0; n < 2; ++n) _Pragma("unroll") for (int k = 0; k < 2; ++k) dst[n][k] = *(const LAS bf16x8*)(lds + PG8_SB(b, h) + boff + n * 2048 + k * 1024); } while (0)
; #define PG8_MMA(ai, bj, At, Bt) do { __builtin_amdgcn_s_setprio(1); _Pragma("unroll") for (int m = 0; m < 4; ++m) _Pragma("unroll") for (int n = 0; n < 2; ++n) _Pragma("unroll") for (int k = 0; k < 2; ++k) \
;         acc[ai][bj][m][n] = __builtin_amdgcn_mfma_f32_16x16x32_bf16(Bt[n][k], At[m][k], acc[ai][bj][m][n], 0, 0, 0); __builtin_amdgcn_s_setprio(0); } while (0)
; #define PG8_WAIT_V(n) asm volatile("s_waitcnt vmcnt(" #n ")" ::: "memory")
; #define PG8_WAIT_L(n) asm volatile("s_waitcnt lgkmcnt(" #n ")" ::: "memory")
; #define PG8_BAR __builtin_amdgcn_s_barrier()
; #define PG8_SCHED __builtin_amdgcn_sched_barrier(0)
; template <class Epi, bool ALIGN_EPI>
; __device__ __forceinline__ void gemm_phase(LAS unsigned char* lds, const Gemm g, const StaticOrder& S, const Epi& E) {
;     ...
;             PG8_WAIT_V(8); PG8_WAIT_L(0); PG8_BAR; PG8_MMA(1, 0, At, B0); PG8_MMA(1, 1, At, B1); PG8_BAR; PG8_SCHED;
;             PG8_LDB(B0, 1, 0); PG8_LDB(B1, 1, 1); PG8_SCHED; PG8_LDA(At, 1, 0); PG8_STAGE(PG8_SA(0, 1), a2 + hA, voffA);
;             PG8_WAIT_V(8); PG8_WAIT_L(0); PG8_BAR; PG8_MMA(0, 0, At, B0); PG8_MMA(0, 1, At, B1); PG8_BAR; PG8_SCHED;
	s_setprio 1
	s_waitcnt lgkmcnt(0)
	v_mfma_f32_16x16x32_bf16 v[60:63], v[152:155], v[184:187], v[60:63]
	v_mfma_f32_16x16x32_bf16 v[60:63], v[156:159], v[188:191], v[60:63]
	v_mfma_f32_16x16x32_bf16 v[56:59], v[160:163], v[184:187], v[56:59]
	v_mfma_f32_16x16x32_bf16 v[56:59], v[164:167], v[188:191], v[56:59]
	v_mfma_f32_16x16x32_bf16 v[52:55], v[152:155], v[194:197], v[52:55]
	v_mfma_f32_16x16x32_bf16 v[52:55], v[156:159], v[198:201], v[52:55]
	v_mfma_f32_16x16x32_bf16 v[44:47], v[160:163], v[194:197], v[44:47]
	v_mfma_f32_16x16x32_bf16 v[44:47], v[164:167], v[198:201], v[44:47]
	v_mfma_f32_16x16x32_bf16 v[36:39], v[152:155], v[202:205], v[36:39]
	v_mfma_f32_16x16x32_bf16 v[36:39], v[156:159], v[206:209], v[36:39]
	v_mfma_f32_16x16x32_bf16 v[28:31], v[160:163], v[202:205], v[28:31]
	v_mfma_f32_16x16x32_bf16 v[28:31], v[164:167], v[206:209], v[28:31]
	v_mfma_f32_16x16x32_bf16 v[20:23], v[152:155], v[210:213], v[20:23]
	v_mfma_f32_16x16x32_bf16 v[20:23], v[156:159], v[214:217], v[20:23]
	v_mfma_f32_16x16x32_bf16 v[12:15], v[160:163], v[210:213], v[12:15]
	v_mfma_f32_16x16x32_bf16 v[12:15], v[164:167], v[214:217], v[12:15]
	s_setprio 0
	s_setprio 1
	v_mfma_f32_16x16x32_bf16 v[48:51], v[168:171], v[184:187], v[48:51]
	v_mfma_f32_16x16x32_bf16 v[48:51], v[172:175], v[188:191], v[48:51]
	v_mfma_f32_16x16x32_bf16 v[40:43], v[176:179], v[184:187], v[40:43]
	v_mfma_f32_16x16x32_bf16 v[40:43], v[180:183], v[188:191], v[40:43]
	v_mfma_f32_16x16x32_bf16 v[32:35], v[168:171], v[194:197], v[32:35]
	v_mfma_f32_16x16x32_bf16 v[32:35], v[172:175], v[198:201], v[32:35]
	v_mfma_f32_16x16x32_bf16 v[24:27], v[176:179], v[194:197], v[24:27]
	v_mfma_f32_16x16x32_bf16 v[24:27], v[180:183], v[198:201], v[24:27]
	v_mfma_f32_16x16x32_bf16 v[16:19], v[168:171], v[202:205], v[16:19]
	v_mfma_f32_16x16x32_bf16 v[16:19], v[172:175], v[206:209], v[16:19]
	v_mfma_f32_16x16x32_bf16 v[8:11], v[176:179], v[202:205], v[8:11]
	v_mfma_f32_16x16x32_bf16 v[8:11], v[180:183], v[206:209], v[8:11]
	s_barrier
	v_mfma_f32_16x16x32_bf16 v[4:7], v[168:171], v[210:213], v[4:7]
	v_mfma_f32_16x16x32_bf16 v[4:7], v[172:175], v[214:217], v[4:7]
	v_mfma_f32_16x16x32_bf16 v[0:3], v[176:179], v[210:213], v[0:3]
	v_mfma_f32_16x16x32_bf16 v[0:3], v[180:183], v[214:217], v[0:3]
	s_setprio 0
	s_add_i32 s54, 0, 0x18000
	s_add_i32 s55, 0, 0x1c000
	v_add_u32_e32 v164, s54, v147
	v_add_u32_e32 v180, s55, v147
	ds_read_b128 v[152:155], v164
	ds_read_b128 v[156:159], v164 offset:1024
	ds_read_b128 v[160:163], v164 offset:2048
	ds_read_b128 v[164:167], v164 offset:3072
	ds_read_b128 v[168:171], v180
	ds_read_b128 v[172:175], v180 offset:1024
	ds_read_b128 v[176:179], v180 offset:2048
	ds_read_b128 v[180:183], v180 offset:3072
	s_add_u32 s34, s34, 0x80000
	s_addc_u32 s35, s35, 0
	s_mov_b32 m0, s29
	v_lshl_add_u64 v[224:225], s[34:35], 0, v[134:135]
	ds_read_b128 v[184:187], v151 offset:32768
	ds_read_b128 v[188:191], v151 offset:33792
	ds_read_b128 v[194:197], v151 offset:34816
	ds_read_b128 v[198:201], v151 offset:35840
	ds_read_b128 v[202:205], v151 offset:36864
	ds_read_b128 v[206:209], v151 offset:37888
	ds_read_b128 v[210:213], v151 offset:38912
	ds_read_b128 v[214:217], v151 offset:39936
	global_load_lds_dwordx4 v[224:225], off
	v_lshl_add_u64 v[224:225], s[34:35], 0, v[130:131]
	s_mov_b32 m0, s40
	s_nop 0
	global_load_lds_dwordx4 v[224:225], off
	s_waitcnt vmcnt(8)
	s_waitcnt lgkmcnt(0)
	s_barrier
	s_setprio 1
	s_waitcnt lgkmcnt(0)
	v_mfma_f32_16x16x32_bf16 v[124:127], v[152:155], v[184:187], v[124:127]
	v_mfma_f32_16x16x32_bf16 v[124:127], v[156:159], v[188:191], v[124:127]
	v_mfma_f32_16x16x32_bf16 v[120:123], v[160:163], v[184:187], v[120:123]
	v_mfma_f32_16x16x32_bf16 v[120:123], v[164:167], v[188:191], v[120:123]
	v_mfma_f32_16x16x32_bf16 v[116:119], v[152:155], v[194:197], v[116:119]
	v_mfma_f32_16x16x32_bf16 v[116:119], v[156:159], v[198:201], v[116:119]
	v_mfma_f32_16x16x32_bf16 v[108:111], v[160:163], v[194:197], v[108:111]
	v_mfma_f32_16x16x32_bf16 v[108:111], v[164:167], v[198:201], v[108:111]
	v_mfma_f32_16x16x32_bf16 v[100:103], v[152:155], v[202:205], v[100:103]
	v_mfma_f32_16x16x32_bf16 v[100:103], v[156:159], v[206:209], v[100:103]
	v_mfma_f32_16x16x32_bf16 v[92:95], v[160:163], v[202:205], v[92:95]
	v_mfma_f32_16x16x32_bf16 v[92:95], v[164:167], v[206:209], v[92:95]
	v_mfma_f32_16x16x32_bf16 v[84:87], v[152:155], v[210:213], v[84:87]
	v_mfma_f32_16x16x32_bf16 v[84:87], v[156:159], v[214:217], v[84:87]
	v_mfma_f32_16x16x32_bf16 v[76:79], v[160:163], v[210:213], v[76:79]
	v_mfma_f32_16x16x32_bf16 v[76:79], v[164:167], v[214:217], v[76:79]
	s_setprio 0
	s_setprio 1
	v_mfma_f32_16x16x32_bf16 v[112:115], v[168:171], v[184:187], v[112:115]
	v_mfma_f32_16x16x32_bf16 v[112:115], v[172:175], v[188:191], v[112:115]
	v_mfma_f32_16x16x32_bf16 v[104:107], v[176:179], v[184:187], v[104:107]
	v_mfma_f32_16x16x32_bf16 v[104:107], v[180:183], v[188:191], v[104:107]
	v_mfma_f32_16x16x32_bf16 v[96:99], v[168:171], v[194:197], v[96:99]
	v_mfma_f32_16x16x32_bf16 v[96:99], v[172:175], v[198:201], v[96:99]
	v_mfma_f32_16x16x32_bf16 v[88:91], v[176:179], v[194:197], v[88:91]
	v_mfma_f32_16x16x32_bf16 v[88:91], v[180:183], v[198:201], v[88:91]
	v_mfma_f32_16x16x32_bf16 v[80:83], v[168:171], v[202:205], v[80:83]
	v_mfma_f32_16x16x32_bf16 v[80:83], v[172:175], v[206:209], v[80:83]
	v_mfma_f32_16x16x32_bf16 v[72:75], v[176:179], v[202:205], v[72:75]
	v_mfma_f32_16x16x32_bf16 v[72:75], v[180:183], v[206:209], v[72:75]
	s_barrier
; #define PG8_STAGE(bufoff, gbase, voff) do { _Pragma("unroll") for (int _i = 0; _i < 2; ++_i) \
;         __builtin_amdgcn_global_load_lds((const unsigned*)((const char*)(gbase) + (voff)[_i]), (LAS unsigned*)(lds + (bufoff) + ldsw + _i * 8192), 16, 0, 0); } while (0)
; #define PG8_LDA(dst, b, h) do { _Pragma("unroll") for (int m = 0; m < 4; ++m) _Pragma("unroll") for (int k = 0; k < 2; ++k) dst[m][k] = *(const LAS bf16x8*)(lds + PG8_SA(b, h) + aoff + m * 2048 + k * 1024); } while (0)
; #define PG8_MMA(ai, bj, At, Bt) do { __builtin_amdgcn_s_setprio(1); _Pragma("unroll") for (int m = 0; m < 4; ++m) _Pragma("unroll") for (int n = 0; n < 2; ++n) _Pragma("unroll") for (int k = 0; k < 2; ++k) \
;         acc[ai][bj][m][n] = __builtin_amdgcn_mfma_f32_16x16x32_bf16(Bt[n][k], At[m][k], acc[ai][bj][m][n], 0, 0, 0); __builtin_amdgcn_s_setprio(0); } while (0)
; #define PG8_WAIT_V(n) asm volatile("s_waitcnt vmcnt(" #n ")" ::: "memory")
; #define PG8_WAIT_L(n) asm volatile("s_waitcnt lgkmcnt(" #n ")" ::: "memory")
; #define PG8_BAR __builtin_amdgcn_s_barrier()
; #define PG8_SCHED __builtin_amdgcn_sched_barrier(0)
; template <class Epi, bool ALIGN_EPI>
; __device__ __forceinline__ void gemm_phase(LAS unsigned char* lds, const Gemm g, const StaticOrder& S, const Epi& E) {
;     ...
;             PG8_WAIT_V(8); PG8_WAIT_L(0); PG8_BAR; PG8_MMA(0, 0, At, B0); PG8_MMA(0, 1, At, B1); PG8_BAR; PG8_SCHED;
;             PG8_LDA(At, 1, 1); PG8_STAGE(PG8_SB(1, 0), b3, voffB); PG8_STAGE(PG8_SB(1, 1), b3 + hB, voffB); PG8_STAGE(PG8_SA(1, 0), a3, voffA);
;             PG8_WAIT_V(8); PG8_WAIT_L(0); PG8_BAR; PG8_MMA(1, 0, At, B0); PG8_MMA(1, 1, At, B1); PG8_BAR; PG8_SCHED;
;         }
	v_mfma_f32_16x16x32_bf16 v[68:71], v[168:171], v[210:213], v[68:71]
	v_mfma_f32_16x16x32_bf16 v[68:71], v[172:175], v[214:217], v[68:71]
	v_mfma_f32_16x16x32_bf16 v[64:67], v[176:179], v[210:213], v[64:67]
	v_mfma_f32_16x16x32_bf16 v[64:67], v[180:183], v[214:217], v[64:67]
	s_setprio 0
	s_add_i32 s34, s54, s2
	v_lshl_add_u64 v[144:145], v[144:145], 0, s[16:17]
	s_mov_b32 m0, s34
	ds_read_b128 v[184:187], v151 offset:49152
	ds_read_b128 v[188:191], v151 offset:50176
	ds_read_b128 v[194:197], v151 offset:51200
	ds_read_b128 v[198:201], v151 offset:52224
	ds_read_b128 v[202:205], v151 offset:53248
	ds_read_b128 v[206:209], v151 offset:54272
	ds_read_b128 v[210:213], v151 offset:55296
	ds_read_b128 v[214:217], v151 offset:56320
	global_load_lds_dwordx4 v[144:145], off
	s_add_i32 m0, s34, 0x2000
	s_add_u32 s30, s30, 0x30080
	v_lshl_add_u64 v[144:145], v[218:219], 0, s[16:17]
	s_addc_u32 s31, s31, 0
	s_add_i32 s34, s55, s2
	global_load_lds_dwordx4 v[144:145], off
	v_lshl_add_u64 v[144:145], s[30:31], 0, v[132:133]
	s_mov_b32 m0, s34
	s_nop 0
	global_load_lds_dwordx4 v[144:145], off
	v_lshl_add_u64 v[144:145], s[30:31], 0, v[128:129]
	s_add_i32 m0, s34, 0x2000
	s_nop 0
	global_load_lds_dwordx4 v[144:145], off
	v_lshl_add_u64 v[144:145], v[220:221], 0, s[16:17]
	s_mov_b32 m0, s42
	s_nop 0
	global_load_lds_dwordx4 v[144:145], off
	v_lshl_add_u64 v[144:145], v[222:223], 0, s[16:17]
	s_mov_b32 m0, s43
	s_nop 0
	global_load_lds_dwordx4 v[144:145], off
	s_waitcnt vmcnt(8)
	s_waitcnt lgkmcnt(0)
	s_barrier
	s_setprio 1
	s_waitcnt lgkmcnt(0)
	v_mfma_f32_16x16x32_bf16 v[60:63], v[152:155], v[184:187], v[60:63]
	v_mfma_f32_16x16x32_bf16 v[60:63], v[156:159], v[188:191], v[60:63]
	v_mfma_f32_16x16x32_bf16 v[56:59], v[160:163], v[184:187], v[56:59]
	v_mfma_f32_16x16x32_bf16 v[56:59], v[164:167], v[188:191], v[56:59]
	v_mfma_f32_16x16x32_bf16 v[52:55], v[152:155], v[194:197], v[52:55]
	v_mfma_f32_16x16x32_bf16 v[52:55], v[156:159], v[198:201], v[52:55]
	v_mfma_f32_16x16x32_bf16 v[44:47], v[160:163], v[194:197], v[44:47]
	v_mfma_f32_16x16x32_bf16 v[44:47], v[164:167], v[198:201], v[44:47]
	v_mfma_f32_16x16x32_bf16 v[36:39], v[152:155], v[202:205], v[36:39]
	v_mfma_f32_16x16x32_bf16 v[36:39], v[156:159], v[206:209], v[36:39]
	v_mfma_f32_16x16x32_bf16 v[28:31], v[160:163], v[202:205], v[28:31]
	v_mfma_f32_16x16x32_bf16 v[28:31], v[164:167], v[206:209], v[28:31]
	v_mfma_f32_16x16x32_bf16 v[20:23], v[152:155], v[210:213], v[20:23]
	v_mfma_f32_16x16x32_bf16 v[20:23], v[156:159], v[214:217], v[20:23]
	v_mfma_f32_16x16x32_bf16 v[12:15], v[160:163], v[210:213], v[12:15]
	v_mfma_f32_16x16x32_bf16 v[12:15], v[164:167], v[214:217], v[12:15]
	s_setprio 0
	s_setprio 1
	v_mfma_f32_16x16x32_bf16 v[48:51], v[168:171], v[184:187], v[48:51]
	v_mfma_f32_16x16x32_bf16 v[48:51], v[172:175], v[188:191], v[48:51]
	v_mfma_f32_16x16x32_bf16 v[40:43], v[176:179], v[184:187], v[40:43]
	v_mfma_f32_16x16x32_bf16 v[40:43], v[180:183], v[188:191], v[40:43]
	v_mfma_f32_16x16x32_bf16 v[32:35], v[168:171], v[194:197], v[32:35]
	v_mfma_f32_16x16x32_bf16 v[32:35], v[172:175], v[198:201], v[32:35]
	v_mfma_f32_16x16x32_bf16 v[24:27], v[176:179], v[194:197], v[24:27]
	v_mfma_f32_16x16x32_bf16 v[24:27], v[180:183], v[198:201], v[24:27]
	v_mfma_f32_16x16x32_bf16 v[16:19], v[168:171], v[202:205], v[16:19]
	v_mfma_f32_16x16x32_bf16 v[16:19], v[172:175], v[206:209], v[16:19]
	v_mfma_f32_16x16x32_bf16 v[8:11], v[176:179], v[202:205], v[8:11]
	v_mfma_f32_16x16x32_bf16 v[8:11], v[180:183], v[206:209], v[8:11]
	s_barrier
	v_mfma_f32_16x16x32_bf16 v[4:7], v[168:171], v[210:213], v[4:7]
	v_mfma_f32_16x16x32_bf16 v[4:7], v[172:175], v[214:217], v[4:7]
	v_mfma_f32_16x16x32_bf16 v[0:3], v[176:179], v[210:213], v[0:3]
	v_mfma_f32_16x16x32_bf16 v[0:3], v[180:183], v[214:217], v[0:3]
	s_setprio 0
	s_add_i32 s53, s53, 2
	s_add_u32 s6, s6, 0x100
	s_addc_u32 s7, s7, 0
	s_add_u32 s51, s51, 0x100
	s_addc_u32 s52, s52, 0
	s_cmp_gt_u32 s53, 9
	s_cbranch_scc0 .LBB0_403
	s_and_b64 vcc, exec, s[18:19]
	s_cbranch_vccz .LBB0_406
	s_barrier

; #define PG8_STAGE(bufoff, gbase, voff) do { _Pragma("unroll") for (int _i = 0; _i < 2; ++_i) \
;         __builtin_amdgcn_global_load_lds((const unsigned*)((const char*)(gbase) + (voff)[_i]), (LAS unsigned*)(lds + (bufoff) + ldsw + _i * 8192), 16, 0, 0); } while (0)
; #define PG8_LDA(dst, b, h) do { _Pragma("unroll") for (int m = 0; m < 4; ++m) _Pragma("unroll") for (int k = 0; k < 2; ++k) dst[m][k] = *(const LAS bf16x8*)(lds + PG8_SA(b, h) + aoff + m * 2048 + k * 1024); } while (0)
; #define PG8_LDB(dst, b, h) do { _Pragma("unroll") for (int n = 0; n < 2; ++n) _Pragma("unroll") for (int k = 0; k < 2; ++k) dst[n][k] = *(const LAS bf16x8*)(lds + PG8_SB(b, h) + boff + n * 2048 + k * 1024); } while (0)
; #define PG8_MMA(ai, bj, At, Bt) do { __builtin_amdgcn_s_setprio(1); _Pragma("unroll") for (int m = 0; m < 4; ++m) _Pragma("unroll") for (int n = 0; n < 2; ++n) _Pragma("unroll") for (int k = 0; k < 2; ++k) \
;         acc[ai][bj][m][n] = __builtin_amdgcn_mfma_f32_16x16x32_bf16(Bt[n][k], At[m][k], acc[ai][bj][m][n], 0, 0, 0); __builtin_amdgcn_s_setprio(0); } while (0)
; #define PG8_WAIT_V(n) asm volatile("s_waitcnt vmcnt(" #n ")" ::: "memory")
; #define PG8_WAIT_L(n) asm volatile("s_waitcnt lgkmcnt(" #n ")" ::: "memory")
; #define PG8_BAR __builtin_amdgcn_s_barrier()
; #define PG8_SCHED __builtin_amdgcn_sched_barrier(0)
; template <class Epi, bool ALIGN_EPI>
; __device__ __forceinline__ void gemm_phase(LAS unsigned char* lds, const Gemm g, const StaticOrder& S, const Epi& E) {
;     ...
;         for (int t = 0; t < nt; t += 2) {
;             const bool last = (t == nt - 2);
;             const char* a1 = cA + (size_t)(t + 1) * kstep;
;             const char* a2 = last ? nA : cA + (size_t)(t + 2) * kstep; const char* b2 = last ? nB : cB + (size_t)(t + 2) * kstep;
;             const char* a3 = a2 + kstep; const char* b3 = b2 + kstep;
;             PG8_LDB(B0, 0, 0); PG8_LDB(B1, 0, 1); PG8_SCHED; PG8_LDA(At, 0, 0); PG8_STAGE(PG8_SA(1, 1), a1 + hA, voffA);
;             PG8_WAIT_V(8); PG8_WAIT_L(0); PG8_BAR; PG8_MMA(0, 0, At, B0); PG8_MMA(0, 1, At, B1); PG8_BAR; PG8_SCHED;
;             PG8_LDA(At, 0, 1); PG8_STAGE(PG8_SB(0, 0), b2, voffB); PG8_STAGE(PG8_SB(0, 1), b2 + hB, voffB); PG8_STAGE(PG8_SA(0, 0), a2, voffA);
;             PG8_WAIT_V(8); PG8_WAIT_L(0); PG8_BAR; PG8_MMA(1, 0, At, B0); PG8_MMA(1, 1, At, B1); PG8_BAR; PG8_SCHED;
.LBB0_419:
	ds_read_b128 v[148:151], v145
	ds_read_b128 v[152:155], v145 offset:1024
	ds_read_b128 v[156:159], v145 offset:2048
	ds_read_b128 v[160:163], v145 offset:3072
	ds_read_b128 v[164:167], v146
	ds_read_b128 v[168:171], v146 offset:1024
	ds_read_b128 v[172:175], v146 offset:2048
	ds_read_b128 v[176:179], v146 offset:3072
	s_add_u32 s30, s28, 0xfff80080
	s_addc_u32 s31, s29, -1
	s_cmp_eq_u32 s53, 28
	s_cselect_b32 s35, s19, s31
	s_cselect_b32 s34, s49, s30
	s_cselect_b32 s31, s17, s52
	s_cselect_b32 s30, s50, s51
	v_lshl_add_u64 v[140:141], s[28:29], 0, v[136:137]
	s_add_i32 m0, s27, 0xc000
	ds_read_b128 v[180:183], v147
	ds_read_b128 v[184:187], v147 offset:1024
	ds_read_b128 v[188:191], v147 offset:2048
	ds_read_b128 v[194:197], v147 offset:3072
	ds_read_b128 v[198:201], v147 offset:4096
	ds_read_b128 v[202:205], v147 offset:5120
	ds_read_b128 v[206:209], v147 offset:6144
	ds_read_b128 v[210:213], v147 offset:7168
	global_load_lds_dwordx4 v[140:141], off
	v_lshl_add_u64 v[140:141], s[28:29], 0, v[138:139]
	s_add_i32 m0, s27, 0xe000
	s_nop 0
	global_load_lds_dwordx4 v[140:141], off
	s_waitcnt vmcnt(8)
	s_waitcnt lgkmcnt(0)
	s_barrier
	s_setprio 1
	s_waitcnt lgkmcnt(0)
	v_mfma_f32_16x16x32_bf16 v[124:127], v[148:151], v[180:183], v[124:127]
	v_mfma_f32_16x16x32_bf16 v[124:127], v[152:155], v[184:187], v[124:127]
	v_mfma_f32_16x16x32_bf16 v[120:123], v[156:159], v[180:183], v[120:123]
	v_mfma_f32_16x16x32_bf16 v[120:123], v[160:163], v[184:187], v[120:123]
	v_mfma_f32_16x16x32_bf16 v[116:119], v[148:151], v[188:191], v[116:119]
	v_mfma_f32_16x16x32_bf16 v[116:119], v[152:155], v[194:197], v[116:119]
	v_mfma_f32_16x16x32_bf16 v[108:111], v[156:159], v[188:191], v[108:111]
	v_mfma_f32_16x16x32_bf16 v[108:111], v[160:163], v[194:197], v[108:111]
	v_mfma_f32_16x16x32_bf16 v[100:103], v[148:151], v[198:201], v[100:103]
	v_mfma_f32_16x16x32_bf16 v[100:103], v[152:155], v[202:205], v[100:103]
	v_mfma_f32_16x16x32_bf16 v[92:95], v[156:159], v[198:201], v[92:95]
	v_mfma_f32_16x16x32_bf16 v[92:95], v[160:163], v[202:205], v[92:95]
	v_mfma_f32_16x16x32_bf16 v[84:87], v[148:151], v[206:209], v[84:87]
	v_mfma_f32_16x16x32_bf16 v[84:87], v[152:155], v[210:213], v[84:87]
	v_mfma_f32_16x16x32_bf16 v[76:79], v[156:159], v[206:209], v[76:79]
	v_mfma_f32_16x16x32_bf16 v[76:79], v[160:163], v[210:213], v[76:79]
	s_setprio 0
	s_setprio 1
	v_mfma_f32_16x16x32_bf16 v[112:115], v[164:167], v[180:183], v[112:115]
	v_mfma_f32_16x16x32_bf16 v[112:115], v[168:171], v[184:187], v[112:115]
	v_mfma_f32_16x16x32_bf16 v[104:107], v[172:175], v[180:183], v[104:107]
	v_mfma_f32_16x16x32_bf16 v[104:107], v[176:179], v[184:187], v[104:107]
	v_mfma_f32_16x16x32_bf16 v[96:99], v[164:167], v[188:191], v[96:99]
	v_mfma_f32_16x16x32_bf16 v[96:99], v[168:171], v[194:197], v[96:99]
	v_mfma_f32_16x16x32_bf16 v[88:91], v[172:175], v[188:191], v[88:91]
	v_mfma_f32_16x16x32_bf16 v[88:91], v[176:179], v[194:197], v[88:91]
	v_mfma_f32_16x16x32_bf16 v[80:83], v[164:167], v[198:201], v[80:83]
	v_mfma_f32_16x16x32_bf16 v[80:83], v[168:171], v[202:205], v[80:83]
	v_mfma_f32_16x16x32_bf16 v[72:75], v[172:175], v[198:201], v[72:75]
	v_mfma_f32_16x16x32_bf16 v[72:75], v[176:179], v[202:205], v[72:75]
	s_barrier
	v_mfma_f32_16x16x32_bf16 v[68:71], v[164:167], v[206:209], v[68:71]
	v_mfma_f32_16x16x32_bf16 v[68:71], v[168:171], v[210:213], v[68:71]
	v_mfma_f32_16x16x32_bf16 v[64:67], v[172:175], v[206:209], v[64:67]
	v_mfma_f32_16x16x32_bf16 v[64:67], v[176:179], v[210:213], v[64:67]
	s_setprio 0
	s_add_i32 s54, s45, s1
	v_lshl_add_u64 v[140:141], s[30:31], 0, v[132:133]
	s_mov_b32 m0, s54
	ds_read_b128 v[180:183], v147 offset:16384
	ds_read_b128 v[184:187], v147 offset:17408
	ds_read_b128 v[188:191], v147 offset:18432
	ds_read_b128 v[194:197], v147 offset:19456
	ds_read_b128 v[198:201], v147 offset:20480
	ds_read_b128 v[202:205], v147 offset:21504
	ds_read_b128 v[206:209], v147 offset:22528
	ds_read_b128 v[210:213], v147 offset:23552
	global_load_lds_dwordx4 v[140:141], off
	s_add_i32 m0, s54, 0x2000
	s_add_u32 s54, s30, 0x80000
	v_lshl_add_u64 v[214:215], s[30:31], 0, v[128:129]
	s_addc_u32 s55, s31, 0
	s_add_i32 s56, s46, s1
	global_load_lds_dwordx4 v[214:215], off
	v_lshl_add_u64 v[216:217], s[54:55], 0, v[132:133]
	s_mov_b32 m0, s56
	v_lshl_add_u64 v[218:219], s[34:35], 0, v[130:131]
	global_load_lds_dwordx4 v[216:217], off
	v_lshl_add_u64 v[216:217], s[54:55], 0, v[128:129]
	s_add_i32 m0, s56, 0x2000
	s_nop 0
	global_load_lds_dwordx4 v[216:217], off
	v_lshl_add_u64 v[216:217], s[34:35], 0, v[134:135]
	s_mov_b32 m0, s27
	s_nop 0
	global_load_lds_dwordx4 v[216:217], off
	s_mov_b32 m0, s39
	s_nop 0
	global_load_lds_dwordx4 v[218:219], off
	s_waitcnt vmcnt(8)
	s_waitcnt lgkmcnt(0)
	s_barrier
; #define PG8_STAGE(bufoff, gbase, voff) do { _Pragma("unroll") for (int _i = 0; _i < 2; ++_i) \
;         __builtin_amdgcn_global_load_lds((const unsigned*)((const char*)(gbase) + (voff)[_i]), (LAS unsigned*)(lds + (bufoff) + ldsw + _i * 8192), 16, 0, 0); } while (0)
; #define PG8_LDA(dst, b, h) do { _Pragma("unroll") for (int m = 0; m < 4; ++m) _Pragma("unroll") for (int k = 0; k < 2; ++k) dst[m][k] = *(const LAS bf16x8*)(lds + PG8_SA(b, h) + aoff + m * 2048 + k * 1024); } while (0)
; #define PG8_LDB(dst, b, h) do { _Pragma("unroll") for (int n = 0; n < 2; ++n) _Pragma("unroll") for (int k = 0; k < 2; ++k) dst[n][k] = *(const LAS bf16x8*)(lds + PG8_SB(b, h) + boff + n * 2048 + k * 1024); } while (0)
; #define PG8_MMA(ai, bj, At, Bt) do { __builtin_amdgcn_s_setprio(1); _Pragma("unroll") for (int m = 0; m < 4; ++m) _Pragma("unroll") for (int n = 0; n < 2; ++n) _Pragma("unroll") for (int k = 0; k < 2; ++k) \
;         acc[ai][bj][m][n] = __builtin_amdgcn_mfma_f32_16x16x32_bf16(Bt[n][k], At[m][k], acc[ai][bj][m][n], 0, 0, 0); __builtin_amdgcn_s_setprio(0); } while (0)
; #define PG8_WAIT_V(n) asm volatile("s_waitcnt vmcnt(" #n ")" ::: "memory")
; #define PG8_WAIT_L(n) asm volatile("s_waitcnt lgkmcnt(" #n ")" ::: "memory")
; #define PG8_BAR __builtin_amdgcn_s_barrier()
; #define PG8_SCHED __builtin_amdgcn_sched_barrier(0)
; template <class Epi, bool ALIGN_EPI>
; __device__ __forceinline__ void gemm_phase(LAS unsigned char* lds, const Gemm g, const StaticOrder& S, const Epi& E) {
;     ...
;             PG8_WAIT_V(8); PG8_WAIT_L(0); PG8_BAR; PG8_MMA(1, 0, At, B0); PG8_MMA(1, 1, At, B1); PG8_BAR; PG8_SCHED;
;             PG8_LDB(B0, 1, 0); PG8_LDB(B1, 1, 1); PG8_SCHED; PG8_LDA(At, 1, 0); PG8_STAGE(PG8_SA(0, 1), a2 + hA, voffA);
;             PG8_WAIT_V(8); PG8_WAIT_L(0); PG8_BAR; PG8_MMA(0, 0, At, B0); PG8_MMA(0, 1, At, B1); PG8_BAR; PG8_SCHED;
;             PG8_LDA(At, 1, 1); PG8_STAGE(PG8_SB(1, 0), b3, voffB); PG8_STAGE(PG8_SB(1, 1), b3 + hB, voffB); PG8_STAGE(PG8_SA(1, 0), a3, voffA);
	s_setprio 1
	s_waitcnt lgkmcnt(0)
	v_mfma_f32_16x16x32_bf16 v[60:63], v[148:151], v[180:183], v[60:63]
	v_mfma_f32_16x16x32_bf16 v[60:63], v[152:155], v[184:187], v[60:63]
	v_mfma_f32_16x16x32_bf16 v[56:59], v[156:159], v[180:183], v[56:59]
	v_mfma_f32_16x16x32_bf16 v[56:59], v[160:163], v[184:187], v[56:59]
	v_mfma_f32_16x16x32_bf16 v[52:55], v[148:151], v[188:191], v[52:55]
	v_mfma_f32_16x16x32_bf16 v[52:55], v[152:155], v[194:197], v[52:55]
	v_mfma_f32_16x16x32_bf16 v[44:47], v[156:159], v[188:191], v[44:47]
	v_mfma_f32_16x16x32_bf16 v[44:47], v[160:163], v[194:197], v[44:47]
	v_mfma_f32_16x16x32_bf16 v[36:39], v[148:151], v[198:201], v[36:39]
	v_mfma_f32_16x16x32_bf16 v[36:39], v[152:155], v[202:205], v[36:39]
	v_mfma_f32_16x16x32_bf16 v[28:31], v[156:159], v[198:201], v[28:31]
	v_mfma_f32_16x16x32_bf16 v[28:31], v[160:163], v[202:205], v[28:31]
	v_mfma_f32_16x16x32_bf16 v[20:23], v[148:151], v[206:209], v[20:23]
	v_mfma_f32_16x16x32_bf16 v[20:23], v[152:155], v[210:213], v[20:23]
	v_mfma_f32_16x16x32_bf16 v[12:15], v[156:159], v[206:209], v[12:15]
	v_mfma_f32_16x16x32_bf16 v[12:15], v[160:163], v[210:213], v[12:15]
	s_setprio 0
	s_setprio 1
	v_mfma_f32_16x16x32_bf16 v[48:51], v[164:167], v[180:183], v[48:51]
	v_mfma_f32_16x16x32_bf16 v[48:51], v[168:171], v[184:187], v[48:51]
	v_mfma_f32_16x16x32_bf16 v[40:43], v[172:175], v[180:183], v[40:43]
	v_mfma_f32_16x16x32_bf16 v[40:43], v[176:179], v[184:187], v[40:43]
	v_mfma_f32_16x16x32_bf16 v[32:35], v[164:167], v[188:191], v[32:35]
	v_mfma_f32_16x16x32_bf16 v[32:35], v[168:171], v[194:197], v[32:35]
	v_mfma_f32_16x16x32_bf16 v[24:27], v[172:175], v[188:191], v[24:27]
	v_mfma_f32_16x16x32_bf16 v[24:27], v[176:179], v[194:197], v[24:27]
	v_mfma_f32_16x16x32_bf16 v[16:19], v[164:167], v[198:201], v[16:19]
	v_mfma_f32_16x16x32_bf16 v[16:19], v[168:171], v[202:205], v[16:19]
	v_mfma_f32_16x16x32_bf16 v[8:11], v[172:175], v[198:201], v[8:11]
	v_mfma_f32_16x16x32_bf16 v[8:11], v[176:179], v[202:205], v[8:11]
	s_barrier
	v_mfma_f32_16x16x32_bf16 v[4:7], v[164:167], v[206:209], v[4:7]
	v_mfma_f32_16x16x32_bf16 v[4:7], v[168:171], v[210:213], v[4:7]
	v_mfma_f32_16x16x32_bf16 v[0:3], v[172:175], v[206:209], v[0:3]
	v_mfma_f32_16x16x32_bf16 v[0:3], v[176:179], v[210:213], v[0:3]
	s_setprio 0
	s_add_i32 s54, 0, 0x18000
	s_add_i32 s55, 0, 0x1c000
	v_add_u32_e32 v160, s54, v143
	v_add_u32_e32 v176, s55, v143
	ds_read_b128 v[148:151], v160
	ds_read_b128 v[152:155], v160 offset:1024
	ds_read_b128 v[156:159], v160 offset:2048
	ds_read_b128 v[160:163], v160 offset:3072
	ds_read_b128 v[164:167], v176
	ds_read_b128 v[168:171], v176 offset:1024
	ds_read_b128 v[172:175], v176 offset:2048
	ds_read_b128 v[176:179], v176 offset:3072
	s_add_u32 s34, s34, 0x80000
	s_addc_u32 s35, s35, 0
	s_mov_b32 m0, s40
	v_lshl_add_u64 v[220:221], s[34:35], 0, v[134:135]
	ds_read_b128 v[180:183], v147 offset:32768
	ds_read_b128 v[184:187], v147 offset:33792
	ds_read_b128 v[188:191], v147 offset:34816
	ds_read_b128 v[194:197], v147 offset:35840
	ds_read_b128 v[198:201], v147 offset:36864
	ds_read_b128 v[202:205], v147 offset:37888
	ds_read_b128 v[206:209], v147 offset:38912
	ds_read_b128 v[210:213], v147 offset:39936
	global_load_lds_dwordx4 v[220:221], off
	v_lshl_add_u64 v[220:221], s[34:35], 0, v[130:131]
	s_mov_b32 m0, s41
	s_nop 0
	global_load_lds_dwordx4 v[220:221], off
	s_waitcnt vmcnt(8)
	s_waitcnt lgkmcnt(0)
	s_barrier
	s_setprio 1
	s_waitcnt lgkmcnt(0)
	v_mfma_f32_16x16x32_bf16 v[124:127], v[148:151], v[180:183], v[124:127]
	v_mfma_f32_16x16x32_bf16 v[124:127], v[152:155], v[184:187], v[124:127]
	v_mfma_f32_16x16x32_bf16 v[120:123], v[156:159], v[180:183], v[120:123]
	v_mfma_f32_16x16x32_bf16 v[120:123], v[160:163], v[184:187], v[120:123]
	v_mfma_f32_16x16x32_bf16 v[116:119], v[148:151], v[188:191], v[116:119]
	v_mfma_f32_16x16x32_bf16 v[116:119], v[152:155], v[194:197], v[116:119]
	v_mfma_f32_16x16x32_bf16 v[108:111], v[156:159], v[188:191], v[108:111]
	v_mfma_f32_16x16x32_bf16 v[108:111], v[160:163], v[194:197], v[108:111]
	v_mfma_f32_16x16x32_bf16 v[100:103], v[148:151], v[198:201], v[100:103]
	v_mfma_f32_16x16x32_bf16 v[100:103], v[152:155], v[202:205], v[100:103]
	v_mfma_f32_16x16x32_bf16 v[92:95], v[156:159], v[198:201], v[92:95]
	v_mfma_f32_16x16x32_bf16 v[92:95], v[160:163], v[202:205], v[92:95]
	v_mfma_f32_16x16x32_bf16 v[84:87], v[148:151], v[206:209], v[84:87]
	v_mfma_f32_16x16x32_bf16 v[84:87], v[152:155], v[210:213], v[84:87]
	v_mfma_f32_16x16x32_bf16 v[76:79], v[156:159], v[206:209], v[76:79]
	v_mfma_f32_16x16x32_bf16 v[76:79], v[160:163], v[210:213], v[76:79]
	s_setprio 0
	s_setprio 1
	v_mfma_f32_16x16x32_bf16 v[112:115], v[164:167], v[180:183], v[112:115]
	v_mfma_f32_16x16x32_bf16 v[112:115], v[168:171], v[184:187], v[112:115]
	v_mfma_f32_16x16x32_bf16 v[104:107], v[172:175], v[180:183], v[104:107]
	v_mfma_f32_16x16x32_bf16 v[104:107], v[176:179], v[184:187], v[104:107]
	v_mfma_f32_16x16x32_bf16 v[96:99], v[164:167], v[188:191], v[96:99]
	v_mfma_f32_16x16x32_bf16 v[96:99], v[168:171], v[194:197], v[96:99]
	v_mfma_f32_16x16x32_bf16 v[88:91], v[172:175], v[188:191], v[88:91]
	v_mfma_f32_16x16x32_bf16 v[88:91], v[176:179], v[194:197], v[88:91]
	v_mfma_f32_16x16x32_bf16 v[80:83], v[164:167], v[198:201], v[80:83]
	v_mfma_f32_16x16x32_bf16 v[80:83], v[168:171], v[202:205], v[80:83]
	v_mfma_f32_16x16x32_bf16 v[72:75], v[172:175], v[198:201], v[72:75]
	v_mfma_f32_16x16x32_bf16 v[72:75], v[176:179], v[202:205], v[72:75]
	s_barrier
; #define PG8_STAGE(bufoff, gbase, voff) do { _Pragma("unroll") for (int _i = 0; _i < 2; ++_i) \
;         __builtin_amdgcn_global_load_lds((const unsigned*)((const char*)(gbase) + (voff)[_i]), (LAS unsigned*)(lds + (bufoff) + ldsw + _i * 8192), 16, 0, 0); } while (0)
; #define PG8_LDA(dst, b, h) do { _Pragma("unroll") for (int m = 0; m < 4; ++m) _Pragma("unroll") for (int k = 0; k < 2; ++k) dst[m][k] = *(const LAS bf16x8*)(lds + PG8_SA(b, h) + aoff + m * 2048 + k * 1024); } while (0)
; #define PG8_MMA(ai, bj, At, Bt) do { __builtin_amdgcn_s_setprio(1); _Pragma("unroll") for (int m = 0; m < 4; ++m) _Pragma("unroll") for (int n = 0; n < 2; ++n) _Pragma("unroll") for (int k = 0; k < 2; ++k) \
;         acc[ai][bj][m][n] = __builtin_amdgcn_mfma_f32_16x16x32_bf16(Bt[n][k], At[m][k], acc[ai][bj][m][n], 0, 0, 0); __builtin_amdgcn_s_setprio(0); } while (0)
; #define PG8_WAIT_V(n) asm volatile("s_waitcnt vmcnt(" #n ")" ::: "memory")
; #define PG8_WAIT_L(n) asm volatile("s_waitcnt lgkmcnt(" #n ")" ::: "memory")
; #define PG8_BAR __builtin_amdgcn_s_barrier()
; #define PG8_SCHED __builtin_amdgcn_sched_barrier(0)
; template <class Epi, bool ALIGN_EPI>
; __device__ __forceinline__ void gemm_phase(LAS unsigned char* lds, const Gemm g, const StaticOrder& S, const Epi& E) {
;     ...
;             PG8_WAIT_V(8); PG8_WAIT_L(0); PG8_BAR; PG8_MMA(0, 0, At, B0); PG8_MMA(0, 1, At, B1); PG8_BAR; PG8_SCHED;
;             PG8_LDA(At, 1, 1); PG8_STAGE(PG8_SB(1, 0), b3, voffB); PG8_STAGE(PG8_SB(1, 1), b3 + hB, voffB); PG8_STAGE(PG8_SA(1, 0), a3, voffA);
;             PG8_WAIT_V(8); PG8_WAIT_L(0); PG8_BAR; PG8_MMA(1, 0, At, B0); PG8_MMA(1, 1, At, B1); PG8_BAR; PG8_SCHED;
;         }
;         if constexpr (ALIGN_EPI) { if (wr == 0) PG8_BAR; }
	v_mfma_f32_16x16x32_bf16 v[68:71], v[164:167], v[206:209], v[68:71]
	v_mfma_f32_16x16x32_bf16 v[68:71], v[168:171], v[210:213], v[68:71]
	v_mfma_f32_16x16x32_bf16 v[64:67], v[172:175], v[206:209], v[64:67]
	v_mfma_f32_16x16x32_bf16 v[64:67], v[176:179], v[210:213], v[64:67]
	s_setprio 0
	s_add_i32 s34, s54, s1
	v_lshl_add_u64 v[140:141], v[140:141], 0, s[10:11]
	s_mov_b32 m0, s34
	ds_read_b128 v[180:183], v147 offset:49152
	ds_read_b128 v[184:187], v147 offset:50176
	ds_read_b128 v[188:191], v147 offset:51200
	ds_read_b128 v[194:197], v147 offset:52224
	ds_read_b128 v[198:201], v147 offset:53248
	ds_read_b128 v[202:205], v147 offset:54272
	ds_read_b128 v[206:209], v147 offset:55296
	ds_read_b128 v[210:213], v147 offset:56320
	global_load_lds_dwordx4 v[140:141], off
	s_add_i32 m0, s34, 0x2000
	s_add_u32 s30, s30, 0x80080
	v_lshl_add_u64 v[140:141], v[214:215], 0, s[10:11]
	s_addc_u32 s31, s31, 0
	s_add_i32 s34, s55, s1
	global_load_lds_dwordx4 v[140:141], off
	v_lshl_add_u64 v[140:141], s[30:31], 0, v[132:133]
	s_mov_b32 m0, s34
	s_nop 0
	global_load_lds_dwordx4 v[140:141], off
	v_lshl_add_u64 v[140:141], s[30:31], 0, v[128:129]
	s_add_i32 m0, s34, 0x2000
	s_nop 0
	global_load_lds_dwordx4 v[140:141], off
	v_lshl_add_u64 v[140:141], v[216:217], 0, s[10:11]
	s_mov_b32 m0, s42
	s_nop 0
	global_load_lds_dwordx4 v[140:141], off
	v_lshl_add_u64 v[140:141], v[218:219], 0, s[10:11]
	s_mov_b32 m0, s43
	s_nop 0
	global_load_lds_dwordx4 v[140:141], off
	s_waitcnt vmcnt(8)
	s_waitcnt lgkmcnt(0)
	s_barrier
	s_setprio 1
	s_waitcnt lgkmcnt(0)
	v_mfma_f32_16x16x32_bf16 v[60:63], v[148:151], v[180:183], v[60:63]
	v_mfma_f32_16x16x32_bf16 v[60:63], v[152:155], v[184:187], v[60:63]
	v_mfma_f32_16x16x32_bf16 v[56:59], v[156:159], v[180:183], v[56:59]
	v_mfma_f32_16x16x32_bf16 v[56:59], v[160:163], v[184:187], v[56:59]
	v_mfma_f32_16x16x32_bf16 v[52:55], v[148:151], v[188:191], v[52:55]
	v_mfma_f32_16x16x32_bf16 v[52:55], v[152:155], v[194:197], v[52:55]
	v_mfma_f32_16x16x32_bf16 v[44:47], v[156:159], v[188:191], v[44:47]
	v_mfma_f32_16x16x32_bf16 v[44:47], v[160:163], v[194:197], v[44:47]
	v_mfma_f32_16x16x32_bf16 v[36:39], v[148:151], v[198:201], v[36:39]
	v_mfma_f32_16x16x32_bf16 v[36:39], v[152:155], v[202:205], v[36:39]
	v_mfma_f32_16x16x32_bf16 v[28:31], v[156:159], v[198:201], v[28:31]
	v_mfma_f32_16x16x32_bf16 v[28:31], v[160:163], v[202:205], v[28:31]
	v_mfma_f32_16x16x32_bf16 v[20:23], v[148:151], v[206:209], v[20:23]
	v_mfma_f32_16x16x32_bf16 v[20:23], v[152:155], v[210:213], v[20:23]
	v_mfma_f32_16x16x32_bf16 v[12:15], v[156:159], v[206:209], v[12:15]
	v_mfma_f32_16x16x32_bf16 v[12:15], v[160:163], v[210:213], v[12:15]
	s_setprio 0
	s_setprio 1
	v_mfma_f32_16x16x32_bf16 v[48:51], v[164:167], v[180:183], v[48:51]
	v_mfma_f32_16x16x32_bf16 v[48:51], v[168:171], v[184:187], v[48:51]
	v_mfma_f32_16x16x32_bf16 v[40:43], v[172:175], v[180:183], v[40:43]
	v_mfma_f32_16x16x32_bf16 v[40:43], v[176:179], v[184:187], v[40:43]
	v_mfma_f32_16x16x32_bf16 v[32:35], v[164:167], v[188:191], v[32:35]
	v_mfma_f32_16x16x32_bf16 v[32:35], v[168:171], v[194:197], v[32:35]
	v_mfma_f32_16x16x32_bf16 v[24:27], v[172:175], v[188:191], v[24:27]
	v_mfma_f32_16x16x32_bf16 v[24:27], v[176:179], v[194:197], v[24:27]
	v_mfma_f32_16x16x32_bf16 v[16:19], v[164:167], v[198:201], v[16:19]
	v_mfma_f32_16x16x32_bf16 v[16:19], v[168:171], v[202:205], v[16:19]
	v_mfma_f32_16x16x32_bf16 v[8:11], v[172:175], v[198:201], v[8:11]
	v_mfma_f32_16x16x32_bf16 v[8:11], v[176:179], v[202:205], v[8:11]
	s_barrier
	v_mfma_f32_16x16x32_bf16 v[4:7], v[164:167], v[206:209], v[4:7]
	v_mfma_f32_16x16x32_bf16 v[4:7], v[168:171], v[210:213], v[4:7]
	v_mfma_f32_16x16x32_bf16 v[0:3], v[172:175], v[206:209], v[0:3]
	v_mfma_f32_16x16x32_bf16 v[0:3], v[176:179], v[210:213], v[0:3]
	s_setprio 0
	s_add_i32 s53, s53, 2
	s_add_u32 s28, s28, 0x100
	s_addc_u32 s29, s29, 0
	s_add_u32 s51, s51, 0x100
	s_addc_u32 s52, s52, 0
	s_cmp_gt_u32 s53, 29
	s_cbranch_scc0 .LBB0_419
	s_and_b64 vcc, exec, s[14:15]
	s_cbranch_vccz .LBB0_422
	s_barrier

; #define PG8_STAGE(bufoff, gbase, voff) do { _Pragma("unroll") for (int _i = 0; _i < 2; ++_i) \
;         __builtin_amdgcn_global_load_lds((const unsigned*)((const char*)(gbase) + (voff)[_i]), (LAS unsigned*)(lds + (bufoff) + ldsw + _i * 8192), 16, 0, 0); } while (0)
; #define PG8_LDA(dst, b, h) do { _Pragma("unroll") for (int m = 0; m < 4; ++m) _Pragma("unroll") for (int k = 0; k < 2; ++k) dst[m][k] = *(const LAS bf16x8*)(lds + PG8_SA(b, h) + aoff + m * 2048 + k * 1024); } while (0)
; #define PG8_LDB(dst, b, h) do { _Pragma("unroll") for (int n = 0; n < 2; ++n) _Pragma("unroll") for (int k = 0; k < 2; ++k) dst[n][k] = *(const LAS bf16x8*)(lds + PG8_SB(b, h) + boff + n * 2048 + k * 1024); } while (0)
; #define PG8_MMA(ai, bj, At, Bt) do { __builtin_amdgcn_s_setprio(1); _Pragma("unroll") for (int m = 0; m < 4; ++m) _Pragma("unroll") for (int n = 0; n < 2; ++n) _Pragma("unroll") for (int k = 0; k < 2; ++k) \
;         acc[ai][bj][m][n] = __builtin_amdgcn_mfma_f32_16x16x32_bf16(Bt[n][k], At[m][k], acc[ai][bj][m][n], 0, 0, 0); __builtin_amdgcn_s_setprio(0); } while (0)
; #define PG8_WAIT_V(n) asm volatile("s_waitcnt vmcnt(" #n ")" ::: "memory")
; #define PG8_WAIT_L(n) asm volatile("s_waitcnt lgkmcnt(" #n ")" ::: "memory")
; #define PG8_BAR __builtin_amdgcn_s_barrier()
; #define PG8_SCHED __builtin_amdgcn_sched_barrier(0)
; template <class Epi, bool ALIGN_EPI>
; __device__ __forceinline__ void gemm_phase(LAS unsigned char* lds, const Gemm g, const StaticOrder& S, const Epi& E) {
;     ...
;         for (int t = 0; t < nt; t += 2) {
;             const bool last = (t == nt - 2);
;             const char* a1 = cA + (size_t)(t + 1) * kstep;
;             const char* a2 = last ? nA : cA + (size_t)(t + 2) * kstep; const char* b2 = last ? nB : cB + (size_t)(t + 2) * kstep;
;             const char* a3 = a2 + kstep; const char* b3 = b2 + kstep;
;             PG8_LDB(B0, 0, 0); PG8_LDB(B1, 0, 1); PG8_SCHED; PG8_LDA(At, 0, 0); PG8_STAGE(PG8_SA(1, 1), a1 + hA, voffA);
;             PG8_WAIT_V(8); PG8_WAIT_L(0); PG8_BAR; PG8_MMA(0, 0, At, B0); PG8_MMA(0, 1, At, B1); PG8_BAR; PG8_SCHED;
;             PG8_LDA(At, 0, 1); PG8_STAGE(PG8_SB(0, 0), b2, voffB); PG8_STAGE(PG8_SB(0, 1), b2 + hB, voffB); PG8_STAGE(PG8_SA(0, 0), a2, voffA);
;             PG8_WAIT_V(8); PG8_WAIT_L(0); PG8_BAR; PG8_MMA(1, 0, At, B0); PG8_MMA(1, 1, At, B1); PG8_BAR; PG8_SCHED;
.LBB0_775:
	ds_read_b128 v[128:131], v196
	ds_read_b128 v[132:135], v196 offset:1024
	ds_read_b128 v[136:139], v196 offset:2048
	ds_read_b128 v[140:143], v196 offset:3072
	ds_read_b128 v[144:147], v197
	ds_read_b128 v[148:151], v197 offset:1024
	ds_read_b128 v[152:155], v197 offset:2048
	ds_read_b128 v[156:159], v197 offset:3072
	s_add_u32 s37, s40, 0xfff80080
	s_addc_u32 s38, s41, -1
	s_cmp_eq_u32 s29, 28
	s_cselect_b32 s45, s0, s38
	s_cselect_b32 s44, s1, s37
	s_cselect_b32 s43, s2, s27
	s_cselect_b32 s42, s3, s9
	v_lshl_add_u64 v[216:217], s[40:41], 0, v[168:169]
	s_add_i32 m0, s50, 0xc000
	ds_read_b128 v[176:179], v198
	ds_read_b128 v[180:183], v198 offset:1024
	ds_read_b128 v[184:187], v198 offset:2048
	ds_read_b128 v[188:191], v198 offset:3072
	ds_read_b128 v[200:203], v198 offset:4096
	ds_read_b128 v[204:207], v198 offset:5120
	ds_read_b128 v[208:211], v198 offset:6144
	ds_read_b128 v[212:215], v198 offset:7168
	global_load_lds_dwordx4 v[216:217], off
	v_lshl_add_u64 v[216:217], s[40:41], 0, v[170:171]
	s_add_i32 m0, s50, 0xe000
	s_nop 0
	global_load_lds_dwordx4 v[216:217], off
	s_waitcnt vmcnt(8)
	s_waitcnt lgkmcnt(0)
	s_barrier
	s_setprio 1
	s_waitcnt lgkmcnt(0)
	v_mfma_f32_16x16x32_bf16 v[124:127], v[128:131], v[176:179], v[124:127]
	v_mfma_f32_16x16x32_bf16 v[124:127], v[132:135], v[180:183], v[124:127]
	v_mfma_f32_16x16x32_bf16 v[120:123], v[136:139], v[176:179], v[120:123]
	v_mfma_f32_16x16x32_bf16 v[120:123], v[140:143], v[180:183], v[120:123]
	v_mfma_f32_16x16x32_bf16 v[108:111], v[128:131], v[184:187], v[108:111]
	v_mfma_f32_16x16x32_bf16 v[108:111], v[132:135], v[188:191], v[108:111]
	v_mfma_f32_16x16x32_bf16 v[104:107], v[136:139], v[184:187], v[104:107]
	v_mfma_f32_16x16x32_bf16 v[104:107], v[140:143], v[188:191], v[104:107]
	v_mfma_f32_16x16x32_bf16 v[92:95], v[128:131], v[200:203], v[92:95]
	v_mfma_f32_16x16x32_bf16 v[92:95], v[132:135], v[204:207], v[92:95]
	v_mfma_f32_16x16x32_bf16 v[88:91], v[136:139], v[200:203], v[88:91]
	v_mfma_f32_16x16x32_bf16 v[88:91], v[140:143], v[204:207], v[88:91]
	v_mfma_f32_16x16x32_bf16 v[76:79], v[128:131], v[208:211], v[76:79]
	v_mfma_f32_16x16x32_bf16 v[76:79], v[132:135], v[212:215], v[76:79]
	v_mfma_f32_16x16x32_bf16 v[72:75], v[136:139], v[208:211], v[72:75]
	v_mfma_f32_16x16x32_bf16 v[72:75], v[140:143], v[212:215], v[72:75]
	s_setprio 0
	s_setprio 1
	v_mfma_f32_16x16x32_bf16 v[116:119], v[144:147], v[176:179], v[116:119]
	v_mfma_f32_16x16x32_bf16 v[116:119], v[148:151], v[180:183], v[116:119]
	v_mfma_f32_16x16x32_bf16 v[112:115], v[152:155], v[176:179], v[112:115]
	v_mfma_f32_16x16x32_bf16 v[112:115], v[156:159], v[180:183], v[112:115]
	v_mfma_f32_16x16x32_bf16 v[100:103], v[144:147], v[184:187], v[100:103]
	v_mfma_f32_16x16x32_bf16 v[100:103], v[148:151], v[188:191], v[100:103]
	v_mfma_f32_16x16x32_bf16 v[96:99], v[152:155], v[184:187], v[96:99]
	v_mfma_f32_16x16x32_bf16 v[96:99], v[156:159], v[188:191], v[96:99]
	v_mfma_f32_16x16x32_bf16 v[84:87], v[144:147], v[200:203], v[84:87]
	v_mfma_f32_16x16x32_bf16 v[84:87], v[148:151], v[204:207], v[84:87]
	v_mfma_f32_16x16x32_bf16 v[80:83], v[152:155], v[200:203], v[80:83]
	v_mfma_f32_16x16x32_bf16 v[80:83], v[156:159], v[204:207], v[80:83]
	s_barrier
	v_mfma_f32_16x16x32_bf16 v[68:71], v[144:147], v[208:211], v[68:71]
	v_mfma_f32_16x16x32_bf16 v[68:71], v[148:151], v[212:215], v[68:71]
	v_mfma_f32_16x16x32_bf16 v[64:67], v[152:155], v[208:211], v[64:67]
	v_mfma_f32_16x16x32_bf16 v[64:67], v[156:159], v[212:215], v[64:67]
	s_setprio 0
	s_add_i32 s37, s60, s49
	v_lshl_add_u64 v[216:217], s[42:43], 0, v[162:163]
	s_mov_b32 m0, s37
	ds_read_b128 v[176:179], v198 offset:16384
	ds_read_b128 v[180:183], v198 offset:17408
	ds_read_b128 v[184:187], v198 offset:18432
	ds_read_b128 v[188:191], v198 offset:19456
	ds_read_b128 v[200:203], v198 offset:20480
	ds_read_b128 v[204:207], v198 offset:21504
	ds_read_b128 v[208:211], v198 offset:22528
	ds_read_b128 v[212:215], v198 offset:23552
	global_load_lds_dwordx4 v[216:217], off
	s_add_i32 m0, s37, 0x2000
	s_add_u32 s38, s42, 0x80000
	v_lshl_add_u64 v[218:219], s[42:43], 0, v[166:167]
	s_addc_u32 s39, s43, 0
	s_add_i32 s37, s61, s49
	global_load_lds_dwordx4 v[218:219], off
	v_lshl_add_u64 v[220:221], s[38:39], 0, v[162:163]
	s_mov_b32 m0, s37
	v_lshl_add_u64 v[222:223], s[44:45], 0, v[164:165]
	global_load_lds_dwordx4 v[220:221], off
	v_lshl_add_u64 v[220:221], s[38:39], 0, v[166:167]
	s_add_i32 m0, s37, 0x2000
	s_nop 0
	global_load_lds_dwordx4 v[220:221], off
	v_lshl_add_u64 v[220:221], s[44:45], 0, v[160:161]
	s_mov_b32 m0, s50
	s_nop 0
	global_load_lds_dwordx4 v[220:221], off
	s_mov_b32 m0, s51
	s_nop 0
	global_load_lds_dwordx4 v[222:223], off
	s_waitcnt vmcnt(8)
	s_waitcnt lgkmcnt(0)
	s_barrier
; #define PG8_STAGE(bufoff, gbase, voff) do { _Pragma("unroll") for (int _i = 0; _i < 2; ++_i) \
;         __builtin_amdgcn_global_load_lds((const unsigned*)((const char*)(gbase) + (voff)[_i]), (LAS unsigned*)(lds + (bufoff) + ldsw + _i * 8192), 16, 0, 0); } while (0)
; #define PG8_LDA(dst, b, h) do { _Pragma("unroll") for (int m = 0; m < 4; ++m) _Pragma("unroll") for (int k = 0; k < 2; ++k) dst[m][k] = *(const LAS bf16x8*)(lds + PG8_SA(b, h) + aoff + m * 2048 + k * 1024); } while (0)
; #define PG8_LDB(dst, b, h) do { _Pragma("unroll") for (int n = 0; n < 2; ++n) _Pragma("unroll") for (int k = 0; k < 2; ++k) dst[n][k] = *(const LAS bf16x8*)(lds + PG8_SB(b, h) + boff + n * 2048 + k * 1024); } while (0)
; #define PG8_MMA(ai, bj, At, Bt) do { __builtin_amdgcn_s_setprio(1); _Pragma("unroll") for (int m = 0; m < 4; ++m) _Pragma("unroll") for (int n = 0; n < 2; ++n) _Pragma("unroll") for (int k = 0; k < 2; ++k) \
;         acc[ai][bj][m][n] = __builtin_amdgcn_mfma_f32_16x16x32_bf16(Bt[n][k], At[m][k], acc[ai][bj][m][n], 0, 0, 0); __builtin_amdgcn_s_setprio(0); } while (0)
; #define PG8_WAIT_V(n) asm volatile("s_waitcnt vmcnt(" #n ")" ::: "memory")
; #define PG8_WAIT_L(n) asm volatile("s_waitcnt lgkmcnt(" #n ")" ::: "memory")
; #define PG8_BAR __builtin_amdgcn_s_barrier()
; #define PG8_SCHED __builtin_amdgcn_sched_barrier(0)
; template <class Epi, bool ALIGN_EPI>
; __device__ __forceinline__ void gemm_phase(LAS unsigned char* lds, const Gemm g, const StaticOrder& S, const Epi& E) {
;     ...
;             PG8_WAIT_V(8); PG8_WAIT_L(0); PG8_BAR; PG8_MMA(1, 0, At, B0); PG8_MMA(1, 1, At, B1); PG8_BAR; PG8_SCHED;
;             PG8_LDB(B0, 1, 0); PG8_LDB(B1, 1, 1); PG8_SCHED; PG8_LDA(At, 1, 0); PG8_STAGE(PG8_SA(0, 1), a2 + hA, voffA);
;             PG8_WAIT_V(8); PG8_WAIT_L(0); PG8_BAR; PG8_MMA(0, 0, At, B0); PG8_MMA(0, 1, At, B1); PG8_BAR; PG8_SCHED;
;             PG8_LDA(At, 1, 1); PG8_STAGE(PG8_SB(1, 0), b3, voffB); PG8_STAGE(PG8_SB(1, 1), b3 + hB, voffB); PG8_STAGE(PG8_SA(1, 0), a3, voffA);
	s_setprio 1
	s_waitcnt lgkmcnt(0)
	v_mfma_f32_16x16x32_bf16 v[60:63], v[128:131], v[176:179], v[60:63]
	v_mfma_f32_16x16x32_bf16 v[60:63], v[132:135], v[180:183], v[60:63]
	v_mfma_f32_16x16x32_bf16 v[56:59], v[136:139], v[176:179], v[56:59]
	v_mfma_f32_16x16x32_bf16 v[56:59], v[140:143], v[180:183], v[56:59]
	v_mfma_f32_16x16x32_bf16 v[44:47], v[128:131], v[184:187], v[44:47]
	v_mfma_f32_16x16x32_bf16 v[44:47], v[132:135], v[188:191], v[44:47]
	v_mfma_f32_16x16x32_bf16 v[40:43], v[136:139], v[184:187], v[40:43]
	v_mfma_f32_16x16x32_bf16 v[40:43], v[140:143], v[188:191], v[40:43]
	v_mfma_f32_16x16x32_bf16 v[28:31], v[128:131], v[200:203], v[28:31]
	v_mfma_f32_16x16x32_bf16 v[28:31], v[132:135], v[204:207], v[28:31]
	v_mfma_f32_16x16x32_bf16 v[24:27], v[136:139], v[200:203], v[24:27]
	v_mfma_f32_16x16x32_bf16 v[24:27], v[140:143], v[204:207], v[24:27]
	v_mfma_f32_16x16x32_bf16 v[16:19], v[128:131], v[208:211], v[16:19]
	v_mfma_f32_16x16x32_bf16 v[16:19], v[132:135], v[212:215], v[16:19]
	v_mfma_f32_16x16x32_bf16 v[8:11], v[136:139], v[208:211], v[8:11]
	v_mfma_f32_16x16x32_bf16 v[8:11], v[140:143], v[212:215], v[8:11]
	s_setprio 0
	s_setprio 1
	v_mfma_f32_16x16x32_bf16 v[52:55], v[144:147], v[176:179], v[52:55]
	v_mfma_f32_16x16x32_bf16 v[52:55], v[148:151], v[180:183], v[52:55]
	v_mfma_f32_16x16x32_bf16 v[48:51], v[152:155], v[176:179], v[48:51]
	v_mfma_f32_16x16x32_bf16 v[48:51], v[156:159], v[180:183], v[48:51]
	v_mfma_f32_16x16x32_bf16 v[36:39], v[144:147], v[184:187], v[36:39]
	v_mfma_f32_16x16x32_bf16 v[36:39], v[148:151], v[188:191], v[36:39]
	v_mfma_f32_16x16x32_bf16 v[32:35], v[152:155], v[184:187], v[32:35]
	v_mfma_f32_16x16x32_bf16 v[32:35], v[156:159], v[188:191], v[32:35]
	v_mfma_f32_16x16x32_bf16 v[20:23], v[144:147], v[200:203], v[20:23]
	v_mfma_f32_16x16x32_bf16 v[20:23], v[148:151], v[204:207], v[20:23]
	v_mfma_f32_16x16x32_bf16 v[12:15], v[152:155], v[200:203], v[12:15]
	v_mfma_f32_16x16x32_bf16 v[12:15], v[156:159], v[204:207], v[12:15]
	s_barrier
	v_mfma_f32_16x16x32_bf16 v[4:7], v[144:147], v[208:211], v[4:7]
	v_mfma_f32_16x16x32_bf16 v[4:7], v[148:151], v[212:215], v[4:7]
	v_mfma_f32_16x16x32_bf16 v[0:3], v[152:155], v[208:211], v[0:3]
	v_mfma_f32_16x16x32_bf16 v[0:3], v[156:159], v[212:215], v[0:3]
	s_setprio 0
	s_add_i32 s37, 0, 0x18000
	s_add_i32 s63, 0, 0x1c000
	v_add_u32_e32 v140, s37, v194
	v_add_u32_e32 v156, s63, v194
	ds_read_b128 v[128:131], v140
	ds_read_b128 v[132:135], v140 offset:1024
	ds_read_b128 v[136:139], v140 offset:2048
	ds_read_b128 v[140:143], v140 offset:3072
	ds_read_b128 v[144:147], v156
	ds_read_b128 v[148:151], v156 offset:1024
	ds_read_b128 v[152:155], v156 offset:2048
	ds_read_b128 v[156:159], v156 offset:3072
	s_add_u32 s38, s44, 0x80000
	s_addc_u32 s39, s45, 0
	s_mov_b32 m0, s52
	v_lshl_add_u64 v[224:225], s[38:39], 0, v[160:161]
	ds_read_b128 v[176:179], v198 offset:32768
	ds_read_b128 v[180:183], v198 offset:33792
	ds_read_b128 v[184:187], v198 offset:34816
	ds_read_b128 v[188:191], v198 offset:35840
	ds_read_b128 v[200:203], v198 offset:36864
	ds_read_b128 v[204:207], v198 offset:37888
	ds_read_b128 v[208:211], v198 offset:38912
	ds_read_b128 v[212:215], v198 offset:39936
	global_load_lds_dwordx4 v[224:225], off
	v_lshl_add_u64 v[224:225], s[38:39], 0, v[164:165]
	s_mov_b32 m0, s53
	s_nop 0
	global_load_lds_dwordx4 v[224:225], off
	s_waitcnt vmcnt(8)
	s_waitcnt lgkmcnt(0)
	s_barrier
	s_setprio 1
	s_waitcnt lgkmcnt(0)
	v_mfma_f32_16x16x32_bf16 v[124:127], v[128:131], v[176:179], v[124:127]
	v_mfma_f32_16x16x32_bf16 v[124:127], v[132:135], v[180:183], v[124:127]
	v_mfma_f32_16x16x32_bf16 v[120:123], v[136:139], v[176:179], v[120:123]
	v_mfma_f32_16x16x32_bf16 v[120:123], v[140:143], v[180:183], v[120:123]
	v_mfma_f32_16x16x32_bf16 v[108:111], v[128:131], v[184:187], v[108:111]
	v_mfma_f32_16x16x32_bf16 v[108:111], v[132:135], v[188:191], v[108:111]
	v_mfma_f32_16x16x32_bf16 v[104:107], v[136:139], v[184:187], v[104:107]
	v_mfma_f32_16x16x32_bf16 v[104:107], v[140:143], v[188:191], v[104:107]
	v_mfma_f32_16x16x32_bf16 v[92:95], v[128:131], v[200:203], v[92:95]
	v_mfma_f32_16x16x32_bf16 v[92:95], v[132:135], v[204:207], v[92:95]
	v_mfma_f32_16x16x32_bf16 v[88:91], v[136:139], v[200:203], v[88:91]
	v_mfma_f32_16x16x32_bf16 v[88:91], v[140:143], v[204:207], v[88:91]
	v_mfma_f32_16x16x32_bf16 v[76:79], v[128:131], v[208:211], v[76:79]
	v_mfma_f32_16x16x32_bf16 v[76:79], v[132:135], v[212:215], v[76:79]
	v_mfma_f32_16x16x32_bf16 v[72:75], v[136:139], v[208:211], v[72:75]
	v_mfma_f32_16x16x32_bf16 v[72:75], v[140:143], v[212:215], v[72:75]
	s_setprio 0
	s_setprio 1
	v_mfma_f32_16x16x32_bf16 v[116:119], v[144:147], v[176:179], v[116:119]
	v_mfma_f32_16x16x32_bf16 v[116:119], v[148:151], v[180:183], v[116:119]
	v_mfma_f32_16x16x32_bf16 v[112:115], v[152:155], v[176:179], v[112:115]
	v_mfma_f32_16x16x32_bf16 v[112:115], v[156:159], v[180:183], v[112:115]
	v_mfma_f32_16x16x32_bf16 v[100:103], v[144:147], v[184:187], v[100:103]
	v_mfma_f32_16x16x32_bf16 v[100:103], v[148:151], v[188:191], v[100:103]
	v_mfma_f32_16x16x32_bf16 v[96:99], v[152:155], v[184:187], v[96:99]
	v_mfma_f32_16x16x32_bf16 v[96:99], v[156:159], v[188:191], v[96:99]
	v_mfma_f32_16x16x32_bf16 v[84:87], v[144:147], v[200:203], v[84:87]
	v_mfma_f32_16x16x32_bf16 v[84:87], v[148:151], v[204:207], v[84:87]
	v_mfma_f32_16x16x32_bf16 v[80:83], v[152:155], v[200:203], v[80:83]
	v_mfma_f32_16x16x32_bf16 v[80:83], v[156:159], v[204:207], v[80:83]
	s_barrier
; #define PG8_STAGE(bufoff, gbase, voff) do { _Pragma("unroll") for (int _i = 0; _i < 2; ++_i) \
;         __builtin_amdgcn_global_load_lds((const unsigned*)((const char*)(gbase) + (voff)[_i]), (LAS unsigned*)(lds + (bufoff) + ldsw + _i * 8192), 16, 0, 0); } while (0)
; #define PG8_LDA(dst, b, h) do { _Pragma("unroll") for (int m = 0; m < 4; ++m) _Pragma("unroll") for (int k = 0; k < 2; ++k) dst[m][k] = *(const LAS bf16x8*)(lds + PG8_SA(b, h) + aoff + m * 2048 + k * 1024); } while (0)
; #define PG8_MMA(ai, bj, At, Bt) do { __builtin_amdgcn_s_setprio(1); _Pragma("unroll") for (int m = 0; m < 4; ++m) _Pragma("unroll") for (int n = 0; n < 2; ++n) _Pragma("unroll") for (int k = 0; k < 2; ++k) \
;         acc[ai][bj][m][n] = __builtin_amdgcn_mfma_f32_16x16x32_bf16(Bt[n][k], At[m][k], acc[ai][bj][m][n], 0, 0, 0); __builtin_amdgcn_s_setprio(0); } while (0)
; #define PG8_WAIT_V(n) asm volatile("s_waitcnt vmcnt(" #n ")" ::: "memory")
; #define PG8_WAIT_L(n) asm volatile("s_waitcnt lgkmcnt(" #n ")" ::: "memory")
; #define PG8_BAR __builtin_amdgcn_s_barrier()
; #define PG8_SCHED __builtin_amdgcn_sched_barrier(0)
; template <class Epi, bool ALIGN_EPI>
; __device__ __forceinline__ void gemm_phase(LAS unsigned char* lds, const Gemm g, const StaticOrder& S, const Epi& E) {
;     ...
;             PG8_WAIT_V(8); PG8_WAIT_L(0); PG8_BAR; PG8_MMA(0, 0, At, B0); PG8_MMA(0, 1, At, B1); PG8_BAR; PG8_SCHED;
;             PG8_LDA(At, 1, 1); PG8_STAGE(PG8_SB(1, 0), b3, voffB); PG8_STAGE(PG8_SB(1, 1), b3 + hB, voffB); PG8_STAGE(PG8_SA(1, 0), a3, voffA);
;             PG8_WAIT_V(8); PG8_WAIT_L(0); PG8_BAR; PG8_MMA(1, 0, At, B0); PG8_MMA(1, 1, At, B1); PG8_BAR; PG8_SCHED;
;         }
;         if constexpr (ALIGN_EPI) { if (wr == 0) PG8_BAR; }
	v_mfma_f32_16x16x32_bf16 v[68:71], v[144:147], v[208:211], v[68:71]
	v_mfma_f32_16x16x32_bf16 v[68:71], v[148:151], v[212:215], v[68:71]
	v_mfma_f32_16x16x32_bf16 v[64:67], v[152:155], v[208:211], v[64:67]
	v_mfma_f32_16x16x32_bf16 v[64:67], v[156:159], v[212:215], v[64:67]
	s_setprio 0
	s_add_i32 s37, s37, s49
	v_lshl_add_u64 v[216:217], v[216:217], 0, s[20:21]
	s_mov_b32 m0, s37
	ds_read_b128 v[176:179], v198 offset:49152
	ds_read_b128 v[180:183], v198 offset:50176
	ds_read_b128 v[184:187], v198 offset:51200
	ds_read_b128 v[188:191], v198 offset:52224
	ds_read_b128 v[200:203], v198 offset:53248
	ds_read_b128 v[204:207], v198 offset:54272
	ds_read_b128 v[208:211], v198 offset:55296
	ds_read_b128 v[212:215], v198 offset:56320
	global_load_lds_dwordx4 v[216:217], off
	s_add_i32 m0, s37, 0x2000
	s_add_u32 s38, s42, 0x80080
	v_lshl_add_u64 v[216:217], v[218:219], 0, s[20:21]
	s_addc_u32 s39, s43, 0
	s_add_i32 s37, s63, s49
	global_load_lds_dwordx4 v[216:217], off
	v_lshl_add_u64 v[216:217], s[38:39], 0, v[162:163]
	s_mov_b32 m0, s37
	s_nop 0
	global_load_lds_dwordx4 v[216:217], off
	v_lshl_add_u64 v[216:217], s[38:39], 0, v[166:167]
	s_add_i32 m0, s37, 0x2000
	s_nop 0
	global_load_lds_dwordx4 v[216:217], off
	v_lshl_add_u64 v[216:217], v[220:221], 0, s[20:21]
	s_mov_b32 m0, s57
	s_nop 0
	global_load_lds_dwordx4 v[216:217], off
	v_lshl_add_u64 v[216:217], v[222:223], 0, s[20:21]
	s_mov_b32 m0, s58
	s_nop 0
	global_load_lds_dwordx4 v[216:217], off
	s_waitcnt vmcnt(8)
	s_waitcnt lgkmcnt(0)
	s_barrier
	s_setprio 1
	s_waitcnt lgkmcnt(0)
	v_mfma_f32_16x16x32_bf16 v[60:63], v[128:131], v[176:179], v[60:63]
	v_mfma_f32_16x16x32_bf16 v[60:63], v[132:135], v[180:183], v[60:63]
	v_mfma_f32_16x16x32_bf16 v[56:59], v[136:139], v[176:179], v[56:59]
	v_mfma_f32_16x16x32_bf16 v[56:59], v[140:143], v[180:183], v[56:59]
	v_mfma_f32_16x16x32_bf16 v[44:47], v[128:131], v[184:187], v[44:47]
	v_mfma_f32_16x16x32_bf16 v[44:47], v[132:135], v[188:191], v[44:47]
	v_mfma_f32_16x16x32_bf16 v[40:43], v[136:139], v[184:187], v[40:43]
	v_mfma_f32_16x16x32_bf16 v[40:43], v[140:143], v[188:191], v[40:43]
	v_mfma_f32_16x16x32_bf16 v[28:31], v[128:131], v[200:203], v[28:31]
	v_mfma_f32_16x16x32_bf16 v[28:31], v[132:135], v[204:207], v[28:31]
	v_mfma_f32_16x16x32_bf16 v[24:27], v[136:139], v[200:203], v[24:27]
	v_mfma_f32_16x16x32_bf16 v[24:27], v[140:143], v[204:207], v[24:27]
	v_mfma_f32_16x16x32_bf16 v[16:19], v[128:131], v[208:211], v[16:19]
	v_mfma_f32_16x16x32_bf16 v[16:19], v[132:135], v[212:215], v[16:19]
	v_mfma_f32_16x16x32_bf16 v[8:11], v[136:139], v[208:211], v[8:11]
	v_mfma_f32_16x16x32_bf16 v[8:11], v[140:143], v[212:215], v[8:11]
	s_setprio 0
	s_setprio 1
	v_mfma_f32_16x16x32_bf16 v[52:55], v[144:147], v[176:179], v[52:55]
	v_mfma_f32_16x16x32_bf16 v[52:55], v[148:151], v[180:183], v[52:55]
	v_mfma_f32_16x16x32_bf16 v[48:51], v[152:155], v[176:179], v[48:51]
	v_mfma_f32_16x16x32_bf16 v[48:51], v[156:159], v[180:183], v[48:51]
	v_mfma_f32_16x16x32_bf16 v[36:39], v[144:147], v[184:187], v[36:39]
	v_mfma_f32_16x16x32_bf16 v[36:39], v[148:151], v[188:191], v[36:39]
	v_mfma_f32_16x16x32_bf16 v[32:35], v[152:155], v[184:187], v[32:35]
	v_mfma_f32_16x16x32_bf16 v[32:35], v[156:159], v[188:191], v[32:35]
	v_mfma_f32_16x16x32_bf16 v[20:23], v[144:147], v[200:203], v[20:23]
	v_mfma_f32_16x16x32_bf16 v[20:23], v[148:151], v[204:207], v[20:23]
	v_mfma_f32_16x16x32_bf16 v[12:15], v[152:155], v[200:203], v[12:15]
	v_mfma_f32_16x16x32_bf16 v[12:15], v[156:159], v[204:207], v[12:15]
	s_barrier
	v_mfma_f32_16x16x32_bf16 v[4:7], v[144:147], v[208:211], v[4:7]
	v_mfma_f32_16x16x32_bf16 v[4:7], v[148:151], v[212:215], v[4:7]
	v_mfma_f32_16x16x32_bf16 v[0:3], v[152:155], v[208:211], v[0:3]
	v_mfma_f32_16x16x32_bf16 v[0:3], v[156:159], v[212:215], v[0:3]
	s_setprio 0
	s_add_i32 s29, s29, 2
	s_add_u32 s40, s40, 0x100
	s_addc_u32 s41, s41, 0
	s_add_u32 s9, s9, 0x100
	s_addc_u32 s27, s27, 0
	s_cmp_gt_u32 s29, 29
	s_cbranch_scc0 .LBB0_775
	s_and_b64 vcc, exec, s[22:23]
	s_cbranch_vccz .LBB0_778
	s_barrier

; #define PG8_STAGE(bufoff, gbase, voff) do { _Pragma("unroll") for (int _i = 0; _i < 2; ++_i) \
;         __builtin_amdgcn_global_load_lds((const unsigned*)((const char*)(gbase) + (voff)[_i]), (LAS unsigned*)(lds + (bufoff) + ldsw + _i * 8192), 16, 0, 0); } while (0)
; #define PG8_LDA(dst, b, h) do { _Pragma("unroll") for (int m = 0; m < 4; ++m) _Pragma("unroll") for (int k = 0; k < 2; ++k) dst[m][k] = *(const LAS bf16x8*)(lds + PG8_SA(b, h) + aoff + m * 2048 + k * 1024); } while (0)
; #define PG8_LDB(dst, b, h) do { _Pragma("unroll") for (int n = 0; n < 2; ++n) _Pragma("unroll") for (int k = 0; k < 2; ++k) dst[n][k] = *(const LAS bf16x8*)(lds + PG8_SB(b, h) + boff + n * 2048 + k * 1024); } while (0)
; #define PG8_MMA(ai, bj, At, Bt) do { __builtin_amdgcn_s_setprio(1); _Pragma("unroll") for (int m = 0; m < 4; ++m) _Pragma("unroll") for (int n = 0; n < 2; ++n) _Pragma("unroll") for (int k = 0; k < 2; ++k) \
;         acc[ai][bj][m][n] = __builtin_amdgcn_mfma_f32_16x16x32_bf16(Bt[n][k], At[m][k], acc[ai][bj][m][n], 0, 0, 0); __builtin_amdgcn_s_setprio(0); } while (0)
; #define PG8_WAIT_V(n) asm volatile("s_waitcnt vmcnt(" #n ")" ::: "memory")
; #define PG8_WAIT_L(n) asm volatile("s_waitcnt lgkmcnt(" #n ")" ::: "memory")
; #define PG8_BAR __builtin_amdgcn_s_barrier()
; #define PG8_SCHED __builtin_amdgcn_sched_barrier(0)
; template <class Epi, bool ALIGN_EPI>
; __device__ __forceinline__ void gemm_phase(LAS unsigned char* lds, const Gemm g, const StaticOrder& S, const Epi& E) {
;     ...
;         for (int t = 0; t < nt; t += 2) {
;             const bool last = (t == nt - 2);
;             const char* a1 = cA + (size_t)(t + 1) * kstep;
;             const char* a2 = last ? nA : cA + (size_t)(t + 2) * kstep; const char* b2 = last ? nB : cB + (size_t)(t + 2) * kstep;
;             const char* a3 = a2 + kstep; const char* b3 = b2 + kstep;
;             PG8_LDB(B0, 0, 0); PG8_LDB(B1, 0, 1); PG8_SCHED; PG8_LDA(At, 0, 0); PG8_STAGE(PG8_SA(1, 1), a1 + hA, voffA);
;             PG8_WAIT_V(8); PG8_WAIT_L(0); PG8_BAR; PG8_MMA(0, 0, At, B0); PG8_MMA(0, 1, At, B1); PG8_BAR; PG8_SCHED;
;             PG8_LDA(At, 0, 1); PG8_STAGE(PG8_SB(0, 0), b2, voffB); PG8_STAGE(PG8_SB(0, 1), b2 + hB, voffB); PG8_STAGE(PG8_SA(0, 0), a2, voffA);
;             PG8_WAIT_V(8); PG8_WAIT_L(0); PG8_BAR; PG8_MMA(1, 0, At, B0); PG8_MMA(1, 1, At, B1); PG8_BAR; PG8_SCHED;
.LBB0_926:
	ds_read_b128 v[168:171], v153
	ds_read_b128 v[172:175], v153 offset:1024
	ds_read_b128 v[176:179], v153 offset:2048
	ds_read_b128 v[180:183], v153 offset:3072
	ds_read_b128 v[184:187], v155
	ds_read_b128 v[188:191], v155 offset:1024
	ds_read_b128 v[194:197], v155 offset:2048
	ds_read_b128 v[198:201], v155 offset:3072
	s_add_u32 s8, s6, 0xfff80080
	s_addc_u32 s9, s7, -1
	s_cmp_eq_u32 s71, 28
	s_cselect_b32 s55, s47, s9
	s_cselect_b32 s54, s67, s8
	s_cselect_b32 s9, s45, s70
	s_cselect_b32 s8, s68, s69
	v_lshl_add_u64 v[234:235], s[6:7], 0, v[136:137]
	s_add_i32 m0, s39, 0xc000
	ds_read_b128 v[202:205], v156
	ds_read_b128 v[206:209], v156 offset:1024
	ds_read_b128 v[210:213], v156 offset:2048
	ds_read_b128 v[214:217], v156 offset:3072
	ds_read_b128 v[218:221], v156 offset:4096
	ds_read_b128 v[222:225], v156 offset:5120
	ds_read_b128 v[226:229], v156 offset:6144
	ds_read_b128 v[230:233], v156 offset:7168
	global_load_lds_dwordx4 v[234:235], off
	v_lshl_add_u64 v[234:235], s[6:7], 0, v[138:139]
	s_add_i32 m0, s39, 0xe000
	s_nop 0
	global_load_lds_dwordx4 v[234:235], off
	s_waitcnt vmcnt(8)
	s_waitcnt lgkmcnt(0)
	s_barrier
	s_setprio 1
	s_waitcnt lgkmcnt(0)
	v_mfma_f32_16x16x32_bf16 v[124:127], v[168:171], v[202:205], v[124:127]
	v_mfma_f32_16x16x32_bf16 v[124:127], v[172:175], v[206:209], v[124:127]
	v_mfma_f32_16x16x32_bf16 v[120:123], v[176:179], v[202:205], v[120:123]
	v_mfma_f32_16x16x32_bf16 v[120:123], v[180:183], v[206:209], v[120:123]
	v_mfma_f32_16x16x32_bf16 v[108:111], v[168:171], v[210:213], v[108:111]
	v_mfma_f32_16x16x32_bf16 v[108:111], v[172:175], v[214:217], v[108:111]
	v_mfma_f32_16x16x32_bf16 v[104:107], v[176:179], v[210:213], v[104:107]
	v_mfma_f32_16x16x32_bf16 v[104:107], v[180:183], v[214:217], v[104:107]
	v_mfma_f32_16x16x32_bf16 v[92:95], v[168:171], v[218:221], v[92:95]
	v_mfma_f32_16x16x32_bf16 v[92:95], v[172:175], v[222:225], v[92:95]
	v_mfma_f32_16x16x32_bf16 v[88:91], v[176:179], v[218:221], v[88:91]
	v_mfma_f32_16x16x32_bf16 v[88:91], v[180:183], v[222:225], v[88:91]
	v_mfma_f32_16x16x32_bf16 v[76:79], v[168:171], v[226:229], v[76:79]
	v_mfma_f32_16x16x32_bf16 v[76:79], v[172:175], v[230:233], v[76:79]
	v_mfma_f32_16x16x32_bf16 v[72:75], v[176:179], v[226:229], v[72:75]
	v_mfma_f32_16x16x32_bf16 v[72:75], v[180:183], v[230:233], v[72:75]
	s_setprio 0
	s_setprio 1
	v_mfma_f32_16x16x32_bf16 v[116:119], v[184:187], v[202:205], v[116:119]
	v_mfma_f32_16x16x32_bf16 v[116:119], v[188:191], v[206:209], v[116:119]
	v_mfma_f32_16x16x32_bf16 v[112:115], v[194:197], v[202:205], v[112:115]
	v_mfma_f32_16x16x32_bf16 v[112:115], v[198:201], v[206:209], v[112:115]
	v_mfma_f32_16x16x32_bf16 v[100:103], v[184:187], v[210:213], v[100:103]
	v_mfma_f32_16x16x32_bf16 v[100:103], v[188:191], v[214:217], v[100:103]
	v_mfma_f32_16x16x32_bf16 v[96:99], v[194:197], v[210:213], v[96:99]
	v_mfma_f32_16x16x32_bf16 v[96:99], v[198:201], v[214:217], v[96:99]
	v_mfma_f32_16x16x32_bf16 v[84:87], v[184:187], v[218:221], v[84:87]
	v_mfma_f32_16x16x32_bf16 v[84:87], v[188:191], v[222:225], v[84:87]
	v_mfma_f32_16x16x32_bf16 v[80:83], v[194:197], v[218:221], v[80:83]
	v_mfma_f32_16x16x32_bf16 v[80:83], v[198:201], v[222:225], v[80:83]
	s_barrier
	v_mfma_f32_16x16x32_bf16 v[68:71], v[184:187], v[226:229], v[68:71]
	v_mfma_f32_16x16x32_bf16 v[68:71], v[188:191], v[230:233], v[68:71]
	v_mfma_f32_16x16x32_bf16 v[64:67], v[194:197], v[226:229], v[64:67]
	v_mfma_f32_16x16x32_bf16 v[64:67], v[198:201], v[230:233], v[64:67]
	s_setprio 0
	s_add_i32 s72, s63, s33
	v_lshl_add_u64 v[234:235], s[8:9], 0, v[132:133]
	s_mov_b32 m0, s72
	ds_read_b128 v[202:205], v156 offset:16384
	ds_read_b128 v[206:209], v156 offset:17408
	ds_read_b128 v[210:213], v156 offset:18432
	ds_read_b128 v[214:217], v156 offset:19456
	ds_read_b128 v[218:221], v156 offset:20480
	ds_read_b128 v[222:225], v156 offset:21504
	ds_read_b128 v[226:229], v156 offset:22528
	ds_read_b128 v[230:233], v156 offset:23552
	global_load_lds_dwordx4 v[234:235], off
	s_add_i32 m0, s72, 0x2000
	s_add_u32 s72, s8, 0x80000
	v_lshl_add_u64 v[236:237], s[8:9], 0, v[128:129]
	s_addc_u32 s73, s9, 0
	s_add_i32 s74, s64, s33
	global_load_lds_dwordx4 v[236:237], off
	v_lshl_add_u64 v[238:239], s[72:73], 0, v[132:133]
	s_mov_b32 m0, s74
	v_lshl_add_u64 v[240:241], s[54:55], 0, v[130:131]
	global_load_lds_dwordx4 v[238:239], off
	v_lshl_add_u64 v[238:239], s[72:73], 0, v[128:129]
	s_add_i32 m0, s74, 0x2000
	s_nop 0
	global_load_lds_dwordx4 v[238:239], off
	v_lshl_add_u64 v[238:239], s[54:55], 0, v[134:135]
	s_mov_b32 m0, s39
	s_nop 0
	global_load_lds_dwordx4 v[238:239], off
	s_mov_b32 m0, s53
	s_nop 0
	global_load_lds_dwordx4 v[240:241], off
	s_waitcnt vmcnt(8)
	s_waitcnt lgkmcnt(0)
	s_barrier
; #define PG8_STAGE(bufoff, gbase, voff) do { _Pragma("unroll") for (int _i = 0; _i < 2; ++_i) \
;         __builtin_amdgcn_global_load_lds((const unsigned*)((const char*)(gbase) + (voff)[_i]), (LAS unsigned*)(lds + (bufoff) + ldsw + _i * 8192), 16, 0, 0); } while (0)
; #define PG8_LDA(dst, b, h) do { _Pragma("unroll") for (int m = 0; m < 4; ++m) _Pragma("unroll") for (int k = 0; k < 2; ++k) dst[m][k] = *(const LAS bf16x8*)(lds + PG8_SA(b, h) + aoff + m * 2048 + k * 1024); } while (0)
; #define PG8_LDB(dst, b, h) do { _Pragma("unroll") for (int n = 0; n < 2; ++n) _Pragma("unroll") for (int k = 0; k < 2; ++k) dst[n][k] = *(const LAS bf16x8*)(lds + PG8_SB(b, h) + boff + n * 2048 + k * 1024); } while (0)
; #define PG8_MMA(ai, bj, At, Bt) do { __builtin_amdgcn_s_setprio(1); _Pragma("unroll") for (int m = 0; m < 4; ++m) _Pragma("unroll") for (int n = 0; n < 2; ++n) _Pragma("unroll") for (int k = 0; k < 2; ++k) \
;         acc[ai][bj][m][n] = __builtin_amdgcn_mfma_f32_16x16x32_bf16(Bt[n][k], At[m][k], acc[ai][bj][m][n], 0, 0, 0); __builtin_amdgcn_s_setprio(0); } while (0)
; #define PG8_WAIT_V(n) asm volatile("s_waitcnt vmcnt(" #n ")" ::: "memory")
; #define PG8_WAIT_L(n) asm volatile("s_waitcnt lgkmcnt(" #n ")" ::: "memory")
; #define PG8_BAR __builtin_amdgcn_s_barrier()
; #define PG8_SCHED __builtin_amdgcn_sched_barrier(0)
; template <class Epi, bool ALIGN_EPI>
; __device__ __forceinline__ void gemm_phase(LAS unsigned char* lds, const Gemm g, const StaticOrder& S, const Epi& E) {
;     ...
;             PG8_WAIT_V(8); PG8_WAIT_L(0); PG8_BAR; PG8_MMA(1, 0, At, B0); PG8_MMA(1, 1, At, B1); PG8_BAR; PG8_SCHED;
;             PG8_LDB(B0, 1, 0); PG8_LDB(B1, 1, 1); PG8_SCHED; PG8_LDA(At, 1, 0); PG8_STAGE(PG8_SA(0, 1), a2 + hA, voffA);
;             PG8_WAIT_V(8); PG8_WAIT_L(0); PG8_BAR; PG8_MMA(0, 0, At, B0); PG8_MMA(0, 1, At, B1); PG8_BAR; PG8_SCHED;
;             PG8_LDA(At, 1, 1); PG8_STAGE(PG8_SB(1, 0), b3, voffB); PG8_STAGE(PG8_SB(1, 1), b3 + hB, voffB); PG8_STAGE(PG8_SA(1, 0), a3, voffA);
	s_setprio 1
	s_waitcnt lgkmcnt(0)
	v_mfma_f32_16x16x32_bf16 v[60:63], v[168:171], v[202:205], v[60:63]
	v_mfma_f32_16x16x32_bf16 v[60:63], v[172:175], v[206:209], v[60:63]
	v_mfma_f32_16x16x32_bf16 v[56:59], v[176:179], v[202:205], v[56:59]
	v_mfma_f32_16x16x32_bf16 v[56:59], v[180:183], v[206:209], v[56:59]
	v_mfma_f32_16x16x32_bf16 v[44:47], v[168:171], v[210:213], v[44:47]
	v_mfma_f32_16x16x32_bf16 v[44:47], v[172:175], v[214:217], v[44:47]
	v_mfma_f32_16x16x32_bf16 v[40:43], v[176:179], v[210:213], v[40:43]
	v_mfma_f32_16x16x32_bf16 v[40:43], v[180:183], v[214:217], v[40:43]
	v_mfma_f32_16x16x32_bf16 v[28:31], v[168:171], v[218:221], v[28:31]
	v_mfma_f32_16x16x32_bf16 v[28:31], v[172:175], v[222:225], v[28:31]
	v_mfma_f32_16x16x32_bf16 v[24:27], v[176:179], v[218:221], v[24:27]
	v_mfma_f32_16x16x32_bf16 v[24:27], v[180:183], v[222:225], v[24:27]
	v_mfma_f32_16x16x32_bf16 v[12:15], v[168:171], v[226:229], v[12:15]
	v_mfma_f32_16x16x32_bf16 v[12:15], v[172:175], v[230:233], v[12:15]
	v_mfma_f32_16x16x32_bf16 v[8:11], v[176:179], v[226:229], v[8:11]
	v_mfma_f32_16x16x32_bf16 v[8:11], v[180:183], v[230:233], v[8:11]
	s_setprio 0
	s_setprio 1
	v_mfma_f32_16x16x32_bf16 v[52:55], v[184:187], v[202:205], v[52:55]
	v_mfma_f32_16x16x32_bf16 v[52:55], v[188:191], v[206:209], v[52:55]
	v_mfma_f32_16x16x32_bf16 v[48:51], v[194:197], v[202:205], v[48:51]
	v_mfma_f32_16x16x32_bf16 v[48:51], v[198:201], v[206:209], v[48:51]
	v_mfma_f32_16x16x32_bf16 v[36:39], v[184:187], v[210:213], v[36:39]
	v_mfma_f32_16x16x32_bf16 v[36:39], v[188:191], v[214:217], v[36:39]
	v_mfma_f32_16x16x32_bf16 v[32:35], v[194:197], v[210:213], v[32:35]
	v_mfma_f32_16x16x32_bf16 v[32:35], v[198:201], v[214:217], v[32:35]
	v_mfma_f32_16x16x32_bf16 v[20:23], v[184:187], v[218:221], v[20:23]
	v_mfma_f32_16x16x32_bf16 v[20:23], v[188:191], v[222:225], v[20:23]
	v_mfma_f32_16x16x32_bf16 v[16:19], v[194:197], v[218:221], v[16:19]
	v_mfma_f32_16x16x32_bf16 v[16:19], v[198:201], v[222:225], v[16:19]
	s_barrier
	v_mfma_f32_16x16x32_bf16 v[4:7], v[184:187], v[226:229], v[4:7]
	v_mfma_f32_16x16x32_bf16 v[4:7], v[188:191], v[230:233], v[4:7]
	v_mfma_f32_16x16x32_bf16 v[0:3], v[194:197], v[226:229], v[0:3]
	v_mfma_f32_16x16x32_bf16 v[0:3], v[198:201], v[230:233], v[0:3]
	s_setprio 0
	s_add_i32 s72, 0, 0x18000
	v_add_u32_e32 v167, s72, v149
	s_add_i32 s73, 0, 0x1c000
	ds_read_b128 v[168:171], v167
	ds_read_b128 v[172:175], v167 offset:1024
	ds_read_b128 v[176:179], v167 offset:2048
	ds_read_b128 v[180:183], v167 offset:3072
	v_add_u32_e32 v167, s73, v149
	ds_read_b128 v[184:187], v167
	ds_read_b128 v[188:191], v167 offset:1024
	ds_read_b128 v[194:197], v167 offset:2048
	ds_read_b128 v[198:201], v167 offset:3072
	s_add_u32 s54, s54, 0x80000
	s_addc_u32 s55, s55, 0
	s_mov_b32 m0, s56
	v_lshl_add_u64 v[242:243], s[54:55], 0, v[134:135]
	ds_read_b128 v[202:205], v156 offset:32768
	ds_read_b128 v[206:209], v156 offset:33792
	ds_read_b128 v[210:213], v156 offset:34816
	ds_read_b128 v[214:217], v156 offset:35840
	ds_read_b128 v[218:221], v156 offset:36864
	ds_read_b128 v[222:225], v156 offset:37888
	ds_read_b128 v[226:229], v156 offset:38912
	ds_read_b128 v[230:233], v156 offset:39936
	global_load_lds_dwordx4 v[242:243], off
	v_lshl_add_u64 v[242:243], s[54:55], 0, v[130:131]
	s_mov_b32 m0, s57
	s_nop 0
	global_load_lds_dwordx4 v[242:243], off
	s_waitcnt vmcnt(8)
	s_waitcnt lgkmcnt(0)
	s_barrier
	s_setprio 1
	s_waitcnt lgkmcnt(0)
	v_mfma_f32_16x16x32_bf16 v[124:127], v[168:171], v[202:205], v[124:127]
	v_mfma_f32_16x16x32_bf16 v[124:127], v[172:175], v[206:209], v[124:127]
	v_mfma_f32_16x16x32_bf16 v[120:123], v[176:179], v[202:205], v[120:123]
	v_mfma_f32_16x16x32_bf16 v[120:123], v[180:183], v[206:209], v[120:123]
	v_mfma_f32_16x16x32_bf16 v[108:111], v[168:171], v[210:213], v[108:111]
	v_mfma_f32_16x16x32_bf16 v[108:111], v[172:175], v[214:217], v[108:111]
	v_mfma_f32_16x16x32_bf16 v[104:107], v[176:179], v[210:213], v[104:107]
	v_mfma_f32_16x16x32_bf16 v[104:107], v[180:183], v[214:217], v[104:107]
	v_mfma_f32_16x16x32_bf16 v[92:95], v[168:171], v[218:221], v[92:95]
	v_mfma_f32_16x16x32_bf16 v[92:95], v[172:175], v[222:225], v[92:95]
	v_mfma_f32_16x16x32_bf16 v[88:91], v[176:179], v[218:221], v[88:91]
	v_mfma_f32_16x16x32_bf16 v[88:91], v[180:183], v[222:225], v[88:91]
	v_mfma_f32_16x16x32_bf16 v[76:79], v[168:171], v[226:229], v[76:79]
	v_mfma_f32_16x16x32_bf16 v[76:79], v[172:175], v[230:233], v[76:79]
	v_mfma_f32_16x16x32_bf16 v[72:75], v[176:179], v[226:229], v[72:75]
	v_mfma_f32_16x16x32_bf16 v[72:75], v[180:183], v[230:233], v[72:75]
	s_setprio 0
	s_setprio 1
	v_mfma_f32_16x16x32_bf16 v[116:119], v[184:187], v[202:205], v[116:119]
	v_mfma_f32_16x16x32_bf16 v[116:119], v[188:191], v[206:209], v[116:119]
	v_mfma_f32_16x16x32_bf16 v[112:115], v[194:197], v[202:205], v[112:115]
	v_mfma_f32_16x16x32_bf16 v[112:115], v[198:201], v[206:209], v[112:115]
	v_mfma_f32_16x16x32_bf16 v[100:103], v[184:187], v[210:213], v[100:103]
	v_mfma_f32_16x16x32_bf16 v[100:103], v[188:191], v[214:217], v[100:103]
	v_mfma_f32_16x16x32_bf16 v[96:99], v[194:197], v[210:213], v[96:99]
	v_mfma_f32_16x16x32_bf16 v[96:99], v[198:201], v[214:217], v[96:99]
	v_mfma_f32_16x16x32_bf16 v[84:87], v[184:187], v[218:221], v[84:87]
	v_mfma_f32_16x16x32_bf16 v[84:87], v[188:191], v[222:225], v[84:87]
	v_mfma_f32_16x16x32_bf16 v[80:83], v[194:197], v[218:221], v[80:83]
	v_mfma_f32_16x16x32_bf16 v[80:83], v[198:201], v[222:225], v[80:83]
	s_barrier
; #define PG8_STAGE(bufoff, gbase, voff) do { _Pragma("unroll") for (int _i = 0; _i < 2; ++_i) \
;         __builtin_amdgcn_global_load_lds((const unsigned*)((const char*)(gbase) + (voff)[_i]), (LAS unsigned*)(lds + (bufoff) + ldsw + _i * 8192), 16, 0, 0); } while (0)
; #define PG8_LDA(dst, b, h) do { _Pragma("unroll") for (int m = 0; m < 4; ++m) _Pragma("unroll") for (int k = 0; k < 2; ++k) dst[m][k] = *(const LAS bf16x8*)(lds + PG8_SA(b, h) + aoff + m * 2048 + k * 1024); } while (0)
; #define PG8_MMA(ai, bj, At, Bt) do { __builtin_amdgcn_s_setprio(1); _Pragma("unroll") for (int m = 0; m < 4; ++m) _Pragma("unroll") for (int n = 0; n < 2; ++n) _Pragma("unroll") for (int k = 0; k < 2; ++k) \
;         acc[ai][bj][m][n] = __builtin_amdgcn_mfma_f32_16x16x32_bf16(Bt[n][k], At[m][k], acc[ai][bj][m][n], 0, 0, 0); __builtin_amdgcn_s_setprio(0); } while (0)
; #define PG8_WAIT_V(n) asm volatile("s_waitcnt vmcnt(" #n ")" ::: "memory")
; #define PG8_WAIT_L(n) asm volatile("s_waitcnt lgkmcnt(" #n ")" ::: "memory")
; #define PG8_BAR __builtin_amdgcn_s_barrier()
; #define PG8_SCHED __builtin_amdgcn_sched_barrier(0)
; template <class Epi, bool ALIGN_EPI>
; __device__ __forceinline__ void gemm_phase(LAS unsigned char* lds, const Gemm g, const StaticOrder& S, const Epi& E) {
;     ...
;             PG8_WAIT_V(8); PG8_WAIT_L(0); PG8_BAR; PG8_MMA(0, 0, At, B0); PG8_MMA(0, 1, At, B1); PG8_BAR; PG8_SCHED;
;             PG8_LDA(At, 1, 1); PG8_STAGE(PG8_SB(1, 0), b3, voffB); PG8_STAGE(PG8_SB(1, 1), b3 + hB, voffB); PG8_STAGE(PG8_SA(1, 0), a3, voffA);
;             PG8_WAIT_V(8); PG8_WAIT_L(0); PG8_BAR; PG8_MMA(1, 0, At, B0); PG8_MMA(1, 1, At, B1); PG8_BAR; PG8_SCHED;
;         }
;         if constexpr (ALIGN_EPI) { if (wr == 0) PG8_BAR; }
	v_mfma_f32_16x16x32_bf16 v[68:71], v[184:187], v[226:229], v[68:71]
	v_mfma_f32_16x16x32_bf16 v[68:71], v[188:191], v[230:233], v[68:71]
	v_mfma_f32_16x16x32_bf16 v[64:67], v[194:197], v[226:229], v[64:67]
	v_mfma_f32_16x16x32_bf16 v[64:67], v[198:201], v[230:233], v[64:67]
	s_setprio 0
	s_add_i32 s54, s72, s33
	v_lshl_add_u64 v[234:235], v[234:235], 0, s[18:19]
	s_mov_b32 m0, s54
	ds_read_b128 v[202:205], v156 offset:49152
	ds_read_b128 v[206:209], v156 offset:50176
	ds_read_b128 v[210:213], v156 offset:51200
	ds_read_b128 v[214:217], v156 offset:52224
	ds_read_b128 v[218:221], v156 offset:53248
	ds_read_b128 v[222:225], v156 offset:54272
	ds_read_b128 v[226:229], v156 offset:55296
	ds_read_b128 v[230:233], v156 offset:56320
	global_load_lds_dwordx4 v[234:235], off
	s_add_i32 m0, s54, 0x2000
	s_add_u32 s8, s8, 0x80080
	v_lshl_add_u64 v[234:235], v[236:237], 0, s[18:19]
	s_addc_u32 s9, s9, 0
	s_add_i32 s54, s73, s33
	global_load_lds_dwordx4 v[234:235], off
	v_lshl_add_u64 v[234:235], s[8:9], 0, v[132:133]
	s_mov_b32 m0, s54
	s_nop 0
	global_load_lds_dwordx4 v[234:235], off
	v_lshl_add_u64 v[234:235], s[8:9], 0, v[128:129]
	s_add_i32 m0, s54, 0x2000
	s_nop 0
	global_load_lds_dwordx4 v[234:235], off
	v_lshl_add_u64 v[234:235], v[238:239], 0, s[18:19]
	s_mov_b32 m0, s60
	s_nop 0
	global_load_lds_dwordx4 v[234:235], off
	v_lshl_add_u64 v[234:235], v[240:241], 0, s[18:19]
	s_mov_b32 m0, s61
	s_nop 0
	global_load_lds_dwordx4 v[234:235], off
	s_waitcnt vmcnt(8)
	s_waitcnt lgkmcnt(0)
	s_barrier
	s_setprio 1
	s_waitcnt lgkmcnt(0)
	v_mfma_f32_16x16x32_bf16 v[60:63], v[168:171], v[202:205], v[60:63]
	v_mfma_f32_16x16x32_bf16 v[60:63], v[172:175], v[206:209], v[60:63]
	v_mfma_f32_16x16x32_bf16 v[56:59], v[176:179], v[202:205], v[56:59]
	v_mfma_f32_16x16x32_bf16 v[56:59], v[180:183], v[206:209], v[56:59]
	v_mfma_f32_16x16x32_bf16 v[44:47], v[168:171], v[210:213], v[44:47]
	v_mfma_f32_16x16x32_bf16 v[44:47], v[172:175], v[214:217], v[44:47]
	v_mfma_f32_16x16x32_bf16 v[40:43], v[176:179], v[210:213], v[40:43]
	v_mfma_f32_16x16x32_bf16 v[40:43], v[180:183], v[214:217], v[40:43]
	v_mfma_f32_16x16x32_bf16 v[28:31], v[168:171], v[218:221], v[28:31]
	v_mfma_f32_16x16x32_bf16 v[28:31], v[172:175], v[222:225], v[28:31]
	v_mfma_f32_16x16x32_bf16 v[24:27], v[176:179], v[218:221], v[24:27]
	v_mfma_f32_16x16x32_bf16 v[24:27], v[180:183], v[222:225], v[24:27]
	v_mfma_f32_16x16x32_bf16 v[12:15], v[168:171], v[226:229], v[12:15]
	v_mfma_f32_16x16x32_bf16 v[12:15], v[172:175], v[230:233], v[12:15]
	v_mfma_f32_16x16x32_bf16 v[8:11], v[176:179], v[226:229], v[8:11]
	v_mfma_f32_16x16x32_bf16 v[8:11], v[180:183], v[230:233], v[8:11]
	s_setprio 0
	s_setprio 1
	v_mfma_f32_16x16x32_bf16 v[52:55], v[184:187], v[202:205], v[52:55]
	v_mfma_f32_16x16x32_bf16 v[52:55], v[188:191], v[206:209], v[52:55]
	v_mfma_f32_16x16x32_bf16 v[48:51], v[194:197], v[202:205], v[48:51]
	v_mfma_f32_16x16x32_bf16 v[48:51], v[198:201], v[206:209], v[48:51]
	v_mfma_f32_16x16x32_bf16 v[36:39], v[184:187], v[210:213], v[36:39]
	v_mfma_f32_16x16x32_bf16 v[36:39], v[188:191], v[214:217], v[36:39]
	v_mfma_f32_16x16x32_bf16 v[32:35], v[194:197], v[210:213], v[32:35]
	v_mfma_f32_16x16x32_bf16 v[32:35], v[198:201], v[214:217], v[32:35]
	v_mfma_f32_16x16x32_bf16 v[20:23], v[184:187], v[218:221], v[20:23]
	v_mfma_f32_16x16x32_bf16 v[20:23], v[188:191], v[222:225], v[20:23]
	v_mfma_f32_16x16x32_bf16 v[16:19], v[194:197], v[218:221], v[16:19]
	v_mfma_f32_16x16x32_bf16 v[16:19], v[198:201], v[222:225], v[16:19]
	s_barrier
	v_mfma_f32_16x16x32_bf16 v[4:7], v[184:187], v[226:229], v[4:7]
	v_mfma_f32_16x16x32_bf16 v[4:7], v[188:191], v[230:233], v[4:7]
	v_mfma_f32_16x16x32_bf16 v[0:3], v[194:197], v[226:229], v[0:3]
	v_mfma_f32_16x16x32_bf16 v[0:3], v[198:201], v[230:233], v[0:3]
	s_setprio 0
	s_add_i32 s71, s71, 2
	s_add_u32 s6, s6, 0x100
	s_addc_u32 s7, s7, 0
	s_add_u32 s69, s69, 0x100
	s_addc_u32 s70, s70, 0
	s_cmp_gt_u32 s71, 29
	s_cbranch_scc0 .LBB0_926
	s_and_b64 vcc, exec, s[20:21]
	s_cbranch_vccz .LBB0_929
	s_barrier

; #define PG8_STAGE(bufoff, gbase, voff) do { _Pragma("unroll") for (int _i = 0; _i < 2; ++_i) \
;         __builtin_amdgcn_global_load_lds((const unsigned*)((const char*)(gbase) + (voff)[_i]), (LAS unsigned*)(lds + (bufoff) + ldsw + _i * 8192), 16, 0, 0); } while (0)
; #define PG8_LDA(dst, b, h) do { _Pragma("unroll") for (int m = 0; m < 4; ++m) _Pragma("unroll") for (int k = 0; k < 2; ++k) dst[m][k] = *(const LAS bf16x8*)(lds + PG8_SA(b, h) + aoff + m * 2048 + k * 1024); } while (0)
; #define PG8_LDB(dst, b, h) do { _Pragma("unroll") for (int n = 0; n < 2; ++n) _Pragma("unroll") for (int k = 0; k < 2; ++k) dst[n][k] = *(const LAS bf16x8*)(lds + PG8_SB(b, h) + boff + n * 2048 + k * 1024); } while (0)
; #define PG8_MMA(ai, bj, At, Bt) do { __builtin_amdgcn_s_setprio(1); _Pragma("unroll") for (int m = 0; m < 4; ++m) _Pragma("unroll") for (int n = 0; n < 2; ++n) _Pragma("unroll") for (int k = 0; k < 2; ++k) \
;         acc[ai][bj][m][n] = __builtin_amdgcn_mfma_f32_16x16x32_bf16(Bt[n][k], At[m][k], acc[ai][bj][m][n], 0, 0, 0); __builtin_amdgcn_s_setprio(0); } while (0)
; #define PG8_WAIT_V(n) asm volatile("s_waitcnt vmcnt(" #n ")" ::: "memory")
; #define PG8_WAIT_L(n) asm volatile("s_waitcnt lgkmcnt(" #n ")" ::: "memory")
; #define PG8_BAR __builtin_amdgcn_s_barrier()
; #define PG8_SCHED __builtin_amdgcn_sched_barrier(0)
; template <class Epi, bool ALIGN_EPI>
; __device__ __forceinline__ void gemm_phase(LAS unsigned char* lds, const Gemm g, const StaticOrder& S, const Epi& E) {
;     ...
;         for (int t = 0; t < nt; t += 2) {
;             const bool last = (t == nt - 2);
;             const char* a1 = cA + (size_t)(t + 1) * kstep;
;             const char* a2 = last ? nA : cA + (size_t)(t + 2) * kstep; const char* b2 = last ? nB : cB + (size_t)(t + 2) * kstep;
;             const char* a3 = a2 + kstep; const char* b3 = b2 + kstep;
;             PG8_LDB(B0, 0, 0); PG8_LDB(B1, 0, 1); PG8_SCHED; PG8_LDA(At, 0, 0); PG8_STAGE(PG8_SA(1, 1), a1 + hA, voffA);
;             PG8_WAIT_V(8); PG8_WAIT_L(0); PG8_BAR; PG8_MMA(0, 0, At, B0); PG8_MMA(0, 1, At, B1); PG8_BAR; PG8_SCHED;
;             PG8_LDA(At, 0, 1); PG8_STAGE(PG8_SB(0, 0), b2, voffB); PG8_STAGE(PG8_SB(0, 1), b2 + hB, voffB); PG8_STAGE(PG8_SA(0, 0), a2, voffA);
;             PG8_WAIT_V(8); PG8_WAIT_L(0); PG8_BAR; PG8_MMA(1, 0, At, B0); PG8_MMA(1, 1, At, B1); PG8_BAR; PG8_SCHED;
.LBB0_1005:
	ds_read_b128 v[128:131], v175
	ds_read_b128 v[132:135], v175 offset:1024
	ds_read_b128 v[136:139], v175 offset:2048
	ds_read_b128 v[140:143], v175 offset:3072
	ds_read_b128 v[160:163], v176
	ds_read_b128 v[164:167], v176 offset:1024
	ds_read_b128 v[168:171], v176 offset:2048
	ds_read_b128 v[180:183], v176 offset:3072
	s_add_u32 s40, s36, 0xffe00080
	s_addc_u32 s41, s37, -1
	s_cmpk_eq_i32 s57, 0x7c
	s_cselect_b32 s43, s25, s41
	s_cselect_b32 s42, s31, s40
	s_cselect_b32 s41, s23, s56
	s_cselect_b32 s40, s54, s55
	v_lshl_add_u64 v[218:219], s[36:37], 0, v[152:153]
	s_add_i32 m0, s35, 0xc000
	ds_read_b128 v[184:187], v177
	ds_read_b128 v[188:191], v177 offset:1024
	ds_read_b128 v[194:197], v177 offset:2048
	ds_read_b128 v[198:201], v177 offset:3072
	ds_read_b128 v[202:205], v177 offset:4096
	ds_read_b128 v[206:209], v177 offset:5120
	ds_read_b128 v[210:213], v177 offset:6144
	ds_read_b128 v[214:217], v177 offset:7168
	global_load_lds_dwordx4 v[218:219], off
	v_lshl_add_u64 v[218:219], s[36:37], 0, v[154:155]
	s_add_i32 m0, s35, 0xe000
	s_nop 0
	global_load_lds_dwordx4 v[218:219], off
	s_waitcnt vmcnt(8)
	s_waitcnt lgkmcnt(0)
	s_barrier
	s_setprio 1
	s_waitcnt lgkmcnt(0)
	v_mfma_f32_16x16x32_bf16 v[124:127], v[128:131], v[184:187], v[124:127]
	v_mfma_f32_16x16x32_bf16 v[124:127], v[132:135], v[188:191], v[124:127]
	v_mfma_f32_16x16x32_bf16 v[120:123], v[136:139], v[184:187], v[120:123]
	v_mfma_f32_16x16x32_bf16 v[120:123], v[140:143], v[188:191], v[120:123]
	v_mfma_f32_16x16x32_bf16 v[112:115], v[128:131], v[194:197], v[112:115]
	v_mfma_f32_16x16x32_bf16 v[112:115], v[132:135], v[198:201], v[112:115]
	v_mfma_f32_16x16x32_bf16 v[104:107], v[136:139], v[194:197], v[104:107]
	v_mfma_f32_16x16x32_bf16 v[104:107], v[140:143], v[198:201], v[104:107]
	v_mfma_f32_16x16x32_bf16 v[92:95], v[128:131], v[202:205], v[92:95]
	v_mfma_f32_16x16x32_bf16 v[92:95], v[132:135], v[206:209], v[92:95]
	v_mfma_f32_16x16x32_bf16 v[88:91], v[136:139], v[202:205], v[88:91]
	v_mfma_f32_16x16x32_bf16 v[88:91], v[140:143], v[206:209], v[88:91]
	v_mfma_f32_16x16x32_bf16 v[76:79], v[128:131], v[210:213], v[76:79]
	v_mfma_f32_16x16x32_bf16 v[76:79], v[132:135], v[214:217], v[76:79]
	v_mfma_f32_16x16x32_bf16 v[72:75], v[136:139], v[210:213], v[72:75]
	v_mfma_f32_16x16x32_bf16 v[72:75], v[140:143], v[214:217], v[72:75]
	s_setprio 0
	s_setprio 1
	v_mfma_f32_16x16x32_bf16 v[116:119], v[160:163], v[184:187], v[116:119]
	v_mfma_f32_16x16x32_bf16 v[116:119], v[164:167], v[188:191], v[116:119]
	v_mfma_f32_16x16x32_bf16 v[108:111], v[168:171], v[184:187], v[108:111]
	v_mfma_f32_16x16x32_bf16 v[108:111], v[180:183], v[188:191], v[108:111]
	v_mfma_f32_16x16x32_bf16 v[100:103], v[160:163], v[194:197], v[100:103]
	v_mfma_f32_16x16x32_bf16 v[100:103], v[164:167], v[198:201], v[100:103]
	v_mfma_f32_16x16x32_bf16 v[96:99], v[168:171], v[194:197], v[96:99]
	v_mfma_f32_16x16x32_bf16 v[96:99], v[180:183], v[198:201], v[96:99]
	v_mfma_f32_16x16x32_bf16 v[84:87], v[160:163], v[202:205], v[84:87]
	v_mfma_f32_16x16x32_bf16 v[84:87], v[164:167], v[206:209], v[84:87]
	v_mfma_f32_16x16x32_bf16 v[80:83], v[168:171], v[202:205], v[80:83]
	v_mfma_f32_16x16x32_bf16 v[80:83], v[180:183], v[206:209], v[80:83]
	s_barrier
	v_mfma_f32_16x16x32_bf16 v[68:71], v[160:163], v[210:213], v[68:71]
	v_mfma_f32_16x16x32_bf16 v[68:71], v[164:167], v[214:217], v[68:71]
	v_mfma_f32_16x16x32_bf16 v[64:67], v[168:171], v[210:213], v[64:67]
	v_mfma_f32_16x16x32_bf16 v[64:67], v[180:183], v[214:217], v[64:67]
	s_setprio 0
	s_add_i32 s58, s51, s33
	v_lshl_add_u64 v[218:219], s[40:41], 0, v[146:147]
	s_mov_b32 m0, s58
	ds_read_b128 v[184:187], v177 offset:16384
	ds_read_b128 v[188:191], v177 offset:17408
	ds_read_b128 v[194:197], v177 offset:18432
	ds_read_b128 v[198:201], v177 offset:19456
	ds_read_b128 v[202:205], v177 offset:20480
	ds_read_b128 v[206:209], v177 offset:21504
	ds_read_b128 v[210:213], v177 offset:22528
	ds_read_b128 v[214:217], v177 offset:23552
	global_load_lds_dwordx4 v[218:219], off
	s_add_i32 m0, s58, 0x2000
	s_add_u32 s58, s40, 0x200000
	v_lshl_add_u64 v[220:221], s[40:41], 0, v[150:151]
	s_addc_u32 s59, s41, 0
	s_add_i32 s60, s52, s33
	global_load_lds_dwordx4 v[220:221], off
	v_lshl_add_u64 v[222:223], s[58:59], 0, v[146:147]
	s_mov_b32 m0, s60
	v_lshl_add_u64 v[224:225], s[42:43], 0, v[148:149]
	global_load_lds_dwordx4 v[222:223], off
	v_lshl_add_u64 v[222:223], s[58:59], 0, v[150:151]
	s_add_i32 m0, s60, 0x2000
	s_nop 0
	global_load_lds_dwordx4 v[222:223], off
	v_lshl_add_u64 v[222:223], s[42:43], 0, v[144:145]
	s_mov_b32 m0, s35
	s_nop 0
	global_load_lds_dwordx4 v[222:223], off
	s_mov_b32 m0, s38
	s_nop 0
	global_load_lds_dwordx4 v[224:225], off
	s_waitcnt vmcnt(8)
	s_waitcnt lgkmcnt(0)
	s_barrier
; #define PG8_STAGE(bufoff, gbase, voff) do { _Pragma("unroll") for (int _i = 0; _i < 2; ++_i) \
;         __builtin_amdgcn_global_load_lds((const unsigned*)((const char*)(gbase) + (voff)[_i]), (LAS unsigned*)(lds + (bufoff) + ldsw + _i * 8192), 16, 0, 0); } while (0)
; #define PG8_LDA(dst, b, h) do { _Pragma("unroll") for (int m = 0; m < 4; ++m) _Pragma("unroll") for (int k = 0; k < 2; ++k) dst[m][k] = *(const LAS bf16x8*)(lds + PG8_SA(b, h) + aoff + m * 2048 + k * 1024); } while (0)
; #define PG8_LDB(dst, b, h) do { _Pragma("unroll") for (int n = 0; n < 2; ++n) _Pragma("unroll") for (int k = 0; k < 2; ++k) dst[n][k] = *(const LAS bf16x8*)(lds + PG8_SB(b, h) + boff + n * 2048 + k * 1024); } while (0)
; #define PG8_MMA(ai, bj, At, Bt) do { __builtin_amdgcn_s_setprio(1); _Pragma("unroll") for (int m = 0; m < 4; ++m) _Pragma("unroll") for (int n = 0; n < 2; ++n) _Pragma("unroll") for (int k = 0; k < 2; ++k) \
;         acc[ai][bj][m][n] = __builtin_amdgcn_mfma_f32_16x16x32_bf16(Bt[n][k], At[m][k], acc[ai][bj][m][n], 0, 0, 0); __builtin_amdgcn_s_setprio(0); } while (0)
; #define PG8_WAIT_V(n) asm volatile("s_waitcnt vmcnt(" #n ")" ::: "memory")
; #define PG8_WAIT_L(n) asm volatile("s_waitcnt lgkmcnt(" #n ")" ::: "memory")
; #define PG8_BAR __builtin_amdgcn_s_barrier()
; #define PG8_SCHED __builtin_amdgcn_sched_barrier(0)
; template <class Epi, bool ALIGN_EPI>
; __device__ __forceinline__ void gemm_phase(LAS unsigned char* lds, const Gemm g, const StaticOrder& S, const Epi& E) {
;     ...
;             PG8_WAIT_V(8); PG8_WAIT_L(0); PG8_BAR; PG8_MMA(1, 0, At, B0); PG8_MMA(1, 1, At, B1); PG8_BAR; PG8_SCHED;
;             PG8_LDB(B0, 1, 0); PG8_LDB(B1, 1, 1); PG8_SCHED; PG8_LDA(At, 1, 0); PG8_STAGE(PG8_SA(0, 1), a2 + hA, voffA);
;             PG8_WAIT_V(8); PG8_WAIT_L(0); PG8_BAR; PG8_MMA(0, 0, At, B0); PG8_MMA(0, 1, At, B1); PG8_BAR; PG8_SCHED;
;             PG8_LDA(At, 1, 1); PG8_STAGE(PG8_SB(1, 0), b3, voffB); PG8_STAGE(PG8_SB(1, 1), b3 + hB, voffB); PG8_STAGE(PG8_SA(1, 0), a3, voffA);
	s_setprio 1
	s_waitcnt lgkmcnt(0)
	v_mfma_f32_16x16x32_bf16 v[60:63], v[128:131], v[184:187], v[60:63]
	v_mfma_f32_16x16x32_bf16 v[60:63], v[132:135], v[188:191], v[60:63]
	v_mfma_f32_16x16x32_bf16 v[56:59], v[136:139], v[184:187], v[56:59]
	v_mfma_f32_16x16x32_bf16 v[56:59], v[140:143], v[188:191], v[56:59]
	v_mfma_f32_16x16x32_bf16 v[44:47], v[128:131], v[194:197], v[44:47]
	v_mfma_f32_16x16x32_bf16 v[44:47], v[132:135], v[198:201], v[44:47]
	v_mfma_f32_16x16x32_bf16 v[40:43], v[136:139], v[194:197], v[40:43]
	v_mfma_f32_16x16x32_bf16 v[40:43], v[140:143], v[198:201], v[40:43]
	v_mfma_f32_16x16x32_bf16 v[28:31], v[128:131], v[202:205], v[28:31]
	v_mfma_f32_16x16x32_bf16 v[28:31], v[132:135], v[206:209], v[28:31]
	v_mfma_f32_16x16x32_bf16 v[24:27], v[136:139], v[202:205], v[24:27]
	v_mfma_f32_16x16x32_bf16 v[24:27], v[140:143], v[206:209], v[24:27]
	v_mfma_f32_16x16x32_bf16 v[12:15], v[128:131], v[210:213], v[12:15]
	v_mfma_f32_16x16x32_bf16 v[12:15], v[132:135], v[214:217], v[12:15]
	v_mfma_f32_16x16x32_bf16 v[8:11], v[136:139], v[210:213], v[8:11]
	v_mfma_f32_16x16x32_bf16 v[8:11], v[140:143], v[214:217], v[8:11]
	s_setprio 0
	s_setprio 1
	v_mfma_f32_16x16x32_bf16 v[52:55], v[160:163], v[184:187], v[52:55]
	v_mfma_f32_16x16x32_bf16 v[52:55], v[164:167], v[188:191], v[52:55]
	v_mfma_f32_16x16x32_bf16 v[48:51], v[168:171], v[184:187], v[48:51]
	v_mfma_f32_16x16x32_bf16 v[48:51], v[180:183], v[188:191], v[48:51]
	v_mfma_f32_16x16x32_bf16 v[36:39], v[160:163], v[194:197], v[36:39]
	v_mfma_f32_16x16x32_bf16 v[36:39], v[164:167], v[198:201], v[36:39]
	v_mfma_f32_16x16x32_bf16 v[32:35], v[168:171], v[194:197], v[32:35]
	v_mfma_f32_16x16x32_bf16 v[32:35], v[180:183], v[198:201], v[32:35]
	v_mfma_f32_16x16x32_bf16 v[20:23], v[160:163], v[202:205], v[20:23]
	v_mfma_f32_16x16x32_bf16 v[20:23], v[164:167], v[206:209], v[20:23]
	v_mfma_f32_16x16x32_bf16 v[16:19], v[168:171], v[202:205], v[16:19]
	v_mfma_f32_16x16x32_bf16 v[16:19], v[180:183], v[206:209], v[16:19]
	s_barrier
	v_mfma_f32_16x16x32_bf16 v[4:7], v[160:163], v[210:213], v[4:7]
	v_mfma_f32_16x16x32_bf16 v[4:7], v[164:167], v[214:217], v[4:7]
	v_mfma_f32_16x16x32_bf16 v[0:3], v[168:171], v[210:213], v[0:3]
	v_mfma_f32_16x16x32_bf16 v[0:3], v[180:183], v[214:217], v[0:3]
	s_setprio 0
	s_add_i32 s58, 0, 0x18000
	s_add_i32 s59, 0, 0x1c000
	v_add_u32_e32 v140, s58, v173
	v_add_u32_e32 v179, s59, v173
	ds_read_b128 v[128:131], v140
	ds_read_b128 v[132:135], v140 offset:1024
	ds_read_b128 v[136:139], v140 offset:2048
	ds_read_b128 v[140:143], v140 offset:3072
	ds_read_b128 v[160:163], v179
	ds_read_b128 v[164:167], v179 offset:1024
	ds_read_b128 v[168:171], v179 offset:2048
	ds_read_b128 v[180:183], v179 offset:3072
	s_add_u32 s42, s42, 0x200000
	s_addc_u32 s43, s43, 0
	s_mov_b32 m0, s39
	v_lshl_add_u64 v[226:227], s[42:43], 0, v[144:145]
	ds_read_b128 v[184:187], v177 offset:32768
	ds_read_b128 v[188:191], v177 offset:33792
	ds_read_b128 v[194:197], v177 offset:34816
	ds_read_b128 v[198:201], v177 offset:35840
	ds_read_b128 v[202:205], v177 offset:36864
	ds_read_b128 v[206:209], v177 offset:37888
	ds_read_b128 v[210:213], v177 offset:38912
	ds_read_b128 v[214:217], v177 offset:39936
	global_load_lds_dwordx4 v[226:227], off
	v_lshl_add_u64 v[226:227], s[42:43], 0, v[148:149]
	s_mov_b32 m0, s44
	s_nop 0
	global_load_lds_dwordx4 v[226:227], off
	s_waitcnt vmcnt(8)
	s_waitcnt lgkmcnt(0)
	s_barrier
	s_setprio 1
	s_waitcnt lgkmcnt(0)
	v_mfma_f32_16x16x32_bf16 v[124:127], v[128:131], v[184:187], v[124:127]
	v_mfma_f32_16x16x32_bf16 v[124:127], v[132:135], v[188:191], v[124:127]
	v_mfma_f32_16x16x32_bf16 v[120:123], v[136:139], v[184:187], v[120:123]
	v_mfma_f32_16x16x32_bf16 v[120:123], v[140:143], v[188:191], v[120:123]
	v_mfma_f32_16x16x32_bf16 v[112:115], v[128:131], v[194:197], v[112:115]
	v_mfma_f32_16x16x32_bf16 v[112:115], v[132:135], v[198:201], v[112:115]
	v_mfma_f32_16x16x32_bf16 v[104:107], v[136:139], v[194:197], v[104:107]
	v_mfma_f32_16x16x32_bf16 v[104:107], v[140:143], v[198:201], v[104:107]
	v_mfma_f32_16x16x32_bf16 v[92:95], v[128:131], v[202:205], v[92:95]
	v_mfma_f32_16x16x32_bf16 v[92:95], v[132:135], v[206:209], v[92:95]
	v_mfma_f32_16x16x32_bf16 v[88:91], v[136:139], v[202:205], v[88:91]
	v_mfma_f32_16x16x32_bf16 v[88:91], v[140:143], v[206:209], v[88:91]
	v_mfma_f32_16x16x32_bf16 v[76:79], v[128:131], v[210:213], v[76:79]
	v_mfma_f32_16x16x32_bf16 v[76:79], v[132:135], v[214:217], v[76:79]
	v_mfma_f32_16x16x32_bf16 v[72:75], v[136:139], v[210:213], v[72:75]
	v_mfma_f32_16x16x32_bf16 v[72:75], v[140:143], v[214:217], v[72:75]
	s_setprio 0
	s_setprio 1
	v_mfma_f32_16x16x32_bf16 v[116:119], v[160:163], v[184:187], v[116:119]
	v_mfma_f32_16x16x32_bf16 v[116:119], v[164:167], v[188:191], v[116:119]
	v_mfma_f32_16x16x32_bf16 v[108:111], v[168:171], v[184:187], v[108:111]
	v_mfma_f32_16x16x32_bf16 v[108:111], v[180:183], v[188:191], v[108:111]
	v_mfma_f32_16x16x32_bf16 v[100:103], v[160:163], v[194:197], v[100:103]
	v_mfma_f32_16x16x32_bf16 v[100:103], v[164:167], v[198:201], v[100:103]
	v_mfma_f32_16x16x32_bf16 v[96:99], v[168:171], v[194:197], v[96:99]
	v_mfma_f32_16x16x32_bf16 v[96:99], v[180:183], v[198:201], v[96:99]
	v_mfma_f32_16x16x32_bf16 v[84:87], v[160:163], v[202:205], v[84:87]
	v_mfma_f32_16x16x32_bf16 v[84:87], v[164:167], v[206:209], v[84:87]
	v_mfma_f32_16x16x32_bf16 v[80:83], v[168:171], v[202:205], v[80:83]
	v_mfma_f32_16x16x32_bf16 v[80:83], v[180:183], v[206:209], v[80:83]
	s_barrier
; #define PG8_STAGE(bufoff, gbase, voff) do { _Pragma("unroll") for (int _i = 0; _i < 2; ++_i) \
;         __builtin_amdgcn_global_load_lds((const unsigned*)((const char*)(gbase) + (voff)[_i]), (LAS unsigned*)(lds + (bufoff) + ldsw + _i * 8192), 16, 0, 0); } while (0)
; #define PG8_LDA(dst, b, h) do { _Pragma("unroll") for (int m = 0; m < 4; ++m) _Pragma("unroll") for (int k = 0; k < 2; ++k) dst[m][k] = *(const LAS bf16x8*)(lds + PG8_SA(b, h) + aoff + m * 2048 + k * 1024); } while (0)
; #define PG8_MMA(ai, bj, At, Bt) do { __builtin_amdgcn_s_setprio(1); _Pragma("unroll") for (int m = 0; m < 4; ++m) _Pragma("unroll") for (int n = 0; n < 2; ++n) _Pragma("unroll") for (int k = 0; k < 2; ++k) \
;         acc[ai][bj][m][n] = __builtin_amdgcn_mfma_f32_16x16x32_bf16(Bt[n][k], At[m][k], acc[ai][bj][m][n], 0, 0, 0); __builtin_amdgcn_s_setprio(0); } while (0)
; #define PG8_WAIT_V(n) asm volatile("s_waitcnt vmcnt(" #n ")" ::: "memory")
; #define PG8_WAIT_L(n) asm volatile("s_waitcnt lgkmcnt(" #n ")" ::: "memory")
; #define PG8_BAR __builtin_amdgcn_s_barrier()
; #define PG8_SCHED __builtin_amdgcn_sched_barrier(0)
; template <class Epi, bool ALIGN_EPI>
; __device__ __forceinline__ void gemm_phase(LAS unsigned char* lds, const Gemm g, const StaticOrder& S, const Epi& E) {
;     ...
;             PG8_WAIT_V(8); PG8_WAIT_L(0); PG8_BAR; PG8_MMA(0, 0, At, B0); PG8_MMA(0, 1, At, B1); PG8_BAR; PG8_SCHED;
;             PG8_LDA(At, 1, 1); PG8_STAGE(PG8_SB(1, 0), b3, voffB); PG8_STAGE(PG8_SB(1, 1), b3 + hB, voffB); PG8_STAGE(PG8_SA(1, 0), a3, voffA);
;             PG8_WAIT_V(8); PG8_WAIT_L(0); PG8_BAR; PG8_MMA(1, 0, At, B0); PG8_MMA(1, 1, At, B1); PG8_BAR; PG8_SCHED;
;         }
;         if constexpr (ALIGN_EPI) { if (wr == 0) PG8_BAR; }
	v_mfma_f32_16x16x32_bf16 v[68:71], v[160:163], v[210:213], v[68:71]
	v_mfma_f32_16x16x32_bf16 v[68:71], v[164:167], v[214:217], v[68:71]
	v_mfma_f32_16x16x32_bf16 v[64:67], v[168:171], v[210:213], v[64:67]
	v_mfma_f32_16x16x32_bf16 v[64:67], v[180:183], v[214:217], v[64:67]
	s_setprio 0
	s_add_i32 s42, s58, s33
	v_lshl_add_u64 v[218:219], v[218:219], 0, s[16:17]
	s_mov_b32 m0, s42
	ds_read_b128 v[184:187], v177 offset:49152
	ds_read_b128 v[188:191], v177 offset:50176
	ds_read_b128 v[194:197], v177 offset:51200
	ds_read_b128 v[198:201], v177 offset:52224
	ds_read_b128 v[202:205], v177 offset:53248
	ds_read_b128 v[206:209], v177 offset:54272
	ds_read_b128 v[210:213], v177 offset:55296
	ds_read_b128 v[214:217], v177 offset:56320
	global_load_lds_dwordx4 v[218:219], off
	s_add_i32 m0, s42, 0x2000
	s_add_u32 s40, s40, 0x200080
	v_lshl_add_u64 v[218:219], v[220:221], 0, s[16:17]
	s_addc_u32 s41, s41, 0
	s_add_i32 s42, s59, s33
	global_load_lds_dwordx4 v[218:219], off
	v_lshl_add_u64 v[218:219], s[40:41], 0, v[146:147]
	s_mov_b32 m0, s42
	s_nop 0
	global_load_lds_dwordx4 v[218:219], off
	v_lshl_add_u64 v[218:219], s[40:41], 0, v[150:151]
	s_add_i32 m0, s42, 0x2000
	s_nop 0
	global_load_lds_dwordx4 v[218:219], off
	v_lshl_add_u64 v[218:219], v[222:223], 0, s[16:17]
	s_mov_b32 m0, s48
	s_nop 0
	global_load_lds_dwordx4 v[218:219], off
	v_lshl_add_u64 v[218:219], v[224:225], 0, s[16:17]
	s_mov_b32 m0, s49
	s_nop 0
	global_load_lds_dwordx4 v[218:219], off
	s_waitcnt vmcnt(8)
	s_waitcnt lgkmcnt(0)
	s_barrier
	s_setprio 1
	s_waitcnt lgkmcnt(0)
	v_mfma_f32_16x16x32_bf16 v[60:63], v[128:131], v[184:187], v[60:63]
	v_mfma_f32_16x16x32_bf16 v[60:63], v[132:135], v[188:191], v[60:63]
	v_mfma_f32_16x16x32_bf16 v[56:59], v[136:139], v[184:187], v[56:59]
	v_mfma_f32_16x16x32_bf16 v[56:59], v[140:143], v[188:191], v[56:59]
	v_mfma_f32_16x16x32_bf16 v[44:47], v[128:131], v[194:197], v[44:47]
	v_mfma_f32_16x16x32_bf16 v[44:47], v[132:135], v[198:201], v[44:47]
	v_mfma_f32_16x16x32_bf16 v[40:43], v[136:139], v[194:197], v[40:43]
	v_mfma_f32_16x16x32_bf16 v[40:43], v[140:143], v[198:201], v[40:43]
	v_mfma_f32_16x16x32_bf16 v[28:31], v[128:131], v[202:205], v[28:31]
	v_mfma_f32_16x16x32_bf16 v[28:31], v[132:135], v[206:209], v[28:31]
	v_mfma_f32_16x16x32_bf16 v[24:27], v[136:139], v[202:205], v[24:27]
	v_mfma_f32_16x16x32_bf16 v[24:27], v[140:143], v[206:209], v[24:27]
	v_mfma_f32_16x16x32_bf16 v[12:15], v[128:131], v[210:213], v[12:15]
	v_mfma_f32_16x16x32_bf16 v[12:15], v[132:135], v[214:217], v[12:15]
	v_mfma_f32_16x16x32_bf16 v[8:11], v[136:139], v[210:213], v[8:11]
	v_mfma_f32_16x16x32_bf16 v[8:11], v[140:143], v[214:217], v[8:11]
	s_setprio 0
	s_setprio 1
	v_mfma_f32_16x16x32_bf16 v[52:55], v[160:163], v[184:187], v[52:55]
	v_mfma_f32_16x16x32_bf16 v[52:55], v[164:167], v[188:191], v[52:55]
	v_mfma_f32_16x16x32_bf16 v[48:51], v[168:171], v[184:187], v[48:51]
	v_mfma_f32_16x16x32_bf16 v[48:51], v[180:183], v[188:191], v[48:51]
	v_mfma_f32_16x16x32_bf16 v[36:39], v[160:163], v[194:197], v[36:39]
	v_mfma_f32_16x16x32_bf16 v[36:39], v[164:167], v[198:201], v[36:39]
	v_mfma_f32_16x16x32_bf16 v[32:35], v[168:171], v[194:197], v[32:35]
	v_mfma_f32_16x16x32_bf16 v[32:35], v[180:183], v[198:201], v[32:35]
	v_mfma_f32_16x16x32_bf16 v[20:23], v[160:163], v[202:205], v[20:23]
	v_mfma_f32_16x16x32_bf16 v[20:23], v[164:167], v[206:209], v[20:23]
	v_mfma_f32_16x16x32_bf16 v[16:19], v[168:171], v[202:205], v[16:19]
	v_mfma_f32_16x16x32_bf16 v[16:19], v[180:183], v[206:209], v[16:19]
	s_barrier
	v_mfma_f32_16x16x32_bf16 v[4:7], v[160:163], v[210:213], v[4:7]
	v_mfma_f32_16x16x32_bf16 v[4:7], v[164:167], v[214:217], v[4:7]
	v_mfma_f32_16x16x32_bf16 v[0:3], v[168:171], v[210:213], v[0:3]
	v_mfma_f32_16x16x32_bf16 v[0:3], v[180:183], v[214:217], v[0:3]
	s_setprio 0
	s_add_i32 s57, s57, 2
	s_add_u32 s36, s36, 0x100
	s_addc_u32 s37, s37, 0
	s_add_u32 s55, s55, 0x100
	s_addc_u32 s56, s56, 0
	s_cmpk_gt_u32 s57, 0x7d
	s_cbranch_scc0 .LBB0_1005
	s_and_b64 vcc, exec, s[18:19]
	s_cbranch_vccz .LBB0_1008
	s_barrier

; #define PG8_STAGE(bufoff, gbase, voff) do { _Pragma("unroll") for (int _i = 0; _i < 2; ++_i) \
;         __builtin_amdgcn_global_load_lds((const unsigned*)((const char*)(gbase) + (voff)[_i]), (LAS unsigned*)(lds + (bufoff) + ldsw + _i * 8192), 16, 0, 0); } while (0)
; #define PG8_LDA(dst, b, h) do { _Pragma("unroll") for (int m = 0; m < 4; ++m) _Pragma("unroll") for (int k = 0; k < 2; ++k) dst[m][k] = *(const LAS bf16x8*)(lds + PG8_SA(b, h) + aoff + m * 2048 + k * 1024); } while (0)
; #define PG8_LDB(dst, b, h) do { _Pragma("unroll") for (int n = 0; n < 2; ++n) _Pragma("unroll") for (int k = 0; k < 2; ++k) dst[n][k] = *(const LAS bf16x8*)(lds + PG8_SB(b, h) + boff + n * 2048 + k * 1024); } while (0)
; #define PG8_MMA(ai, bj, At, Bt) do { __builtin_amdgcn_s_setprio(1); _Pragma("unroll") for (int m = 0; m < 4; ++m) _Pragma("unroll") for (int n = 0; n < 2; ++n) _Pragma("unroll") for (int k = 0; k < 2; ++k) \
;         acc[ai][bj][m][n] = __builtin_amdgcn_mfma_f32_16x16x32_bf16(Bt[n][k], At[m][k], acc[ai][bj][m][n], 0, 0, 0); __builtin_amdgcn_s_setprio(0); } while (0)
; #define PG8_WAIT_V(n) asm volatile("s_waitcnt vmcnt(" #n ")" ::: "memory")
; #define PG8_WAIT_L(n) asm volatile("s_waitcnt lgkmcnt(" #n ")" ::: "memory")
; #define PG8_BAR __builtin_amdgcn_s_barrier()
; #define PG8_SCHED __builtin_amdgcn_sched_barrier(0)
; template <class Epi, bool ALIGN_EPI>
; __device__ __forceinline__ void gemm_phase(LAS unsigned char* lds, const Gemm g, const StaticOrder& S, const Epi& E) {
;     ...
;         for (int t = 0; t < nt; t += 2) {
;             const bool last = (t == nt - 2);
;             const char* a1 = cA + (size_t)(t + 1) * kstep;
;             const char* a2 = last ? nA : cA + (size_t)(t + 2) * kstep; const char* b2 = last ? nB : cB + (size_t)(t + 2) * kstep;
;             const char* a3 = a2 + kstep; const char* b3 = b2 + kstep;
;             PG8_LDB(B0, 0, 0); PG8_LDB(B1, 0, 1); PG8_SCHED; PG8_LDA(At, 0, 0); PG8_STAGE(PG8_SA(1, 1), a1 + hA, voffA);
;             PG8_WAIT_V(8); PG8_WAIT_L(0); PG8_BAR; PG8_MMA(0, 0, At, B0); PG8_MMA(0, 1, At, B1); PG8_BAR; PG8_SCHED;
;             PG8_LDA(At, 0, 1); PG8_STAGE(PG8_SB(0, 0), b2, voffB); PG8_STAGE(PG8_SB(0, 1), b2 + hB, voffB); PG8_STAGE(PG8_SA(0, 0), a2, voffA);
;             PG8_WAIT_V(8); PG8_WAIT_L(0); PG8_BAR; PG8_MMA(1, 0, At, B0); PG8_MMA(1, 1, At, B1); PG8_BAR; PG8_SCHED;
.LBB0_1094:
	ds_read_b128 v[146:149], v153
	ds_read_b128 v[174:177], v153 offset:1024
	ds_read_b128 v[178:181], v153 offset:2048
	ds_read_b128 v[182:185], v153 offset:3072
	ds_read_b128 v[186:189], v154
	ds_read_b128 v[194:197], v154 offset:1024
	ds_read_b128 v[198:201], v154 offset:2048
	ds_read_b128 v[202:205], v154 offset:3072
	s_add_u32 s36, s4, 0xfff80080
	s_addc_u32 s37, s5, -1
	s_cmp_eq_u32 s38, 28
	s_cselect_b32 s45, s0, s37
	s_cselect_b32 s44, s1, s36
	s_cselect_b32 s37, s2, s29
	s_cselect_b32 s36, s3, s27
	v_lshl_add_u64 v[190:191], s[4:5], 0, v[136:137]
	s_add_i32 m0, s41, 0xc000
	ds_read_b128 v[206:209], v155
	ds_read_b128 v[210:213], v155 offset:1024
	ds_read_b128 v[214:217], v155 offset:2048
	ds_read_b128 v[218:221], v155 offset:3072
	ds_read_b128 v[222:225], v155 offset:4096
	ds_read_b128 v[226:229], v155 offset:5120
	ds_read_b128 v[230:233], v155 offset:6144
	ds_read_b128 v[234:237], v155 offset:7168
	global_load_lds_dwordx4 v[190:191], off
	v_lshl_add_u64 v[190:191], s[4:5], 0, v[138:139]
	s_add_i32 m0, s41, 0xe000
	s_nop 0
	global_load_lds_dwordx4 v[190:191], off
	s_waitcnt vmcnt(8)
	s_waitcnt lgkmcnt(0)
	s_barrier
	s_setprio 1
	s_waitcnt lgkmcnt(0)
	v_mfma_f32_16x16x32_bf16 v[124:127], v[146:149], v[206:209], v[124:127]
	v_mfma_f32_16x16x32_bf16 v[124:127], v[174:177], v[210:213], v[124:127]
	v_mfma_f32_16x16x32_bf16 v[120:123], v[178:181], v[206:209], v[120:123]
	v_mfma_f32_16x16x32_bf16 v[120:123], v[182:185], v[210:213], v[120:123]
	v_mfma_f32_16x16x32_bf16 v[108:111], v[146:149], v[214:217], v[108:111]
	v_mfma_f32_16x16x32_bf16 v[108:111], v[174:177], v[218:221], v[108:111]
	v_mfma_f32_16x16x32_bf16 v[104:107], v[178:181], v[214:217], v[104:107]
	v_mfma_f32_16x16x32_bf16 v[104:107], v[182:185], v[218:221], v[104:107]
	v_mfma_f32_16x16x32_bf16 v[92:95], v[146:149], v[222:225], v[92:95]
	v_mfma_f32_16x16x32_bf16 v[92:95], v[174:177], v[226:229], v[92:95]
	v_mfma_f32_16x16x32_bf16 v[88:91], v[178:181], v[222:225], v[88:91]
	v_mfma_f32_16x16x32_bf16 v[88:91], v[182:185], v[226:229], v[88:91]
	v_mfma_f32_16x16x32_bf16 v[76:79], v[146:149], v[230:233], v[76:79]
	v_mfma_f32_16x16x32_bf16 v[76:79], v[174:177], v[234:237], v[76:79]
	v_mfma_f32_16x16x32_bf16 v[72:75], v[178:181], v[230:233], v[72:75]
	v_mfma_f32_16x16x32_bf16 v[72:75], v[182:185], v[234:237], v[72:75]
	s_setprio 0
	s_setprio 1
	v_mfma_f32_16x16x32_bf16 v[116:119], v[186:189], v[206:209], v[116:119]
	v_mfma_f32_16x16x32_bf16 v[116:119], v[194:197], v[210:213], v[116:119]
	v_mfma_f32_16x16x32_bf16 v[112:115], v[198:201], v[206:209], v[112:115]
	v_mfma_f32_16x16x32_bf16 v[112:115], v[202:205], v[210:213], v[112:115]
	v_mfma_f32_16x16x32_bf16 v[100:103], v[186:189], v[214:217], v[100:103]
	v_mfma_f32_16x16x32_bf16 v[100:103], v[194:197], v[218:221], v[100:103]
	v_mfma_f32_16x16x32_bf16 v[96:99], v[198:201], v[214:217], v[96:99]
	v_mfma_f32_16x16x32_bf16 v[96:99], v[202:205], v[218:221], v[96:99]
	v_mfma_f32_16x16x32_bf16 v[84:87], v[186:189], v[222:225], v[84:87]
	v_mfma_f32_16x16x32_bf16 v[84:87], v[194:197], v[226:229], v[84:87]
	v_mfma_f32_16x16x32_bf16 v[80:83], v[198:201], v[222:225], v[80:83]
	v_mfma_f32_16x16x32_bf16 v[80:83], v[202:205], v[226:229], v[80:83]
	s_barrier
	v_mfma_f32_16x16x32_bf16 v[68:71], v[186:189], v[230:233], v[68:71]
	v_mfma_f32_16x16x32_bf16 v[68:71], v[194:197], v[234:237], v[68:71]
	v_mfma_f32_16x16x32_bf16 v[64:67], v[198:201], v[230:233], v[64:67]
	v_mfma_f32_16x16x32_bf16 v[64:67], v[202:205], v[234:237], v[64:67]
	s_setprio 0
	s_add_i32 s39, s61, s51
	v_lshl_add_u64 v[190:191], s[36:37], 0, v[130:131]
	s_mov_b32 m0, s39
	ds_read_b128 v[206:209], v155 offset:16384
	ds_read_b128 v[210:213], v155 offset:17408
	ds_read_b128 v[214:217], v155 offset:18432
	ds_read_b128 v[218:221], v155 offset:19456
	ds_read_b128 v[222:225], v155 offset:20480
	ds_read_b128 v[226:229], v155 offset:21504
	ds_read_b128 v[230:233], v155 offset:22528
	ds_read_b128 v[234:237], v155 offset:23552
	global_load_lds_dwordx4 v[190:191], off
	s_add_i32 m0, s39, 0x2000
	s_add_u32 s46, s36, 0x80000
	v_lshl_add_u64 v[238:239], s[36:37], 0, v[134:135]
	s_addc_u32 s47, s37, 0
	s_add_i32 s39, s62, s51
	global_load_lds_dwordx4 v[238:239], off
	v_lshl_add_u64 v[240:241], s[46:47], 0, v[130:131]
	s_mov_b32 m0, s39
	v_lshl_add_u64 v[242:243], s[44:45], 0, v[132:133]
	global_load_lds_dwordx4 v[240:241], off
	v_lshl_add_u64 v[240:241], s[46:47], 0, v[134:135]
	s_add_i32 m0, s39, 0x2000
	s_nop 0
	global_load_lds_dwordx4 v[240:241], off
	v_lshl_add_u64 v[240:241], s[44:45], 0, v[128:129]
	s_mov_b32 m0, s41
	s_nop 0
	global_load_lds_dwordx4 v[240:241], off
	s_mov_b32 m0, s43
	s_nop 0
	global_load_lds_dwordx4 v[242:243], off
	s_waitcnt vmcnt(8)
	s_waitcnt lgkmcnt(0)
	s_barrier
; #define PG8_STAGE(bufoff, gbase, voff) do { _Pragma("unroll") for (int _i = 0; _i < 2; ++_i) \
;         __builtin_amdgcn_global_load_lds((const unsigned*)((const char*)(gbase) + (voff)[_i]), (LAS unsigned*)(lds + (bufoff) + ldsw + _i * 8192), 16, 0, 0); } while (0)
; #define PG8_LDA(dst, b, h) do { _Pragma("unroll") for (int m = 0; m < 4; ++m) _Pragma("unroll") for (int k = 0; k < 2; ++k) dst[m][k] = *(const LAS bf16x8*)(lds + PG8_SA(b, h) + aoff + m * 2048 + k * 1024); } while (0)
; #define PG8_LDB(dst, b, h) do { _Pragma("unroll") for (int n = 0; n < 2; ++n) _Pragma("unroll") for (int k = 0; k < 2; ++k) dst[n][k] = *(const LAS bf16x8*)(lds + PG8_SB(b, h) + boff + n * 2048 + k * 1024); } while (0)
; #define PG8_MMA(ai, bj, At, Bt) do { __builtin_amdgcn_s_setprio(1); _Pragma("unroll") for (int m = 0; m < 4; ++m) _Pragma("unroll") for (int n = 0; n < 2; ++n) _Pragma("unroll") for (int k = 0; k < 2; ++k) \
;         acc[ai][bj][m][n] = __builtin_amdgcn_mfma_f32_16x16x32_bf16(Bt[n][k], At[m][k], acc[ai][bj][m][n], 0, 0, 0); __builtin_amdgcn_s_setprio(0); } while (0)
; #define PG8_WAIT_V(n) asm volatile("s_waitcnt vmcnt(" #n ")" ::: "memory")
; #define PG8_WAIT_L(n) asm volatile("s_waitcnt lgkmcnt(" #n ")" ::: "memory")
; #define PG8_BAR __builtin_amdgcn_s_barrier()
; #define PG8_SCHED __builtin_amdgcn_sched_barrier(0)
; template <class Epi, bool ALIGN_EPI>
; __device__ __forceinline__ void gemm_phase(LAS unsigned char* lds, const Gemm g, const StaticOrder& S, const Epi& E) {
;     ...
;             PG8_WAIT_V(8); PG8_WAIT_L(0); PG8_BAR; PG8_MMA(1, 0, At, B0); PG8_MMA(1, 1, At, B1); PG8_BAR; PG8_SCHED;
;             PG8_LDB(B0, 1, 0); PG8_LDB(B1, 1, 1); PG8_SCHED; PG8_LDA(At, 1, 0); PG8_STAGE(PG8_SA(0, 1), a2 + hA, voffA);
;             PG8_WAIT_V(8); PG8_WAIT_L(0); PG8_BAR; PG8_MMA(0, 0, At, B0); PG8_MMA(0, 1, At, B1); PG8_BAR; PG8_SCHED;
;             PG8_LDA(At, 1, 1); PG8_STAGE(PG8_SB(1, 0), b3, voffB); PG8_STAGE(PG8_SB(1, 1), b3 + hB, voffB); PG8_STAGE(PG8_SA(1, 0), a3, voffA);
	s_setprio 1
	s_waitcnt lgkmcnt(0)
	v_mfma_f32_16x16x32_bf16 v[60:63], v[146:149], v[206:209], v[60:63]
	v_mfma_f32_16x16x32_bf16 v[60:63], v[174:177], v[210:213], v[60:63]
	v_mfma_f32_16x16x32_bf16 v[56:59], v[178:181], v[206:209], v[56:59]
	v_mfma_f32_16x16x32_bf16 v[56:59], v[182:185], v[210:213], v[56:59]
	v_mfma_f32_16x16x32_bf16 v[44:47], v[146:149], v[214:217], v[44:47]
	v_mfma_f32_16x16x32_bf16 v[44:47], v[174:177], v[218:221], v[44:47]
	v_mfma_f32_16x16x32_bf16 v[40:43], v[178:181], v[214:217], v[40:43]
	v_mfma_f32_16x16x32_bf16 v[40:43], v[182:185], v[218:221], v[40:43]
	v_mfma_f32_16x16x32_bf16 v[28:31], v[146:149], v[222:225], v[28:31]
	v_mfma_f32_16x16x32_bf16 v[28:31], v[174:177], v[226:229], v[28:31]
	v_mfma_f32_16x16x32_bf16 v[24:27], v[178:181], v[222:225], v[24:27]
	v_mfma_f32_16x16x32_bf16 v[24:27], v[182:185], v[226:229], v[24:27]
	v_mfma_f32_16x16x32_bf16 v[12:15], v[146:149], v[230:233], v[12:15]
	v_mfma_f32_16x16x32_bf16 v[12:15], v[174:177], v[234:237], v[12:15]
	v_mfma_f32_16x16x32_bf16 v[8:11], v[178:181], v[230:233], v[8:11]
	v_mfma_f32_16x16x32_bf16 v[8:11], v[182:185], v[234:237], v[8:11]
	s_setprio 0
	s_setprio 1
	v_mfma_f32_16x16x32_bf16 v[52:55], v[186:189], v[206:209], v[52:55]
	v_mfma_f32_16x16x32_bf16 v[52:55], v[194:197], v[210:213], v[52:55]
	v_mfma_f32_16x16x32_bf16 v[48:51], v[198:201], v[206:209], v[48:51]
	v_mfma_f32_16x16x32_bf16 v[48:51], v[202:205], v[210:213], v[48:51]
	v_mfma_f32_16x16x32_bf16 v[36:39], v[186:189], v[214:217], v[36:39]
	v_mfma_f32_16x16x32_bf16 v[36:39], v[194:197], v[218:221], v[36:39]
	v_mfma_f32_16x16x32_bf16 v[32:35], v[198:201], v[214:217], v[32:35]
	v_mfma_f32_16x16x32_bf16 v[32:35], v[202:205], v[218:221], v[32:35]
	v_mfma_f32_16x16x32_bf16 v[20:23], v[186:189], v[222:225], v[20:23]
	v_mfma_f32_16x16x32_bf16 v[20:23], v[194:197], v[226:229], v[20:23]
	v_mfma_f32_16x16x32_bf16 v[16:19], v[198:201], v[222:225], v[16:19]
	v_mfma_f32_16x16x32_bf16 v[16:19], v[202:205], v[226:229], v[16:19]
	s_barrier
	v_mfma_f32_16x16x32_bf16 v[4:7], v[186:189], v[230:233], v[4:7]
	v_mfma_f32_16x16x32_bf16 v[4:7], v[194:197], v[234:237], v[4:7]
	v_mfma_f32_16x16x32_bf16 v[0:3], v[198:201], v[230:233], v[0:3]
	v_mfma_f32_16x16x32_bf16 v[0:3], v[202:205], v[234:237], v[0:3]
	s_setprio 0
	s_add_i32 s39, 0, 0x18000
	v_add_u32_e32 v145, s39, v151
	s_add_i32 s46, 0, 0x1c000
	ds_read_b128 v[146:149], v145
	ds_read_b128 v[174:177], v145 offset:1024
	ds_read_b128 v[178:181], v145 offset:2048
	ds_read_b128 v[182:185], v145 offset:3072
	v_add_u32_e32 v145, s46, v151
	ds_read_b128 v[186:189], v145
	ds_read_b128 v[194:197], v145 offset:1024
	ds_read_b128 v[198:201], v145 offset:2048
	ds_read_b128 v[202:205], v145 offset:3072
	s_add_u32 s44, s44, 0x80000
	s_addc_u32 s45, s45, 0
	s_mov_b32 m0, s52
	v_lshl_add_u64 v[244:245], s[44:45], 0, v[128:129]
	ds_read_b128 v[206:209], v155 offset:32768
	ds_read_b128 v[210:213], v155 offset:33792
	ds_read_b128 v[214:217], v155 offset:34816
	ds_read_b128 v[218:221], v155 offset:35840
	ds_read_b128 v[222:225], v155 offset:36864
	ds_read_b128 v[226:229], v155 offset:37888
	ds_read_b128 v[230:233], v155 offset:38912
	ds_read_b128 v[234:237], v155 offset:39936
	global_load_lds_dwordx4 v[244:245], off
	v_lshl_add_u64 v[244:245], s[44:45], 0, v[132:133]
	s_mov_b32 m0, s53
	s_nop 0
	global_load_lds_dwordx4 v[244:245], off
	s_waitcnt vmcnt(8)
	s_waitcnt lgkmcnt(0)
	s_barrier
	s_setprio 1
	s_waitcnt lgkmcnt(0)
	v_mfma_f32_16x16x32_bf16 v[124:127], v[146:149], v[206:209], v[124:127]
	v_mfma_f32_16x16x32_bf16 v[124:127], v[174:177], v[210:213], v[124:127]
	v_mfma_f32_16x16x32_bf16 v[120:123], v[178:181], v[206:209], v[120:123]
	v_mfma_f32_16x16x32_bf16 v[120:123], v[182:185], v[210:213], v[120:123]
	v_mfma_f32_16x16x32_bf16 v[108:111], v[146:149], v[214:217], v[108:111]
	v_mfma_f32_16x16x32_bf16 v[108:111], v[174:177], v[218:221], v[108:111]
	v_mfma_f32_16x16x32_bf16 v[104:107], v[178:181], v[214:217], v[104:107]
	v_mfma_f32_16x16x32_bf16 v[104:107], v[182:185], v[218:221], v[104:107]
	v_mfma_f32_16x16x32_bf16 v[92:95], v[146:149], v[222:225], v[92:95]
	v_mfma_f32_16x16x32_bf16 v[92:95], v[174:177], v[226:229], v[92:95]
	v_mfma_f32_16x16x32_bf16 v[88:91], v[178:181], v[222:225], v[88:91]
	v_mfma_f32_16x16x32_bf16 v[88:91], v[182:185], v[226:229], v[88:91]
	v_mfma_f32_16x16x32_bf16 v[76:79], v[146:149], v[230:233], v[76:79]
	v_mfma_f32_16x16x32_bf16 v[76:79], v[174:177], v[234:237], v[76:79]
	v_mfma_f32_16x16x32_bf16 v[72:75], v[178:181], v[230:233], v[72:75]
	v_mfma_f32_16x16x32_bf16 v[72:75], v[182:185], v[234:237], v[72:75]
	s_setprio 0
	s_setprio 1
	v_mfma_f32_16x16x32_bf16 v[116:119], v[186:189], v[206:209], v[116:119]
	v_mfma_f32_16x16x32_bf16 v[116:119], v[194:197], v[210:213], v[116:119]
	v_mfma_f32_16x16x32_bf16 v[112:115], v[198:201], v[206:209], v[112:115]
	v_mfma_f32_16x16x32_bf16 v[112:115], v[202:205], v[210:213], v[112:115]
	v_mfma_f32_16x16x32_bf16 v[100:103], v[186:189], v[214:217], v[100:103]
	v_mfma_f32_16x16x32_bf16 v[100:103], v[194:197], v[218:221], v[100:103]
	v_mfma_f32_16x16x32_bf16 v[96:99], v[198:201], v[214:217], v[96:99]
	v_mfma_f32_16x16x32_bf16 v[96:99], v[202:205], v[218:221], v[96:99]
	v_mfma_f32_16x16x32_bf16 v[84:87], v[186:189], v[222:225], v[84:87]
	v_mfma_f32_16x16x32_bf16 v[84:87], v[194:197], v[226:229], v[84:87]
	v_mfma_f32_16x16x32_bf16 v[80:83], v[198:201], v[222:225], v[80:83]
	v_mfma_f32_16x16x32_bf16 v[80:83], v[202:205], v[226:229], v[80:83]
	s_barrier
; #define PG8_STAGE(bufoff, gbase, voff) do { _Pragma("unroll") for (int _i = 0; _i < 2; ++_i) \
;         __builtin_amdgcn_global_load_lds((const unsigned*)((const char*)(gbase) + (voff)[_i]), (LAS unsigned*)(lds + (bufoff) + ldsw + _i * 8192), 16, 0, 0); } while (0)
; #define PG8_LDA(dst, b, h) do { _Pragma("unroll") for (int m = 0; m < 4; ++m) _Pragma("unroll") for (int k = 0; k < 2; ++k) dst[m][k] = *(const LAS bf16x8*)(lds + PG8_SA(b, h) + aoff + m * 2048 + k * 1024); } while (0)
; #define PG8_MMA(ai, bj, At, Bt) do { __builtin_amdgcn_s_setprio(1); _Pragma("unroll") for (int m = 0; m < 4; ++m) _Pragma("unroll") for (int n = 0; n < 2; ++n) _Pragma("unroll") for (int k = 0; k < 2; ++k) \
;         acc[ai][bj][m][n] = __builtin_amdgcn_mfma_f32_16x16x32_bf16(Bt[n][k], At[m][k], acc[ai][bj][m][n], 0, 0, 0); __builtin_amdgcn_s_setprio(0); } while (0)
; #define PG8_WAIT_V(n) asm volatile("s_waitcnt vmcnt(" #n ")" ::: "memory")
; #define PG8_WAIT_L(n) asm volatile("s_waitcnt lgkmcnt(" #n ")" ::: "memory")
; #define PG8_BAR __builtin_amdgcn_s_barrier()
; #define PG8_SCHED __builtin_amdgcn_sched_barrier(0)
; template <class Epi, bool ALIGN_EPI>
; __device__ __forceinline__ void gemm_phase(LAS unsigned char* lds, const Gemm g, const StaticOrder& S, const Epi& E) {
;     ...
;             PG8_WAIT_V(8); PG8_WAIT_L(0); PG8_BAR; PG8_MMA(0, 0, At, B0); PG8_MMA(0, 1, At, B1); PG8_BAR; PG8_SCHED;
;             PG8_LDA(At, 1, 1); PG8_STAGE(PG8_SB(1, 0), b3, voffB); PG8_STAGE(PG8_SB(1, 1), b3 + hB, voffB); PG8_STAGE(PG8_SA(1, 0), a3, voffA);
;             PG8_WAIT_V(8); PG8_WAIT_L(0); PG8_BAR; PG8_MMA(1, 0, At, B0); PG8_MMA(1, 1, At, B1); PG8_BAR; PG8_SCHED;
;         }
;         if constexpr (ALIGN_EPI) { if (wr == 0) PG8_BAR; }
	v_mfma_f32_16x16x32_bf16 v[68:71], v[186:189], v[230:233], v[68:71]
	v_mfma_f32_16x16x32_bf16 v[68:71], v[194:197], v[234:237], v[68:71]
	v_mfma_f32_16x16x32_bf16 v[64:67], v[198:201], v[230:233], v[64:67]
	v_mfma_f32_16x16x32_bf16 v[64:67], v[202:205], v[234:237], v[64:67]
	s_setprio 0
	s_add_i32 s39, s39, s51
	v_lshl_add_u64 v[190:191], v[190:191], 0, s[20:21]
	s_mov_b32 m0, s39
	ds_read_b128 v[206:209], v155 offset:49152
	ds_read_b128 v[210:213], v155 offset:50176
	ds_read_b128 v[214:217], v155 offset:51200
	ds_read_b128 v[218:221], v155 offset:52224
	ds_read_b128 v[222:225], v155 offset:53248
	ds_read_b128 v[226:229], v155 offset:54272
	ds_read_b128 v[230:233], v155 offset:55296
	ds_read_b128 v[234:237], v155 offset:56320
	global_load_lds_dwordx4 v[190:191], off
	s_add_i32 m0, s39, 0x2000
	s_add_u32 s36, s36, 0x80080
	v_lshl_add_u64 v[190:191], v[238:239], 0, s[20:21]
	s_addc_u32 s37, s37, 0
	s_add_i32 s39, s46, s51
	global_load_lds_dwordx4 v[190:191], off
	v_lshl_add_u64 v[190:191], s[36:37], 0, v[130:131]
	s_mov_b32 m0, s39
	s_nop 0
	global_load_lds_dwordx4 v[190:191], off
	v_lshl_add_u64 v[190:191], s[36:37], 0, v[134:135]
	s_add_i32 m0, s39, 0x2000
	s_nop 0
	global_load_lds_dwordx4 v[190:191], off
	v_lshl_add_u64 v[190:191], v[240:241], 0, s[20:21]
	s_mov_b32 m0, s57
	s_nop 0
	global_load_lds_dwordx4 v[190:191], off
	v_lshl_add_u64 v[190:191], v[242:243], 0, s[20:21]
	s_mov_b32 m0, s58
	s_nop 0
	global_load_lds_dwordx4 v[190:191], off
	s_waitcnt vmcnt(8)
	s_waitcnt lgkmcnt(0)
	s_barrier
	s_setprio 1
	s_waitcnt lgkmcnt(0)
	v_mfma_f32_16x16x32_bf16 v[60:63], v[146:149], v[206:209], v[60:63]
	v_mfma_f32_16x16x32_bf16 v[60:63], v[174:177], v[210:213], v[60:63]
	v_mfma_f32_16x16x32_bf16 v[56:59], v[178:181], v[206:209], v[56:59]
	v_mfma_f32_16x16x32_bf16 v[56:59], v[182:185], v[210:213], v[56:59]
	v_mfma_f32_16x16x32_bf16 v[44:47], v[146:149], v[214:217], v[44:47]
	v_mfma_f32_16x16x32_bf16 v[44:47], v[174:177], v[218:221], v[44:47]
	v_mfma_f32_16x16x32_bf16 v[40:43], v[178:181], v[214:217], v[40:43]
	v_mfma_f32_16x16x32_bf16 v[40:43], v[182:185], v[218:221], v[40:43]
	v_mfma_f32_16x16x32_bf16 v[28:31], v[146:149], v[222:225], v[28:31]
	v_mfma_f32_16x16x32_bf16 v[28:31], v[174:177], v[226:229], v[28:31]
	v_mfma_f32_16x16x32_bf16 v[24:27], v[178:181], v[222:225], v[24:27]
	v_mfma_f32_16x16x32_bf16 v[24:27], v[182:185], v[226:229], v[24:27]
	v_mfma_f32_16x16x32_bf16 v[12:15], v[146:149], v[230:233], v[12:15]
	v_mfma_f32_16x16x32_bf16 v[12:15], v[174:177], v[234:237], v[12:15]
	v_mfma_f32_16x16x32_bf16 v[8:11], v[178:181], v[230:233], v[8:11]
	v_mfma_f32_16x16x32_bf16 v[8:11], v[182:185], v[234:237], v[8:11]
	s_setprio 0
	s_setprio 1
	v_mfma_f32_16x16x32_bf16 v[52:55], v[186:189], v[206:209], v[52:55]
	v_mfma_f32_16x16x32_bf16 v[52:55], v[194:197], v[210:213], v[52:55]
	v_mfma_f32_16x16x32_bf16 v[48:51], v[198:201], v[206:209], v[48:51]
	v_mfma_f32_16x16x32_bf16 v[48:51], v[202:205], v[210:213], v[48:51]
	v_mfma_f32_16x16x32_bf16 v[36:39], v[186:189], v[214:217], v[36:39]
	v_mfma_f32_16x16x32_bf16 v[36:39], v[194:197], v[218:221], v[36:39]
	v_mfma_f32_16x16x32_bf16 v[32:35], v[198:201], v[214:217], v[32:35]
	v_mfma_f32_16x16x32_bf16 v[32:35], v[202:205], v[218:221], v[32:35]
	v_mfma_f32_16x16x32_bf16 v[20:23], v[186:189], v[222:225], v[20:23]
	v_mfma_f32_16x16x32_bf16 v[20:23], v[194:197], v[226:229], v[20:23]
	v_mfma_f32_16x16x32_bf16 v[16:19], v[198:201], v[222:225], v[16:19]
	v_mfma_f32_16x16x32_bf16 v[16:19], v[202:205], v[226:229], v[16:19]
	s_barrier
	v_mfma_f32_16x16x32_bf16 v[4:7], v[186:189], v[230:233], v[4:7]
	v_mfma_f32_16x16x32_bf16 v[4:7], v[194:197], v[234:237], v[4:7]
	v_mfma_f32_16x16x32_bf16 v[0:3], v[198:201], v[230:233], v[0:3]
	v_mfma_f32_16x16x32_bf16 v[0:3], v[202:205], v[234:237], v[0:3]
	s_setprio 0
	s_add_i32 s38, s38, 2
	s_add_u32 s4, s4, 0x100
	s_addc_u32 s5, s5, 0
	s_add_u32 s27, s27, 0x100
	s_addc_u32 s29, s29, 0
	s_cmp_gt_u32 s38, 29
	s_cbranch_scc0 .LBB0_1094
	s_and_b64 vcc, exec, s[22:23]
	s_cbranch_vccz .LBB0_1097
	s_barrier

; #define PG8_STAGE(bufoff, gbase, voff) do { _Pragma("unroll") for (int _i = 0; _i < 2; ++_i) \
;         __builtin_amdgcn_global_load_lds((const unsigned*)((const char*)(gbase) + (voff)[_i]), (LAS unsigned*)(lds + (bufoff) + ldsw + _i * 8192), 16, 0, 0); } while (0)
; #define PG8_LDA(dst, b, h) do { _Pragma("unroll") for (int m = 0; m < 4; ++m) _Pragma("unroll") for (int k = 0; k < 2; ++k) dst[m][k] = *(const LAS bf16x8*)(lds + PG8_SA(b, h) + aoff + m * 2048 + k * 1024); } while (0)
; #define PG8_LDB(dst, b, h) do { _Pragma("unroll") for (int n = 0; n < 2; ++n) _Pragma("unroll") for (int k = 0; k < 2; ++k) dst[n][k] = *(const LAS bf16x8*)(lds + PG8_SB(b, h) + boff + n * 2048 + k * 1024); } while (0)
; #define PG8_MMA(ai, bj, At, Bt) do { __builtin_amdgcn_s_setprio(1); _Pragma("unroll") for (int m = 0; m < 4; ++m) _Pragma("unroll") for (int n = 0; n < 2; ++n) _Pragma("unroll") for (int k = 0; k < 2; ++k) \
;         acc[ai][bj][m][n] = __builtin_amdgcn_mfma_f32_16x16x32_bf16(Bt[n][k], At[m][k], acc[ai][bj][m][n], 0, 0, 0); __builtin_amdgcn_s_setprio(0); } while (0)
; #define PG8_WAIT_V(n) asm volatile("s_waitcnt vmcnt(" #n ")" ::: "memory")
; #define PG8_WAIT_L(n) asm volatile("s_waitcnt lgkmcnt(" #n ")" ::: "memory")
; #define PG8_BAR __builtin_amdgcn_s_barrier()
; #define PG8_SCHED __builtin_amdgcn_sched_barrier(0)
; template <class Epi, bool ALIGN_EPI>
; __device__ __forceinline__ void gemm_phase(LAS unsigned char* lds, const Gemm g, const StaticOrder& S, const Epi& E) {
;     ...
;         for (int t = 0; t < nt; t += 2) {
;             const bool last = (t == nt - 2);
;             const char* a1 = cA + (size_t)(t + 1) * kstep;
;             const char* a2 = last ? nA : cA + (size_t)(t + 2) * kstep; const char* b2 = last ? nB : cB + (size_t)(t + 2) * kstep;
;             const char* a3 = a2 + kstep; const char* b3 = b2 + kstep;
;             PG8_LDB(B0, 0, 0); PG8_LDB(B1, 0, 1); PG8_SCHED; PG8_LDA(At, 0, 0); PG8_STAGE(PG8_SA(1, 1), a1 + hA, voffA);
;             PG8_WAIT_V(8); PG8_WAIT_L(0); PG8_BAR; PG8_MMA(0, 0, At, B0); PG8_MMA(0, 1, At, B1); PG8_BAR; PG8_SCHED;
;             PG8_LDA(At, 0, 1); PG8_STAGE(PG8_SB(0, 0), b2, voffB); PG8_STAGE(PG8_SB(0, 1), b2 + hB, voffB); PG8_STAGE(PG8_SA(0, 0), a2, voffA);
;             PG8_WAIT_V(8); PG8_WAIT_L(0); PG8_BAR; PG8_MMA(1, 0, At, B0); PG8_MMA(1, 1, At, B1); PG8_BAR; PG8_SCHED;
.LBB0_1585:
	ds_read_b128 v[128:131], v175
	ds_read_b128 v[132:135], v175 offset:1024
	ds_read_b128 v[136:139], v175 offset:2048
	ds_read_b128 v[140:143], v175 offset:3072
	ds_read_b128 v[160:163], v176
	ds_read_b128 v[164:167], v176 offset:1024
	ds_read_b128 v[168:171], v176 offset:2048
	ds_read_b128 v[180:183], v176 offset:3072
	s_add_u32 s40, s36, 0xfff80080
	s_addc_u32 s41, s37, -1
	s_cmp_eq_u32 s57, 28
	s_cselect_b32 s43, s25, s41
	s_cselect_b32 s42, s31, s40
	s_cselect_b32 s41, s23, s56
	s_cselect_b32 s40, s54, s55
	v_lshl_add_u64 v[218:219], s[36:37], 0, v[152:153]
	s_add_i32 m0, s35, 0xc000
	ds_read_b128 v[184:187], v177
	ds_read_b128 v[188:191], v177 offset:1024
	ds_read_b128 v[194:197], v177 offset:2048
	ds_read_b128 v[198:201], v177 offset:3072
	ds_read_b128 v[202:205], v177 offset:4096
	ds_read_b128 v[206:209], v177 offset:5120
	ds_read_b128 v[210:213], v177 offset:6144
	ds_read_b128 v[214:217], v177 offset:7168
	global_load_lds_dwordx4 v[218:219], off
	v_lshl_add_u64 v[218:219], s[36:37], 0, v[154:155]
	s_add_i32 m0, s35, 0xe000
	s_nop 0
	global_load_lds_dwordx4 v[218:219], off
	s_waitcnt vmcnt(8)
	s_waitcnt lgkmcnt(0)
	s_barrier
	s_setprio 1
	s_waitcnt lgkmcnt(0)
	v_mfma_f32_16x16x32_bf16 v[124:127], v[128:131], v[184:187], v[124:127]
	v_mfma_f32_16x16x32_bf16 v[124:127], v[132:135], v[188:191], v[124:127]
	v_mfma_f32_16x16x32_bf16 v[120:123], v[136:139], v[184:187], v[120:123]
	v_mfma_f32_16x16x32_bf16 v[120:123], v[140:143], v[188:191], v[120:123]
	v_mfma_f32_16x16x32_bf16 v[112:115], v[128:131], v[194:197], v[112:115]
	v_mfma_f32_16x16x32_bf16 v[112:115], v[132:135], v[198:201], v[112:115]
	v_mfma_f32_16x16x32_bf16 v[104:107], v[136:139], v[194:197], v[104:107]
	v_mfma_f32_16x16x32_bf16 v[104:107], v[140:143], v[198:201], v[104:107]
	v_mfma_f32_16x16x32_bf16 v[92:95], v[128:131], v[202:205], v[92:95]
	v_mfma_f32_16x16x32_bf16 v[92:95], v[132:135], v[206:209], v[92:95]
	v_mfma_f32_16x16x32_bf16 v[88:91], v[136:139], v[202:205], v[88:91]
	v_mfma_f32_16x16x32_bf16 v[88:91], v[140:143], v[206:209], v[88:91]
	v_mfma_f32_16x16x32_bf16 v[76:79], v[128:131], v[210:213], v[76:79]
	v_mfma_f32_16x16x32_bf16 v[76:79], v[132:135], v[214:217], v[76:79]
	v_mfma_f32_16x16x32_bf16 v[72:75], v[136:139], v[210:213], v[72:75]
	v_mfma_f32_16x16x32_bf16 v[72:75], v[140:143], v[214:217], v[72:75]
	s_setprio 0
	s_setprio 1
	v_mfma_f32_16x16x32_bf16 v[116:119], v[160:163], v[184:187], v[116:119]
	v_mfma_f32_16x16x32_bf16 v[116:119], v[164:167], v[188:191], v[116:119]
	v_mfma_f32_16x16x32_bf16 v[108:111], v[168:171], v[184:187], v[108:111]
	v_mfma_f32_16x16x32_bf16 v[108:111], v[180:183], v[188:191], v[108:111]
	v_mfma_f32_16x16x32_bf16 v[100:103], v[160:163], v[194:197], v[100:103]
	v_mfma_f32_16x16x32_bf16 v[100:103], v[164:167], v[198:201], v[100:103]
	v_mfma_f32_16x16x32_bf16 v[96:99], v[168:171], v[194:197], v[96:99]
	v_mfma_f32_16x16x32_bf16 v[96:99], v[180:183], v[198:201], v[96:99]
	v_mfma_f32_16x16x32_bf16 v[84:87], v[160:163], v[202:205], v[84:87]
	v_mfma_f32_16x16x32_bf16 v[84:87], v[164:167], v[206:209], v[84:87]
	v_mfma_f32_16x16x32_bf16 v[80:83], v[168:171], v[202:205], v[80:83]
	v_mfma_f32_16x16x32_bf16 v[80:83], v[180:183], v[206:209], v[80:83]
	s_barrier
	v_mfma_f32_16x16x32_bf16 v[68:71], v[160:163], v[210:213], v[68:71]
	v_mfma_f32_16x16x32_bf16 v[68:71], v[164:167], v[214:217], v[68:71]
	v_mfma_f32_16x16x32_bf16 v[64:67], v[168:171], v[210:213], v[64:67]
	v_mfma_f32_16x16x32_bf16 v[64:67], v[180:183], v[214:217], v[64:67]
	s_setprio 0
	s_add_i32 s58, s51, s33
	v_lshl_add_u64 v[218:219], s[40:41], 0, v[146:147]
	s_mov_b32 m0, s58
	ds_read_b128 v[184:187], v177 offset:16384
	ds_read_b128 v[188:191], v177 offset:17408
	ds_read_b128 v[194:197], v177 offset:18432
	ds_read_b128 v[198:201], v177 offset:19456
	ds_read_b128 v[202:205], v177 offset:20480
	ds_read_b128 v[206:209], v177 offset:21504
	ds_read_b128 v[210:213], v177 offset:22528
	ds_read_b128 v[214:217], v177 offset:23552
	global_load_lds_dwordx4 v[218:219], off
	s_add_i32 m0, s58, 0x2000
	s_add_u32 s58, s40, 0x80000
	v_lshl_add_u64 v[220:221], s[40:41], 0, v[150:151]
	s_addc_u32 s59, s41, 0
	s_add_i32 s60, s52, s33
	global_load_lds_dwordx4 v[220:221], off
	v_lshl_add_u64 v[222:223], s[58:59], 0, v[146:147]
	s_mov_b32 m0, s60
	v_lshl_add_u64 v[224:225], s[42:43], 0, v[148:149]
	global_load_lds_dwordx4 v[222:223], off
	v_lshl_add_u64 v[222:223], s[58:59], 0, v[150:151]
	s_add_i32 m0, s60, 0x2000
	s_nop 0
	global_load_lds_dwordx4 v[222:223], off
	v_lshl_add_u64 v[222:223], s[42:43], 0, v[144:145]
	s_mov_b32 m0, s35
	s_nop 0
	global_load_lds_dwordx4 v[222:223], off
	s_mov_b32 m0, s38
	s_nop 0
	global_load_lds_dwordx4 v[224:225], off
	s_waitcnt vmcnt(8)
	s_waitcnt lgkmcnt(0)
	s_barrier
; #define PG8_STAGE(bufoff, gbase, voff) do { _Pragma("unroll") for (int _i = 0; _i < 2; ++_i) \
;         __builtin_amdgcn_global_load_lds((const unsigned*)((const char*)(gbase) + (voff)[_i]), (LAS unsigned*)(lds + (bufoff) + ldsw + _i * 8192), 16, 0, 0); } while (0)
; #define PG8_LDA(dst, b, h) do { _Pragma("unroll") for (int m = 0; m < 4; ++m) _Pragma("unroll") for (int k = 0; k < 2; ++k) dst[m][k] = *(const LAS bf16x8*)(lds + PG8_SA(b, h) + aoff + m * 2048 + k * 1024); } while (0)
; #define PG8_LDB(dst, b, h) do { _Pragma("unroll") for (int n = 0; n < 2; ++n) _Pragma("unroll") for (int k = 0; k < 2; ++k) dst[n][k] = *(const LAS bf16x8*)(lds + PG8_SB(b, h) + boff + n * 2048 + k * 1024); } while (0)
; #define PG8_MMA(ai, bj, At, Bt) do { __builtin_amdgcn_s_setprio(1); _Pragma("unroll") for (int m = 0; m < 4; ++m) _Pragma("unroll") for (int n = 0; n < 2; ++n) _Pragma("unroll") for (int k = 0; k < 2; ++k) \
;         acc[ai][bj][m][n] = __builtin_amdgcn_mfma_f32_16x16x32_bf16(Bt[n][k], At[m][k], acc[ai][bj][m][n], 0, 0, 0); __builtin_amdgcn_s_setprio(0); } while (0)
; #define PG8_WAIT_V(n) asm volatile("s_waitcnt vmcnt(" #n ")" ::: "memory")
; #define PG8_WAIT_L(n) asm volatile("s_waitcnt lgkmcnt(" #n ")" ::: "memory")
; #define PG8_BAR __builtin_amdgcn_s_barrier()
; #define PG8_SCHED __builtin_amdgcn_sched_barrier(0)
; template <class Epi, bool ALIGN_EPI>
; __device__ __forceinline__ void gemm_phase(LAS unsigned char* lds, const Gemm g, const StaticOrder& S, const Epi& E) {
;     ...
;             PG8_WAIT_V(8); PG8_WAIT_L(0); PG8_BAR; PG8_MMA(1, 0, At, B0); PG8_MMA(1, 1, At, B1); PG8_BAR; PG8_SCHED;
;             PG8_LDB(B0, 1, 0); PG8_LDB(B1, 1, 1); PG8_SCHED; PG8_LDA(At, 1, 0); PG8_STAGE(PG8_SA(0, 1), a2 + hA, voffA);
;             PG8_WAIT_V(8); PG8_WAIT_L(0); PG8_BAR; PG8_MMA(0, 0, At, B0); PG8_MMA(0, 1, At, B1); PG8_BAR; PG8_SCHED;
;             PG8_LDA(At, 1, 1); PG8_STAGE(PG8_SB(1, 0), b3, voffB); PG8_STAGE(PG8_SB(1, 1), b3 + hB, voffB); PG8_STAGE(PG8_SA(1, 0), a3, voffA);
	s_setprio 1
	s_waitcnt lgkmcnt(0)
	v_mfma_f32_16x16x32_bf16 v[60:63], v[128:131], v[184:187], v[60:63]
	v_mfma_f32_16x16x32_bf16 v[60:63], v[132:135], v[188:191], v[60:63]
	v_mfma_f32_16x16x32_bf16 v[56:59], v[136:139], v[184:187], v[56:59]
	v_mfma_f32_16x16x32_bf16 v[56:59], v[140:143], v[188:191], v[56:59]
	v_mfma_f32_16x16x32_bf16 v[44:47], v[128:131], v[194:197], v[44:47]
	v_mfma_f32_16x16x32_bf16 v[44:47], v[132:135], v[198:201], v[44:47]
	v_mfma_f32_16x16x32_bf16 v[40:43], v[136:139], v[194:197], v[40:43]
	v_mfma_f32_16x16x32_bf16 v[40:43], v[140:143], v[198:201], v[40:43]
	v_mfma_f32_16x16x32_bf16 v[28:31], v[128:131], v[202:205], v[28:31]
	v_mfma_f32_16x16x32_bf16 v[28:31], v[132:135], v[206:209], v[28:31]
	v_mfma_f32_16x16x32_bf16 v[24:27], v[136:139], v[202:205], v[24:27]
	v_mfma_f32_16x16x32_bf16 v[24:27], v[140:143], v[206:209], v[24:27]
	v_mfma_f32_16x16x32_bf16 v[12:15], v[128:131], v[210:213], v[12:15]
	v_mfma_f32_16x16x32_bf16 v[12:15], v[132:135], v[214:217], v[12:15]
	v_mfma_f32_16x16x32_bf16 v[8:11], v[136:139], v[210:213], v[8:11]
	v_mfma_f32_16x16x32_bf16 v[8:11], v[140:143], v[214:217], v[8:11]
	s_setprio 0
	s_setprio 1
	v_mfma_f32_16x16x32_bf16 v[52:55], v[160:163], v[184:187], v[52:55]
	v_mfma_f32_16x16x32_bf16 v[52:55], v[164:167], v[188:191], v[52:55]
	v_mfma_f32_16x16x32_bf16 v[48:51], v[168:171], v[184:187], v[48:51]
	v_mfma_f32_16x16x32_bf16 v[48:51], v[180:183], v[188:191], v[48:51]
	v_mfma_f32_16x16x32_bf16 v[36:39], v[160:163], v[194:197], v[36:39]
	v_mfma_f32_16x16x32_bf16 v[36:39], v[164:167], v[198:201], v[36:39]
	v_mfma_f32_16x16x32_bf16 v[32:35], v[168:171], v[194:197], v[32:35]
	v_mfma_f32_16x16x32_bf16 v[32:35], v[180:183], v[198:201], v[32:35]
	v_mfma_f32_16x16x32_bf16 v[20:23], v[160:163], v[202:205], v[20:23]
	v_mfma_f32_16x16x32_bf16 v[20:23], v[164:167], v[206:209], v[20:23]
	v_mfma_f32_16x16x32_bf16 v[16:19], v[168:171], v[202:205], v[16:19]
	v_mfma_f32_16x16x32_bf16 v[16:19], v[180:183], v[206:209], v[16:19]
	s_barrier
	v_mfma_f32_16x16x32_bf16 v[4:7], v[160:163], v[210:213], v[4:7]
	v_mfma_f32_16x16x32_bf16 v[4:7], v[164:167], v[214:217], v[4:7]
	v_mfma_f32_16x16x32_bf16 v[0:3], v[168:171], v[210:213], v[0:3]
	v_mfma_f32_16x16x32_bf16 v[0:3], v[180:183], v[214:217], v[0:3]
	s_setprio 0
	s_add_i32 s58, 0, 0x18000
	s_add_i32 s59, 0, 0x1c000
	v_add_u32_e32 v140, s58, v173
	v_add_u32_e32 v179, s59, v173
	ds_read_b128 v[128:131], v140
	ds_read_b128 v[132:135], v140 offset:1024
	ds_read_b128 v[136:139], v140 offset:2048
	ds_read_b128 v[140:143], v140 offset:3072
	ds_read_b128 v[160:163], v179
	ds_read_b128 v[164:167], v179 offset:1024
	ds_read_b128 v[168:171], v179 offset:2048
	ds_read_b128 v[180:183], v179 offset:3072
	s_add_u32 s42, s42, 0x80000
	s_addc_u32 s43, s43, 0
	s_mov_b32 m0, s39
	v_lshl_add_u64 v[226:227], s[42:43], 0, v[144:145]
	ds_read_b128 v[184:187], v177 offset:32768
	ds_read_b128 v[188:191], v177 offset:33792
	ds_read_b128 v[194:197], v177 offset:34816
	ds_read_b128 v[198:201], v177 offset:35840
	ds_read_b128 v[202:205], v177 offset:36864
	ds_read_b128 v[206:209], v177 offset:37888
	ds_read_b128 v[210:213], v177 offset:38912
	ds_read_b128 v[214:217], v177 offset:39936
	global_load_lds_dwordx4 v[226:227], off
	v_lshl_add_u64 v[226:227], s[42:43], 0, v[148:149]
	s_mov_b32 m0, s44
	s_nop 0
	global_load_lds_dwordx4 v[226:227], off
	s_waitcnt vmcnt(8)
	s_waitcnt lgkmcnt(0)
	s_barrier
	s_setprio 1
	s_waitcnt lgkmcnt(0)
	v_mfma_f32_16x16x32_bf16 v[124:127], v[128:131], v[184:187], v[124:127]
	v_mfma_f32_16x16x32_bf16 v[124:127], v[132:135], v[188:191], v[124:127]
	v_mfma_f32_16x16x32_bf16 v[120:123], v[136:139], v[184:187], v[120:123]
	v_mfma_f32_16x16x32_bf16 v[120:123], v[140:143], v[188:191], v[120:123]
	v_mfma_f32_16x16x32_bf16 v[112:115], v[128:131], v[194:197], v[112:115]
	v_mfma_f32_16x16x32_bf16 v[112:115], v[132:135], v[198:201], v[112:115]
	v_mfma_f32_16x16x32_bf16 v[104:107], v[136:139], v[194:197], v[104:107]
	v_mfma_f32_16x16x32_bf16 v[104:107], v[140:143], v[198:201], v[104:107]
	v_mfma_f32_16x16x32_bf16 v[92:95], v[128:131], v[202:205], v[92:95]
	v_mfma_f32_16x16x32_bf16 v[92:95], v[132:135], v[206:209], v[92:95]
	v_mfma_f32_16x16x32_bf16 v[88:91], v[136:139], v[202:205], v[88:91]
	v_mfma_f32_16x16x32_bf16 v[88:91], v[140:143], v[206:209], v[88:91]
	v_mfma_f32_16x16x32_bf16 v[76:79], v[128:131], v[210:213], v[76:79]
	v_mfma_f32_16x16x32_bf16 v[76:79], v[132:135], v[214:217], v[76:79]
	v_mfma_f32_16x16x32_bf16 v[72:75], v[136:139], v[210:213], v[72:75]
	v_mfma_f32_16x16x32_bf16 v[72:75], v[140:143], v[214:217], v[72:75]
	s_setprio 0
	s_setprio 1
	v_mfma_f32_16x16x32_bf16 v[116:119], v[160:163], v[184:187], v[116:119]
	v_mfma_f32_16x16x32_bf16 v[116:119], v[164:167], v[188:191], v[116:119]
	v_mfma_f32_16x16x32_bf16 v[108:111], v[168:171], v[184:187], v[108:111]
	v_mfma_f32_16x16x32_bf16 v[108:111], v[180:183], v[188:191], v[108:111]
	v_mfma_f32_16x16x32_bf16 v[100:103], v[160:163], v[194:197], v[100:103]
	v_mfma_f32_16x16x32_bf16 v[100:103], v[164:167], v[198:201], v[100:103]
	v_mfma_f32_16x16x32_bf16 v[96:99], v[168:171], v[194:197], v[96:99]
	v_mfma_f32_16x16x32_bf16 v[96:99], v[180:183], v[198:201], v[96:99]
	v_mfma_f32_16x16x32_bf16 v[84:87], v[160:163], v[202:205], v[84:87]
	v_mfma_f32_16x16x32_bf16 v[84:87], v[164:167], v[206:209], v[84:87]
	v_mfma_f32_16x16x32_bf16 v[80:83], v[168:171], v[202:205], v[80:83]
	v_mfma_f32_16x16x32_bf16 v[80:83], v[180:183], v[206:209], v[80:83]
	s_barrier
; #define PG8_STAGE(bufoff, gbase, voff) do { _Pragma("unroll") for (int _i = 0; _i < 2; ++_i) \
;         __builtin_amdgcn_global_load_lds((const unsigned*)((const char*)(gbase) + (voff)[_i]), (LAS unsigned*)(lds + (bufoff) + ldsw + _i * 8192), 16, 0, 0); } while (0)
; #define PG8_LDA(dst, b, h) do { _Pragma("unroll") for (int m = 0; m < 4; ++m) _Pragma("unroll") for (int k = 0; k < 2; ++k) dst[m][k] = *(const LAS bf16x8*)(lds + PG8_SA(b, h) + aoff + m * 2048 + k * 1024); } while (0)
; #define PG8_MMA(ai, bj, At, Bt) do { __builtin_amdgcn_s_setprio(1); _Pragma("unroll") for (int m = 0; m < 4; ++m) _Pragma("unroll") for (int n = 0; n < 2; ++n) _Pragma("unroll") for (int k = 0; k < 2; ++k) \
;         acc[ai][bj][m][n] = __builtin_amdgcn_mfma_f32_16x16x32_bf16(Bt[n][k], At[m][k], acc[ai][bj][m][n], 0, 0, 0); __builtin_amdgcn_s_setprio(0); } while (0)
; #define PG8_WAIT_V(n) asm volatile("s_waitcnt vmcnt(" #n ")" ::: "memory")
; #define PG8_WAIT_L(n) asm volatile("s_waitcnt lgkmcnt(" #n ")" ::: "memory")
; #define PG8_BAR __builtin_amdgcn_s_barrier()
; #define PG8_SCHED __builtin_amdgcn_sched_barrier(0)
; template <class Epi, bool ALIGN_EPI>
; __device__ __forceinline__ void gemm_phase(LAS unsigned char* lds, const Gemm g, const StaticOrder& S, const Epi& E) {
;     ...
;             PG8_WAIT_V(8); PG8_WAIT_L(0); PG8_BAR; PG8_MMA(0, 0, At, B0); PG8_MMA(0, 1, At, B1); PG8_BAR; PG8_SCHED;
;             PG8_LDA(At, 1, 1); PG8_STAGE(PG8_SB(1, 0), b3, voffB); PG8_STAGE(PG8_SB(1, 1), b3 + hB, voffB); PG8_STAGE(PG8_SA(1, 0), a3, voffA);
;             PG8_WAIT_V(8); PG8_WAIT_L(0); PG8_BAR; PG8_MMA(1, 0, At, B0); PG8_MMA(1, 1, At, B1); PG8_BAR; PG8_SCHED;
;         }
;         if constexpr (ALIGN_EPI) { if (wr == 0) PG8_BAR; }
	v_mfma_f32_16x16x32_bf16 v[68:71], v[160:163], v[210:213], v[68:71]
	v_mfma_f32_16x16x32_bf16 v[68:71], v[164:167], v[214:217], v[68:71]
	v_mfma_f32_16x16x32_bf16 v[64:67], v[168:171], v[210:213], v[64:67]
	v_mfma_f32_16x16x32_bf16 v[64:67], v[180:183], v[214:217], v[64:67]
	s_setprio 0
	s_add_i32 s42, s58, s33
	v_lshl_add_u64 v[218:219], v[218:219], 0, s[18:19]
	s_mov_b32 m0, s42
	ds_read_b128 v[184:187], v177 offset:49152
	ds_read_b128 v[188:191], v177 offset:50176
	ds_read_b128 v[194:197], v177 offset:51200
	ds_read_b128 v[198:201], v177 offset:52224
	ds_read_b128 v[202:205], v177 offset:53248
	ds_read_b128 v[206:209], v177 offset:54272
	ds_read_b128 v[210:213], v177 offset:55296
	ds_read_b128 v[214:217], v177 offset:56320
	global_load_lds_dwordx4 v[218:219], off
	s_add_i32 m0, s42, 0x2000
	s_add_u32 s40, s40, 0x80080
	v_lshl_add_u64 v[218:219], v[220:221], 0, s[18:19]
	s_addc_u32 s41, s41, 0
	s_add_i32 s42, s59, s33
	global_load_lds_dwordx4 v[218:219], off
	v_lshl_add_u64 v[218:219], s[40:41], 0, v[146:147]
	s_mov_b32 m0, s42
	s_nop 0
	global_load_lds_dwordx4 v[218:219], off
	v_lshl_add_u64 v[218:219], s[40:41], 0, v[150:151]
	s_add_i32 m0, s42, 0x2000
	s_nop 0
	global_load_lds_dwordx4 v[218:219], off
	v_lshl_add_u64 v[218:219], v[222:223], 0, s[18:19]
	s_mov_b32 m0, s48
	s_nop 0
	global_load_lds_dwordx4 v[218:219], off
	v_lshl_add_u64 v[218:219], v[224:225], 0, s[18:19]
	s_mov_b32 m0, s49
	s_nop 0
	global_load_lds_dwordx4 v[218:219], off
	s_waitcnt vmcnt(8)
	s_waitcnt lgkmcnt(0)
	s_barrier
	s_setprio 1
	s_waitcnt lgkmcnt(0)
	v_mfma_f32_16x16x32_bf16 v[60:63], v[128:131], v[184:187], v[60:63]
	v_mfma_f32_16x16x32_bf16 v[60:63], v[132:135], v[188:191], v[60:63]
	v_mfma_f32_16x16x32_bf16 v[56:59], v[136:139], v[184:187], v[56:59]
	v_mfma_f32_16x16x32_bf16 v[56:59], v[140:143], v[188:191], v[56:59]
	v_mfma_f32_16x16x32_bf16 v[44:47], v[128:131], v[194:197], v[44:47]
	v_mfma_f32_16x16x32_bf16 v[44:47], v[132:135], v[198:201], v[44:47]
	v_mfma_f32_16x16x32_bf16 v[40:43], v[136:139], v[194:197], v[40:43]
	v_mfma_f32_16x16x32_bf16 v[40:43], v[140:143], v[198:201], v[40:43]
	v_mfma_f32_16x16x32_bf16 v[28:31], v[128:131], v[202:205], v[28:31]
	v_mfma_f32_16x16x32_bf16 v[28:31], v[132:135], v[206:209], v[28:31]
	v_mfma_f32_16x16x32_bf16 v[24:27], v[136:139], v[202:205], v[24:27]
	v_mfma_f32_16x16x32_bf16 v[24:27], v[140:143], v[206:209], v[24:27]
	v_mfma_f32_16x16x32_bf16 v[12:15], v[128:131], v[210:213], v[12:15]
	v_mfma_f32_16x16x32_bf16 v[12:15], v[132:135], v[214:217], v[12:15]
	v_mfma_f32_16x16x32_bf16 v[8:11], v[136:139], v[210:213], v[8:11]
	v_mfma_f32_16x16x32_bf16 v[8:11], v[140:143], v[214:217], v[8:11]
	s_setprio 0
	s_setprio 1
	v_mfma_f32_16x16x32_bf16 v[52:55], v[160:163], v[184:187], v[52:55]
	v_mfma_f32_16x16x32_bf16 v[52:55], v[164:167], v[188:191], v[52:55]
	v_mfma_f32_16x16x32_bf16 v[48:51], v[168:171], v[184:187], v[48:51]
	v_mfma_f32_16x16x32_bf16 v[48:51], v[180:183], v[188:191], v[48:51]
	v_mfma_f32_16x16x32_bf16 v[36:39], v[160:163], v[194:197], v[36:39]
	v_mfma_f32_16x16x32_bf16 v[36:39], v[164:167], v[198:201], v[36:39]
	v_mfma_f32_16x16x32_bf16 v[32:35], v[168:171], v[194:197], v[32:35]
	v_mfma_f32_16x16x32_bf16 v[32:35], v[180:183], v[198:201], v[32:35]
	v_mfma_f32_16x16x32_bf16 v[20:23], v[160:163], v[202:205], v[20:23]
	v_mfma_f32_16x16x32_bf16 v[20:23], v[164:167], v[206:209], v[20:23]
	v_mfma_f32_16x16x32_bf16 v[16:19], v[168:171], v[202:205], v[16:19]
	v_mfma_f32_16x16x32_bf16 v[16:19], v[180:183], v[206:209], v[16:19]
	s_barrier
	v_mfma_f32_16x16x32_bf16 v[4:7], v[160:163], v[210:213], v[4:7]
	v_mfma_f32_16x16x32_bf16 v[4:7], v[164:167], v[214:217], v[4:7]
	v_mfma_f32_16x16x32_bf16 v[0:3], v[168:171], v[210:213], v[0:3]
	v_mfma_f32_16x16x32_bf16 v[0:3], v[180:183], v[214:217], v[0:3]
	s_setprio 0
	s_add_i32 s57, s57, 2
	s_add_u32 s36, s36, 0x100
	s_addc_u32 s37, s37, 0
	s_add_u32 s55, s55, 0x100
	s_addc_u32 s56, s56, 0
	s_cmp_gt_u32 s57, 29
	s_cbranch_scc0 .LBB0_1585
	s_and_b64 vcc, exec, s[20:21]
	s_cbranch_vccz .LBB0_1588
	s_barrier

; #define PG8_STAGE(bufoff, gbase, voff) do { _Pragma("unroll") for (int _i = 0; _i < 2; ++_i) \
;         __builtin_amdgcn_global_load_lds((const unsigned*)((const char*)(gbase) + (voff)[_i]), (LAS unsigned*)(lds + (bufoff) + ldsw + _i * 8192), 16, 0, 0); } while (0)
; #define PG8_LDA(dst, b, h) do { _Pragma("unroll") for (int m = 0; m < 4; ++m) _Pragma("unroll") for (int k = 0; k < 2; ++k) dst[m][k] = *(const LAS bf16x8*)(lds + PG8_SA(b, h) + aoff + m * 2048 + k * 1024); } while (0)
; #define PG8_LDB(dst, b, h) do { _Pragma("unroll") for (int n = 0; n < 2; ++n) _Pragma("unroll") for (int k = 0; k < 2; ++k) dst[n][k] = *(const LAS bf16x8*)(lds + PG8_SB(b, h) + boff + n * 2048 + k * 1024); } while (0)
; #define PG8_MMA(ai, bj, At, Bt) do { __builtin_amdgcn_s_setprio(1); _Pragma("unroll") for (int m = 0; m < 4; ++m) _Pragma("unroll") for (int n = 0; n < 2; ++n) _Pragma("unroll") for (int k = 0; k < 2; ++k) \
;         acc[ai][bj][m][n] = __builtin_amdgcn_mfma_f32_16x16x32_bf16(Bt[n][k], At[m][k], acc[ai][bj][m][n], 0, 0, 0); __builtin_amdgcn_s_setprio(0); } while (0)
; #define PG8_WAIT_V(n) asm volatile("s_waitcnt vmcnt(" #n ")" ::: "memory")
; #define PG8_WAIT_L(n) asm volatile("s_waitcnt lgkmcnt(" #n ")" ::: "memory")
; #define PG8_BAR __builtin_amdgcn_s_barrier()
; #define PG8_SCHED __builtin_amdgcn_sched_barrier(0)
; template <class Epi, bool ALIGN_EPI>
; __device__ __forceinline__ void gemm_phase(LAS unsigned char* lds, const Gemm g, const StaticOrder& S, const Epi& E) {
;     ...
;         for (int t = 0; t < nt; t += 2) {
;             const bool last = (t == nt - 2);
;             const char* a1 = cA + (size_t)(t + 1) * kstep;
;             const char* a2 = last ? nA : cA + (size_t)(t + 2) * kstep; const char* b2 = last ? nB : cB + (size_t)(t + 2) * kstep;
;             const char* a3 = a2 + kstep; const char* b3 = b2 + kstep;
;             PG8_LDB(B0, 0, 0); PG8_LDB(B1, 0, 1); PG8_SCHED; PG8_LDA(At, 0, 0); PG8_STAGE(PG8_SA(1, 1), a1 + hA, voffA);
;             PG8_WAIT_V(8); PG8_WAIT_L(0); PG8_BAR; PG8_MMA(0, 0, At, B0); PG8_MMA(0, 1, At, B1); PG8_BAR; PG8_SCHED;
;             PG8_LDA(At, 0, 1); PG8_STAGE(PG8_SB(0, 0), b2, voffB); PG8_STAGE(PG8_SB(0, 1), b2 + hB, voffB); PG8_STAGE(PG8_SA(0, 0), a2, voffA);
;             PG8_WAIT_V(8); PG8_WAIT_L(0); PG8_BAR; PG8_MMA(1, 0, At, B0); PG8_MMA(1, 1, At, B1); PG8_BAR; PG8_SCHED;
.LBB0_1755:
	ds_read_b128 v[128:131], v183
	ds_read_b128 v[132:135], v183 offset:1024
	ds_read_b128 v[152:155], v183 offset:2048
	ds_read_b128 v[156:159], v183 offset:3072
	ds_read_b128 v[160:163], v184
	ds_read_b128 v[164:167], v184 offset:1024
	ds_read_b128 v[168:171], v184 offset:2048
	ds_read_b128 v[172:175], v184 offset:3072
	s_add_u32 s30, s28, 0xffe00080
	s_addc_u32 s31, s29, -1
	s_cmpk_eq_i32 s51, 0x7c
	s_cselect_b32 s35, s5, s31
	s_cselect_b32 s34, s21, s30
	s_cselect_b32 s31, s19, s50
	s_cselect_b32 s30, s48, s49
	v_lshl_add_u64 v[214:215], s[28:29], 0, v[144:145]
	s_add_i32 m0, s27, 0xc000
	ds_read_b128 v[176:179], v185
	ds_read_b128 v[186:189], v185 offset:1024
	ds_read_b128 v[190:193], v185 offset:2048
	ds_read_b128 v[194:197], v185 offset:3072
	ds_read_b128 v[198:201], v185 offset:4096
	ds_read_b128 v[202:205], v185 offset:5120
	ds_read_b128 v[206:209], v185 offset:6144
	ds_read_b128 v[210:213], v185 offset:7168
	global_load_lds_dwordx4 v[214:215], off
	v_lshl_add_u64 v[214:215], s[28:29], 0, v[146:147]
	s_add_i32 m0, s27, 0xe000
	s_nop 0
	global_load_lds_dwordx4 v[214:215], off
	s_waitcnt vmcnt(8)
	s_waitcnt lgkmcnt(0)
	s_barrier
	s_setprio 1
	s_waitcnt lgkmcnt(0)
	v_mfma_f32_16x16x32_bf16 v[120:123], v[128:131], v[176:179], v[120:123]
	v_mfma_f32_16x16x32_bf16 v[120:123], v[132:135], v[186:189], v[120:123]
	v_mfma_f32_16x16x32_bf16 v[124:127], v[152:155], v[176:179], v[124:127]
	v_mfma_f32_16x16x32_bf16 v[124:127], v[156:159], v[186:189], v[124:127]
	v_mfma_f32_16x16x32_bf16 v[104:107], v[128:131], v[190:193], v[104:107]
	v_mfma_f32_16x16x32_bf16 v[104:107], v[132:135], v[194:197], v[104:107]
	v_mfma_f32_16x16x32_bf16 v[108:111], v[152:155], v[190:193], v[108:111]
	v_mfma_f32_16x16x32_bf16 v[108:111], v[156:159], v[194:197], v[108:111]
	v_mfma_f32_16x16x32_bf16 v[88:91], v[128:131], v[198:201], v[88:91]
	v_mfma_f32_16x16x32_bf16 v[88:91], v[132:135], v[202:205], v[88:91]
	v_mfma_f32_16x16x32_bf16 v[92:95], v[152:155], v[198:201], v[92:95]
	v_mfma_f32_16x16x32_bf16 v[92:95], v[156:159], v[202:205], v[92:95]
	v_mfma_f32_16x16x32_bf16 v[72:75], v[128:131], v[206:209], v[72:75]
	v_mfma_f32_16x16x32_bf16 v[72:75], v[132:135], v[210:213], v[72:75]
	v_mfma_f32_16x16x32_bf16 v[76:79], v[152:155], v[206:209], v[76:79]
	v_mfma_f32_16x16x32_bf16 v[76:79], v[156:159], v[210:213], v[76:79]
	s_setprio 0
	s_setprio 1
	v_mfma_f32_16x16x32_bf16 v[112:115], v[160:163], v[176:179], v[112:115]
	v_mfma_f32_16x16x32_bf16 v[112:115], v[164:167], v[186:189], v[112:115]
	v_mfma_f32_16x16x32_bf16 v[116:119], v[168:171], v[176:179], v[116:119]
	v_mfma_f32_16x16x32_bf16 v[116:119], v[172:175], v[186:189], v[116:119]
	v_mfma_f32_16x16x32_bf16 v[96:99], v[160:163], v[190:193], v[96:99]
	v_mfma_f32_16x16x32_bf16 v[96:99], v[164:167], v[194:197], v[96:99]
	v_mfma_f32_16x16x32_bf16 v[100:103], v[168:171], v[190:193], v[100:103]
	v_mfma_f32_16x16x32_bf16 v[100:103], v[172:175], v[194:197], v[100:103]
	v_mfma_f32_16x16x32_bf16 v[80:83], v[160:163], v[198:201], v[80:83]
	v_mfma_f32_16x16x32_bf16 v[80:83], v[164:167], v[202:205], v[80:83]
	v_mfma_f32_16x16x32_bf16 v[84:87], v[168:171], v[198:201], v[84:87]
	v_mfma_f32_16x16x32_bf16 v[84:87], v[172:175], v[202:205], v[84:87]
	s_barrier
	v_mfma_f32_16x16x32_bf16 v[64:67], v[160:163], v[206:209], v[64:67]
	v_mfma_f32_16x16x32_bf16 v[64:67], v[164:167], v[210:213], v[64:67]
	v_mfma_f32_16x16x32_bf16 v[68:71], v[168:171], v[206:209], v[68:71]
	v_mfma_f32_16x16x32_bf16 v[68:71], v[172:175], v[210:213], v[68:71]
	s_setprio 0
	s_add_i32 s52, s46, s37
	v_lshl_add_u64 v[214:215], s[30:31], 0, v[138:139]
	s_mov_b32 m0, s52
	ds_read_b128 v[176:179], v185 offset:16384
	ds_read_b128 v[186:189], v185 offset:17408
	ds_read_b128 v[190:193], v185 offset:18432
	ds_read_b128 v[194:197], v185 offset:19456
	ds_read_b128 v[198:201], v185 offset:20480
	ds_read_b128 v[202:205], v185 offset:21504
	ds_read_b128 v[206:209], v185 offset:22528
	ds_read_b128 v[210:213], v185 offset:23552
	global_load_lds_dwordx4 v[214:215], off
	s_add_i32 m0, s52, 0x2000
	s_add_u32 s52, s30, 0x200000
	v_lshl_add_u64 v[216:217], s[30:31], 0, v[142:143]
	s_addc_u32 s53, s31, 0
	s_add_i32 s54, s47, s37
	global_load_lds_dwordx4 v[216:217], off
	v_lshl_add_u64 v[218:219], s[52:53], 0, v[138:139]
	s_mov_b32 m0, s54
	v_lshl_add_u64 v[220:221], s[34:35], 0, v[140:141]
	global_load_lds_dwordx4 v[218:219], off
	v_lshl_add_u64 v[218:219], s[52:53], 0, v[142:143]
	s_add_i32 m0, s54, 0x2000
	s_nop 0
	global_load_lds_dwordx4 v[218:219], off
	v_lshl_add_u64 v[218:219], s[34:35], 0, v[136:137]
	s_mov_b32 m0, s27
	s_nop 0
	global_load_lds_dwordx4 v[218:219], off
	s_mov_b32 m0, s38
	s_nop 0
	global_load_lds_dwordx4 v[220:221], off
	s_waitcnt vmcnt(8)
	s_waitcnt lgkmcnt(0)
	s_barrier
; #define PG8_STAGE(bufoff, gbase, voff) do { _Pragma("unroll") for (int _i = 0; _i < 2; ++_i) \
;         __builtin_amdgcn_global_load_lds((const unsigned*)((const char*)(gbase) + (voff)[_i]), (LAS unsigned*)(lds + (bufoff) + ldsw + _i * 8192), 16, 0, 0); } while (0)
; #define PG8_LDA(dst, b, h) do { _Pragma("unroll") for (int m = 0; m < 4; ++m) _Pragma("unroll") for (int k = 0; k < 2; ++k) dst[m][k] = *(const LAS bf16x8*)(lds + PG8_SA(b, h) + aoff + m * 2048 + k * 1024); } while (0)
; #define PG8_LDB(dst, b, h) do { _Pragma("unroll") for (int n = 0; n < 2; ++n) _Pragma("unroll") for (int k = 0; k < 2; ++k) dst[n][k] = *(const LAS bf16x8*)(lds + PG8_SB(b, h) + boff + n * 2048 + k * 1024); } while (0)
; #define PG8_MMA(ai, bj, At, Bt) do { __builtin_amdgcn_s_setprio(1); _Pragma("unroll") for (int m = 0; m < 4; ++m) _Pragma("unroll") for (int n = 0; n < 2; ++n) _Pragma("unroll") for (int k = 0; k < 2; ++k) \
;         acc[ai][bj][m][n] = __builtin_amdgcn_mfma_f32_16x16x32_bf16(Bt[n][k], At[m][k], acc[ai][bj][m][n], 0, 0, 0); __builtin_amdgcn_s_setprio(0); } while (0)
; #define PG8_WAIT_V(n) asm volatile("s_waitcnt vmcnt(" #n ")" ::: "memory")
; #define PG8_WAIT_L(n) asm volatile("s_waitcnt lgkmcnt(" #n ")" ::: "memory")
; #define PG8_BAR __builtin_amdgcn_s_barrier()
; #define PG8_SCHED __builtin_amdgcn_sched_barrier(0)
; template <class Epi, bool ALIGN_EPI>
; __device__ __forceinline__ void gemm_phase(LAS unsigned char* lds, const Gemm g, const StaticOrder& S, const Epi& E) {
;     ...
;             PG8_WAIT_V(8); PG8_WAIT_L(0); PG8_BAR; PG8_MMA(1, 0, At, B0); PG8_MMA(1, 1, At, B1); PG8_BAR; PG8_SCHED;
;             PG8_LDB(B0, 1, 0); PG8_LDB(B1, 1, 1); PG8_SCHED; PG8_LDA(At, 1, 0); PG8_STAGE(PG8_SA(0, 1), a2 + hA, voffA);
;             PG8_WAIT_V(8); PG8_WAIT_L(0); PG8_BAR; PG8_MMA(0, 0, At, B0); PG8_MMA(0, 1, At, B1); PG8_BAR; PG8_SCHED;
;             PG8_LDA(At, 1, 1); PG8_STAGE(PG8_SB(1, 0), b3, voffB); PG8_STAGE(PG8_SB(1, 1), b3 + hB, voffB); PG8_STAGE(PG8_SA(1, 0), a3, voffA);
	s_setprio 1
	s_waitcnt lgkmcnt(0)
	v_mfma_f32_16x16x32_bf16 v[56:59], v[128:131], v[176:179], v[56:59]
	v_mfma_f32_16x16x32_bf16 v[56:59], v[132:135], v[186:189], v[56:59]
	v_mfma_f32_16x16x32_bf16 v[60:63], v[152:155], v[176:179], v[60:63]
	v_mfma_f32_16x16x32_bf16 v[60:63], v[156:159], v[186:189], v[60:63]
	v_mfma_f32_16x16x32_bf16 v[40:43], v[128:131], v[190:193], v[40:43]
	v_mfma_f32_16x16x32_bf16 v[40:43], v[132:135], v[194:197], v[40:43]
	v_mfma_f32_16x16x32_bf16 v[44:47], v[152:155], v[190:193], v[44:47]
	v_mfma_f32_16x16x32_bf16 v[44:47], v[156:159], v[194:197], v[44:47]
	v_mfma_f32_16x16x32_bf16 v[24:27], v[128:131], v[198:201], v[24:27]
	v_mfma_f32_16x16x32_bf16 v[24:27], v[132:135], v[202:205], v[24:27]
	v_mfma_f32_16x16x32_bf16 v[28:31], v[152:155], v[198:201], v[28:31]
	v_mfma_f32_16x16x32_bf16 v[28:31], v[156:159], v[202:205], v[28:31]
	v_mfma_f32_16x16x32_bf16 v[8:11], v[128:131], v[206:209], v[8:11]
	v_mfma_f32_16x16x32_bf16 v[8:11], v[132:135], v[210:213], v[8:11]
	v_mfma_f32_16x16x32_bf16 v[12:15], v[152:155], v[206:209], v[12:15]
	v_mfma_f32_16x16x32_bf16 v[12:15], v[156:159], v[210:213], v[12:15]
	s_setprio 0
	s_setprio 1
	v_mfma_f32_16x16x32_bf16 v[48:51], v[160:163], v[176:179], v[48:51]
	v_mfma_f32_16x16x32_bf16 v[48:51], v[164:167], v[186:189], v[48:51]
	v_mfma_f32_16x16x32_bf16 v[52:55], v[168:171], v[176:179], v[52:55]
	v_mfma_f32_16x16x32_bf16 v[52:55], v[172:175], v[186:189], v[52:55]
	v_mfma_f32_16x16x32_bf16 v[32:35], v[160:163], v[190:193], v[32:35]
	v_mfma_f32_16x16x32_bf16 v[32:35], v[164:167], v[194:197], v[32:35]
	v_mfma_f32_16x16x32_bf16 v[36:39], v[168:171], v[190:193], v[36:39]
	v_mfma_f32_16x16x32_bf16 v[36:39], v[172:175], v[194:197], v[36:39]
	v_mfma_f32_16x16x32_bf16 v[16:19], v[160:163], v[198:201], v[16:19]
	v_mfma_f32_16x16x32_bf16 v[16:19], v[164:167], v[202:205], v[16:19]
	v_mfma_f32_16x16x32_bf16 v[20:23], v[168:171], v[198:201], v[20:23]
	v_mfma_f32_16x16x32_bf16 v[20:23], v[172:175], v[202:205], v[20:23]
	s_barrier
	v_mfma_f32_16x16x32_bf16 v[4:7], v[160:163], v[206:209], v[4:7]
	v_mfma_f32_16x16x32_bf16 v[4:7], v[164:167], v[210:213], v[4:7]
	v_mfma_f32_16x16x32_bf16 v[0:3], v[168:171], v[206:209], v[0:3]
	v_mfma_f32_16x16x32_bf16 v[0:3], v[172:175], v[210:213], v[0:3]
	s_setprio 0
	s_add_i32 s52, 0, 0x18000
	s_add_i32 s53, 0, 0x1c000
	v_add_u32_e32 v156, s52, v181
	v_add_u32_e32 v172, s53, v181
	ds_read_b128 v[128:131], v156
	ds_read_b128 v[132:135], v156 offset:1024
	ds_read_b128 v[152:155], v156 offset:2048
	ds_read_b128 v[156:159], v156 offset:3072
	ds_read_b128 v[160:163], v172
	ds_read_b128 v[164:167], v172 offset:1024
	ds_read_b128 v[168:171], v172 offset:2048
	ds_read_b128 v[172:175], v172 offset:3072
	s_add_u32 s34, s34, 0x200000
	s_addc_u32 s35, s35, 0
	s_mov_b32 m0, s39
	v_lshl_add_u64 v[222:223], s[34:35], 0, v[136:137]
	ds_read_b128 v[176:179], v185 offset:32768
	ds_read_b128 v[186:189], v185 offset:33792
	ds_read_b128 v[190:193], v185 offset:34816
	ds_read_b128 v[194:197], v185 offset:35840
	ds_read_b128 v[198:201], v185 offset:36864
	ds_read_b128 v[202:205], v185 offset:37888
	ds_read_b128 v[206:209], v185 offset:38912
	ds_read_b128 v[210:213], v185 offset:39936
	global_load_lds_dwordx4 v[222:223], off
	v_lshl_add_u64 v[222:223], s[34:35], 0, v[140:141]
	s_mov_b32 m0, s40
	s_nop 0
	global_load_lds_dwordx4 v[222:223], off
	s_waitcnt vmcnt(8)
	s_waitcnt lgkmcnt(0)
	s_barrier
	s_setprio 1
	s_waitcnt lgkmcnt(0)
	v_mfma_f32_16x16x32_bf16 v[120:123], v[128:131], v[176:179], v[120:123]
	v_mfma_f32_16x16x32_bf16 v[120:123], v[132:135], v[186:189], v[120:123]
	v_mfma_f32_16x16x32_bf16 v[124:127], v[152:155], v[176:179], v[124:127]
	v_mfma_f32_16x16x32_bf16 v[124:127], v[156:159], v[186:189], v[124:127]
	v_mfma_f32_16x16x32_bf16 v[104:107], v[128:131], v[190:193], v[104:107]
	v_mfma_f32_16x16x32_bf16 v[104:107], v[132:135], v[194:197], v[104:107]
	v_mfma_f32_16x16x32_bf16 v[108:111], v[152:155], v[190:193], v[108:111]
	v_mfma_f32_16x16x32_bf16 v[108:111], v[156:159], v[194:197], v[108:111]
	v_mfma_f32_16x16x32_bf16 v[88:91], v[128:131], v[198:201], v[88:91]
	v_mfma_f32_16x16x32_bf16 v[88:91], v[132:135], v[202:205], v[88:91]
	v_mfma_f32_16x16x32_bf16 v[92:95], v[152:155], v[198:201], v[92:95]
	v_mfma_f32_16x16x32_bf16 v[92:95], v[156:159], v[202:205], v[92:95]
	v_mfma_f32_16x16x32_bf16 v[72:75], v[128:131], v[206:209], v[72:75]
	v_mfma_f32_16x16x32_bf16 v[72:75], v[132:135], v[210:213], v[72:75]
	v_mfma_f32_16x16x32_bf16 v[76:79], v[152:155], v[206:209], v[76:79]
	v_mfma_f32_16x16x32_bf16 v[76:79], v[156:159], v[210:213], v[76:79]
	s_setprio 0
	s_setprio 1
	v_mfma_f32_16x16x32_bf16 v[112:115], v[160:163], v[176:179], v[112:115]
	v_mfma_f32_16x16x32_bf16 v[112:115], v[164:167], v[186:189], v[112:115]
	v_mfma_f32_16x16x32_bf16 v[116:119], v[168:171], v[176:179], v[116:119]
	v_mfma_f32_16x16x32_bf16 v[116:119], v[172:175], v[186:189], v[116:119]
	v_mfma_f32_16x16x32_bf16 v[96:99], v[160:163], v[190:193], v[96:99]
	v_mfma_f32_16x16x32_bf16 v[96:99], v[164:167], v[194:197], v[96:99]
	v_mfma_f32_16x16x32_bf16 v[100:103], v[168:171], v[190:193], v[100:103]
	v_mfma_f32_16x16x32_bf16 v[100:103], v[172:175], v[194:197], v[100:103]
	v_mfma_f32_16x16x32_bf16 v[80:83], v[160:163], v[198:201], v[80:83]
	v_mfma_f32_16x16x32_bf16 v[80:83], v[164:167], v[202:205], v[80:83]
	v_mfma_f32_16x16x32_bf16 v[84:87], v[168:171], v[198:201], v[84:87]
	v_mfma_f32_16x16x32_bf16 v[84:87], v[172:175], v[202:205], v[84:87]
	s_barrier
; #define PG8_STAGE(bufoff, gbase, voff) do { _Pragma("unroll") for (int _i = 0; _i < 2; ++_i) \
;         __builtin_amdgcn_global_load_lds((const unsigned*)((const char*)(gbase) + (voff)[_i]), (LAS unsigned*)(lds + (bufoff) + ldsw + _i * 8192), 16, 0, 0); } while (0)
; #define PG8_LDA(dst, b, h) do { _Pragma("unroll") for (int m = 0; m < 4; ++m) _Pragma("unroll") for (int k = 0; k < 2; ++k) dst[m][k] = *(const LAS bf16x8*)(lds + PG8_SA(b, h) + aoff + m * 2048 + k * 1024); } while (0)
; #define PG8_MMA(ai, bj, At, Bt) do { __builtin_amdgcn_s_setprio(1); _Pragma("unroll") for (int m = 0; m < 4; ++m) _Pragma("unroll") for (int n = 0; n < 2; ++n) _Pragma("unroll") for (int k = 0; k < 2; ++k) \
;         acc[ai][bj][m][n] = __builtin_amdgcn_mfma_f32_16x16x32_bf16(Bt[n][k], At[m][k], acc[ai][bj][m][n], 0, 0, 0); __builtin_amdgcn_s_setprio(0); } while (0)
; #define PG8_WAIT_V(n) asm volatile("s_waitcnt vmcnt(" #n ")" ::: "memory")
; #define PG8_WAIT_L(n) asm volatile("s_waitcnt lgkmcnt(" #n ")" ::: "memory")
; #define PG8_BAR __builtin_amdgcn_s_barrier()
; #define PG8_SCHED __builtin_amdgcn_sched_barrier(0)
; template <class Epi, bool ALIGN_EPI>
; __device__ __forceinline__ void gemm_phase(LAS unsigned char* lds, const Gemm g, const StaticOrder& S, const Epi& E) {
;     ...
;             PG8_WAIT_V(8); PG8_WAIT_L(0); PG8_BAR; PG8_MMA(0, 0, At, B0); PG8_MMA(0, 1, At, B1); PG8_BAR; PG8_SCHED;
;             PG8_LDA(At, 1, 1); PG8_STAGE(PG8_SB(1, 0), b3, voffB); PG8_STAGE(PG8_SB(1, 1), b3 + hB, voffB); PG8_STAGE(PG8_SA(1, 0), a3, voffA);
;             PG8_WAIT_V(8); PG8_WAIT_L(0); PG8_BAR; PG8_MMA(1, 0, At, B0); PG8_MMA(1, 1, At, B1); PG8_BAR; PG8_SCHED;
;         }
;         if constexpr (ALIGN_EPI) { if (wr == 0) PG8_BAR; }
	v_mfma_f32_16x16x32_bf16 v[64:67], v[160:163], v[206:209], v[64:67]
	v_mfma_f32_16x16x32_bf16 v[64:67], v[164:167], v[210:213], v[64:67]
	v_mfma_f32_16x16x32_bf16 v[68:71], v[168:171], v[206:209], v[68:71]
	v_mfma_f32_16x16x32_bf16 v[68:71], v[172:175], v[210:213], v[68:71]
	s_setprio 0
	s_add_i32 s34, s52, s37
	v_lshl_add_u64 v[214:215], v[214:215], 0, s[12:13]
	s_mov_b32 m0, s34
	ds_read_b128 v[176:179], v185 offset:49152
	ds_read_b128 v[186:189], v185 offset:50176
	ds_read_b128 v[190:193], v185 offset:51200
	ds_read_b128 v[194:197], v185 offset:52224
	ds_read_b128 v[198:201], v185 offset:53248
	ds_read_b128 v[202:205], v185 offset:54272
	ds_read_b128 v[206:209], v185 offset:55296
	ds_read_b128 v[210:213], v185 offset:56320
	global_load_lds_dwordx4 v[214:215], off
	s_add_i32 m0, s34, 0x2000
	s_add_u32 s30, s30, 0x200080
	v_lshl_add_u64 v[214:215], v[216:217], 0, s[12:13]
	s_addc_u32 s31, s31, 0
	s_add_i32 s34, s53, s37
	global_load_lds_dwordx4 v[214:215], off
	v_lshl_add_u64 v[214:215], s[30:31], 0, v[138:139]
	s_mov_b32 m0, s34
	s_nop 0
	global_load_lds_dwordx4 v[214:215], off
	v_lshl_add_u64 v[214:215], s[30:31], 0, v[142:143]
	s_add_i32 m0, s34, 0x2000
	s_nop 0
	global_load_lds_dwordx4 v[214:215], off
	v_lshl_add_u64 v[214:215], v[218:219], 0, s[12:13]
	s_mov_b32 m0, s44
	s_nop 0
	global_load_lds_dwordx4 v[214:215], off
	v_lshl_add_u64 v[214:215], v[220:221], 0, s[12:13]
	s_mov_b32 m0, s45
	s_nop 0
	global_load_lds_dwordx4 v[214:215], off
	s_waitcnt vmcnt(8)
	s_waitcnt lgkmcnt(0)
	s_barrier
	s_setprio 1
	s_waitcnt lgkmcnt(0)
	v_mfma_f32_16x16x32_bf16 v[56:59], v[128:131], v[176:179], v[56:59]
	v_mfma_f32_16x16x32_bf16 v[56:59], v[132:135], v[186:189], v[56:59]
	v_mfma_f32_16x16x32_bf16 v[60:63], v[152:155], v[176:179], v[60:63]
	v_mfma_f32_16x16x32_bf16 v[60:63], v[156:159], v[186:189], v[60:63]
	v_mfma_f32_16x16x32_bf16 v[40:43], v[128:131], v[190:193], v[40:43]
	v_mfma_f32_16x16x32_bf16 v[40:43], v[132:135], v[194:197], v[40:43]
	v_mfma_f32_16x16x32_bf16 v[44:47], v[152:155], v[190:193], v[44:47]
	v_mfma_f32_16x16x32_bf16 v[44:47], v[156:159], v[194:197], v[44:47]
	v_mfma_f32_16x16x32_bf16 v[24:27], v[128:131], v[198:201], v[24:27]
	v_mfma_f32_16x16x32_bf16 v[24:27], v[132:135], v[202:205], v[24:27]
	v_mfma_f32_16x16x32_bf16 v[28:31], v[152:155], v[198:201], v[28:31]
	v_mfma_f32_16x16x32_bf16 v[28:31], v[156:159], v[202:205], v[28:31]
	v_mfma_f32_16x16x32_bf16 v[8:11], v[128:131], v[206:209], v[8:11]
	v_mfma_f32_16x16x32_bf16 v[8:11], v[132:135], v[210:213], v[8:11]
	v_mfma_f32_16x16x32_bf16 v[12:15], v[152:155], v[206:209], v[12:15]
	v_mfma_f32_16x16x32_bf16 v[12:15], v[156:159], v[210:213], v[12:15]
	s_setprio 0
	s_setprio 1
	v_mfma_f32_16x16x32_bf16 v[48:51], v[160:163], v[176:179], v[48:51]
	v_mfma_f32_16x16x32_bf16 v[48:51], v[164:167], v[186:189], v[48:51]
	v_mfma_f32_16x16x32_bf16 v[52:55], v[168:171], v[176:179], v[52:55]
	v_mfma_f32_16x16x32_bf16 v[52:55], v[172:175], v[186:189], v[52:55]
	v_mfma_f32_16x16x32_bf16 v[32:35], v[160:163], v[190:193], v[32:35]
	v_mfma_f32_16x16x32_bf16 v[32:35], v[164:167], v[194:197], v[32:35]
	v_mfma_f32_16x16x32_bf16 v[36:39], v[168:171], v[190:193], v[36:39]
	v_mfma_f32_16x16x32_bf16 v[36:39], v[172:175], v[194:197], v[36:39]
	v_mfma_f32_16x16x32_bf16 v[16:19], v[160:163], v[198:201], v[16:19]
	v_mfma_f32_16x16x32_bf16 v[16:19], v[164:167], v[202:205], v[16:19]
	v_mfma_f32_16x16x32_bf16 v[20:23], v[168:171], v[198:201], v[20:23]
	v_mfma_f32_16x16x32_bf16 v[20:23], v[172:175], v[202:205], v[20:23]
	s_barrier
	v_mfma_f32_16x16x32_bf16 v[4:7], v[160:163], v[206:209], v[4:7]
	v_mfma_f32_16x16x32_bf16 v[4:7], v[164:167], v[210:213], v[4:7]
	v_mfma_f32_16x16x32_bf16 v[0:3], v[168:171], v[206:209], v[0:3]
	v_mfma_f32_16x16x32_bf16 v[0:3], v[172:175], v[210:213], v[0:3]
	s_setprio 0
	s_add_i32 s51, s51, 2
	s_add_u32 s28, s28, 0x100
	s_addc_u32 s29, s29, 0
	s_add_u32 s49, s49, 0x100
	s_addc_u32 s50, s50, 0
	s_cmpk_gt_u32 s51, 0x7d
	s_cbranch_scc0 .LBB0_1755
	s_and_b64 vcc, exec, s[14:15]
	s_cbranch_vccz .LBB0_1758
	s_barrier
